# first 4 MFMAs of each K-loop MMA segment issued before the segment barrier (on saddr + equal priority + peeled iteration)
# baseline (speedup 1.0000x reference)
; #define PG8_STAGE(bufoff, gbase, voff) do { _Pragma("unroll") for (int _i = 0; _i < 2; ++_i) \
;         __builtin_amdgcn_global_load_lds((const unsigned*)((const char*)(gbase) + (voff)[_i]), (LAS unsigned*)(lds + (bufoff) + ldsw + _i * 8192), 16, 0, 0); } while (0)
; #define PG8_LDA(dst, b, h) do { _Pragma("unroll") for (int m = 0; m < 4; ++m) _Pragma("unroll") for (int k = 0; k < 2; ++k) dst[m][k] = *(const LAS bf16x8*)(lds + PG8_SA(b, h) + aoff + m * 2048 + k * 1024); } while (0)
; #define PG8_LDB(dst, b, h) do { _Pragma("unroll") for (int n = 0; n < 2; ++n) _Pragma("unroll") for (int k = 0; k < 2; ++k) dst[n][k] = *(const LAS bf16x8*)(lds + PG8_SB(b, h) + boff + n * 2048 + k * 1024); } while (0)
; #define PG8_WAIT_V(n) asm volatile("s_waitcnt vmcnt(" #n ")" ::: "memory")
; #define PG8_WAIT_L(n) asm volatile("s_waitcnt lgkmcnt(" #n ")" ::: "memory")
; #define PG8_BAR __builtin_amdgcn_s_barrier()
; template <class Epi, class Sched, int KC, bool ALIGN_EPI = false, bool SP2 = false, bool ATILED = false>
; __device__ __forceinline__ void gemm_phase(LAS unsigned char* lds, const Gemm g, const Sched& S, const Epi& E, int wave_s) {
;     ...
;         const bool has_next = S.next(ui + 1, nxt);
;         const char* nA = has_next ? (const char*)g.A + (size_t)nxt.pm * tstepA : cA; const char* nB = has_next ? (const char*)g.Bt + (size_t)nxt.pn * tstep : cB;
;         for (int t = 0; t < nt; t += 2) {
;             const bool last = (t == nt - 2);
;             const char* a1 = cA + PG8_AOFF(t + 1);
;             const char* a2 = last ? nA : cA + PG8_AOFF(t + 2); const char* b2 = last ? nB : cB + (size_t)(t + 2) * kstep;
;             const char* a3 = a2 + kstep; const char* b3 = b2 + kstep;
;             if (last && has_next) S.a_ready(nxt);
;             if constexpr (SP2) {
;             PG8_LDB(B0, 0, 0); PG8_LDB(B1, 0, 1); PG8_SCHED; PG8_LDA(At, 0, 0); PG8_STAGE(PG8_SA(1, 1), a1 + hstepA, voffA);
;             PG8_WAIT_V(8); PG8_WAIT_L(0); PG8_BAR; PG8_MMA(0, 0, At, B0); PG8_MMA(0, 1, At, B1); PG8_BAR; PG8_SCHED;
;     ...
; #pragma unroll
;         for (int a = 0; a < 2; ++a)
; #pragma unroll
;             for (int b = 0; b < 2; ++b)
; #pragma unroll
;                 for (int m = 0; m < 4; ++m)
; #pragma unroll
;                     for (int n = 0; n < 2; ++n) acc[a][b][m][n] = (f32x4){0.f, 0.f, 0.f, 0.f};
;         cur = nxt; cA = nA; cB = nB; ++ui;
.LBB0_232:
	s_ashr_i32 s19, s18, 31
	s_lshl_b64 s[20:21], s[18:19], 17
	s_add_u32 s20, s39, s20
	s_addc_u32 s21, s40, s21
	s_and_b64 s[22:23], s[6:7], exec
	s_cselect_b32 s19, s21, s27
	s_cselect_b32 s53, s20, s26
	s_ashr_i32 s17, s16, 31
	s_lshl_b64 s[22:23], s[16:17], 20
	s_add_u32 s22, s41, s22
	s_addc_u32 s23, s42, s23
	s_and_b64 s[30:31], s[6:7], exec
	s_cselect_b32 s17, s23, s29
	s_cselect_b32 s54, s22, s28
	s_add_u32 s55, s28, 0x100
	v_mov_b32_e32 v2, 0
	s_addc_u32 s56, s29, 0
	s_mov_b32 s57, -2
	s_mov_b64 s[28:29], 0
	s_mov_b32 s58, 0x400000
	v_mov_b32_e32 v3, v2
	v_mov_b32_e32 v4, v2
	v_mov_b32_e32 v5, v2
	v_mov_b32_e32 v14, v2
	v_mov_b32_e32 v15, v2
	v_mov_b32_e32 v16, v2
	v_mov_b32_e32 v17, v2
	v_mov_b32_e32 v22, v2
	v_mov_b32_e32 v23, v2
	v_mov_b32_e32 v24, v2
	v_mov_b32_e32 v25, v2
	v_mov_b32_e32 v30, v2
	v_mov_b32_e32 v31, v2
	v_mov_b32_e32 v32, v2
	v_mov_b32_e32 v33, v2
	v_mov_b32_e32 v38, v2
	v_mov_b32_e32 v39, v2
	v_mov_b32_e32 v40, v2
	v_mov_b32_e32 v41, v2
	v_mov_b32_e32 v46, v2
	v_mov_b32_e32 v47, v2
	v_mov_b32_e32 v48, v2
	v_mov_b32_e32 v49, v2
	v_mov_b32_e32 v54, v2
	v_mov_b32_e32 v55, v2
	v_mov_b32_e32 v56, v2
	v_mov_b32_e32 v57, v2
	v_mov_b32_e32 v62, v2
	v_mov_b32_e32 v63, v2
	v_mov_b32_e32 v64, v2
	v_mov_b32_e32 v65, v2
	v_mov_b32_e32 v6, v2
	v_mov_b32_e32 v7, v2
	v_mov_b32_e32 v8, v2
	v_mov_b32_e32 v9, v2
	v_mov_b32_e32 v10, v2
	v_mov_b32_e32 v11, v2
	v_mov_b32_e32 v12, v2
	v_mov_b32_e32 v13, v2
	v_mov_b32_e32 v18, v2
	v_mov_b32_e32 v19, v2
	v_mov_b32_e32 v20, v2
	v_mov_b32_e32 v21, v2
	v_mov_b32_e32 v26, v2
	v_mov_b32_e32 v27, v2
	v_mov_b32_e32 v28, v2
	v_mov_b32_e32 v29, v2
	v_mov_b32_e32 v34, v2
	v_mov_b32_e32 v35, v2
	v_mov_b32_e32 v36, v2
	v_mov_b32_e32 v37, v2
	v_mov_b32_e32 v42, v2
	v_mov_b32_e32 v43, v2
	v_mov_b32_e32 v44, v2
	v_mov_b32_e32 v45, v2
	v_mov_b32_e32 v50, v2
	v_mov_b32_e32 v51, v2
	v_mov_b32_e32 v52, v2
	v_mov_b32_e32 v53, v2
	v_mov_b32_e32 v58, v2
	v_mov_b32_e32 v59, v2
	v_mov_b32_e32 v60, v2
	v_mov_b32_e32 v61, v2
	v_mov_b32_e32 v70, v2
	v_mov_b32_e32 v71, v2
	v_mov_b32_e32 v72, v2
	v_mov_b32_e32 v73, v2
	v_mov_b32_e32 v78, v2
	v_mov_b32_e32 v79, v2
	v_mov_b32_e32 v80, v2
	v_mov_b32_e32 v81, v2
	v_mov_b32_e32 v86, v2
	v_mov_b32_e32 v87, v2
	v_mov_b32_e32 v88, v2
	v_mov_b32_e32 v89, v2
	v_mov_b32_e32 v94, v2
	v_mov_b32_e32 v95, v2
	v_mov_b32_e32 v96, v2
	v_mov_b32_e32 v97, v2
	v_mov_b32_e32 v102, v2
	v_mov_b32_e32 v103, v2
	v_mov_b32_e32 v104, v2
	v_mov_b32_e32 v105, v2
	v_mov_b32_e32 v110, v2
	v_mov_b32_e32 v111, v2
	v_mov_b32_e32 v112, v2
	v_mov_b32_e32 v113, v2
	v_mov_b32_e32 v118, v2
	v_mov_b32_e32 v119, v2
	v_mov_b32_e32 v120, v2
	v_mov_b32_e32 v121, v2
	v_mov_b32_e32 v126, v2
	v_mov_b32_e32 v127, v2
	v_mov_b32_e32 v128, v2
	v_mov_b32_e32 v129, v2
	v_mov_b32_e32 v66, v2
	v_mov_b32_e32 v67, v2
	v_mov_b32_e32 v68, v2
	v_mov_b32_e32 v69, v2
	v_mov_b32_e32 v74, v2
	v_mov_b32_e32 v75, v2
	v_mov_b32_e32 v76, v2
	v_mov_b32_e32 v77, v2
	v_mov_b32_e32 v82, v2
	v_mov_b32_e32 v83, v2
	v_mov_b32_e32 v84, v2
	v_mov_b32_e32 v85, v2
	v_mov_b32_e32 v90, v2
	v_mov_b32_e32 v91, v2
	v_mov_b32_e32 v92, v2
	v_mov_b32_e32 v93, v2
	v_mov_b32_e32 v98, v2
	v_mov_b32_e32 v99, v2
	v_mov_b32_e32 v100, v2
	v_mov_b32_e32 v101, v2
	v_mov_b32_e32 v106, v2
	v_mov_b32_e32 v107, v2
	v_mov_b32_e32 v108, v2
	v_mov_b32_e32 v109, v2
	v_mov_b32_e32 v114, v2
	v_mov_b32_e32 v115, v2
	v_mov_b32_e32 v116, v2
	v_mov_b32_e32 v117, v2
	v_mov_b32_e32 v122, v2
	v_mov_b32_e32 v123, v2
	v_mov_b32_e32 v124, v2
	v_mov_b32_e32 v125, v2
	s_add_i32 s30, s58, 0xffc00000
	s_and_b32 s30, s30, 0x3800000
	s_and_b32 s31, s28, 0x100
	s_or_b32 s59, s31, s30
	s_and_b32 s34, s58, 0x7800000
	s_add_u32 s30, s28, 0x100
	s_addc_u32 s31, s29, 0
	s_and_b32 s35, s30, 0x100
	s_or_b32 s34, s34, s35
	s_add_u32 s34, s26, s34
	s_addc_u32 s35, s27, 0
	s_add_u32 s28, s55, s28
	s_addc_u32 s29, s56, s29
	s_add_i32 s62, 0, 0x10000
	s_cmp_eq_u32 s57, 28
	s_cselect_b32 s35, s19, s35
	s_cselect_b32 s34, s53, s34
	v_add_u32_e32 v139, s62, v163
	s_cselect_b32 s29, s17, s29
	s_cselect_b32 s28, s54, s28
	s_add_i32 s63, 0, 0x14000
	ds_read_b128 v[152:155], v139
	ds_read_b128 v[156:159], v139 offset:1024
	ds_read_b128 v[168:171], v139 offset:2048
	ds_read_b128 v[172:175], v139 offset:3072
	v_add_u32_e32 v139, s63, v163
	ds_read_b128 v[176:179], v139
	ds_read_b128 v[180:183], v139 offset:1024
	ds_read_b128 v[184:187], v139 offset:2048
	ds_read_b128 v[188:191], v139 offset:3072
	s_add_u32 s59, s26, s59
	s_addc_u32 s61, s27, 0
	s_add_u32 s60, s59, 0x10080
	s_addc_u32 s61, s61, 0
	s_add_i32 m0, s44, 0xc000
	ds_read_b128 v[198:201], v166
	ds_read_b128 v[202:205], v166 offset:1024
	ds_read_b128 v[206:209], v166 offset:2048
	ds_read_b128 v[210:213], v166 offset:3072
	ds_read_b128 v[214:217], v166 offset:4096
	ds_read_b128 v[218:221], v166 offset:5120
	ds_read_b128 v[222:225], v166 offset:6144
	ds_read_b128 v[226:229], v166 offset:7168
	global_load_lds_dwordx4 v136, s[60:61]
	s_add_i32 m0, s44, 0xe000
	s_nop 0
	global_load_lds_dwordx4 v132, s[60:61]
	s_waitcnt vmcnt(16)
	s_waitcnt lgkmcnt(0)
	v_mfma_f32_16x16x32_bf16 v[122:125], v[152:155], v[198:201], v[122:125]
	v_mfma_f32_16x16x32_bf16 v[114:117], v[168:171], v[198:201], v[114:117]
	v_mfma_f32_16x16x32_bf16 v[106:109], v[152:155], v[206:209], v[106:109]
	v_mfma_f32_16x16x32_bf16 v[98:101], v[168:171], v[206:209], v[98:101]
	s_barrier
; #define PG8_STAGE(bufoff, gbase, voff) do { _Pragma("unroll") for (int _i = 0; _i < 2; ++_i) \
;         __builtin_amdgcn_global_load_lds((const unsigned*)((const char*)(gbase) + (voff)[_i]), (LAS unsigned*)(lds + (bufoff) + ldsw + _i * 8192), 16, 0, 0); } while (0)
; #define PG8_LDA(dst, b, h) do { _Pragma("unroll") for (int m = 0; m < 4; ++m) _Pragma("unroll") for (int k = 0; k < 2; ++k) dst[m][k] = *(const LAS bf16x8*)(lds + PG8_SA(b, h) + aoff + m * 2048 + k * 1024); } while (0)
; #define PG8_MMA(ai, bj, At, Bt) do { __builtin_amdgcn_s_setprio(1); _Pragma("unroll") for (int m = 0; m < 4; ++m) _Pragma("unroll") for (int n = 0; n < 2; ++n) _Pragma("unroll") for (int k = 0; k < 2; ++k) \
;         acc[ai][bj][m][n] = __builtin_amdgcn_mfma_f32_16x16x32_bf16(Bt[n][k], At[m][k], acc[ai][bj][m][n], 0, 0, 0); __builtin_amdgcn_s_setprio(0); } while (0)
; #define PG8_WAIT_V(n) asm volatile("s_waitcnt vmcnt(" #n ")" ::: "memory")
; #define PG8_WAIT_L(n) asm volatile("s_waitcnt lgkmcnt(" #n ")" ::: "memory")
; #define PG8_BAR __builtin_amdgcn_s_barrier()
; #define PG8_SCHED __builtin_amdgcn_sched_barrier(0)
; template <class Epi, class Sched, int KC, bool ALIGN_EPI = false, bool SP2 = false, bool ATILED = false>
; __device__ __forceinline__ void gemm_phase(LAS unsigned char* lds, const Gemm g, const Sched& S, const Epi& E, int wave_s) {
;     ...
;             PG8_WAIT_V(8); PG8_WAIT_L(0); PG8_BAR; PG8_MMA(0, 0, At, B0); PG8_MMA(0, 1, At, B1); PG8_BAR; PG8_SCHED;
;             PG8_LDA(At, 0, 1); PG8_STAGE(PG8_SB(0, 0), b2, voffB); PG8_STAGE(PG8_SB(0, 1), b2 + hstepB, voffB); PG8_STAGE(PG8_SA(0, 0), a2, voffA);
;             PG8_WAIT_V(8); PG8_WAIT_L(0); PG8_BAR; PG8_MMA(1, 0, At, B0); PG8_MMA(1, 1, At, B1); PG8_BAR; PG8_SCHED;
	s_waitcnt lgkmcnt(0)
	v_mfma_f32_16x16x32_bf16 v[90:93], v[152:155], v[214:217], v[90:93]
	v_mfma_f32_16x16x32_bf16 v[82:85], v[168:171], v[214:217], v[82:85]
	v_mfma_f32_16x16x32_bf16 v[74:77], v[152:155], v[222:225], v[74:77]
	v_mfma_f32_16x16x32_bf16 v[66:69], v[168:171], v[222:225], v[66:69]
	v_mfma_f32_16x16x32_bf16 v[122:125], v[156:159], v[202:205], v[122:125]
	v_mfma_f32_16x16x32_bf16 v[114:117], v[172:175], v[202:205], v[114:117]
	v_mfma_f32_16x16x32_bf16 v[106:109], v[156:159], v[210:213], v[106:109]
	v_mfma_f32_16x16x32_bf16 v[98:101], v[172:175], v[210:213], v[98:101]
	v_mfma_f32_16x16x32_bf16 v[90:93], v[156:159], v[218:221], v[90:93]
	v_mfma_f32_16x16x32_bf16 v[82:85], v[172:175], v[218:221], v[82:85]
	v_mfma_f32_16x16x32_bf16 v[74:77], v[156:159], v[226:229], v[74:77]
	v_mfma_f32_16x16x32_bf16 v[66:69], v[172:175], v[226:229], v[66:69]
	v_mfma_f32_16x16x32_bf16 v[126:129], v[176:179], v[198:201], v[126:129]
	v_mfma_f32_16x16x32_bf16 v[118:121], v[184:187], v[198:201], v[118:121]
	v_mfma_f32_16x16x32_bf16 v[110:113], v[176:179], v[206:209], v[110:113]
	v_mfma_f32_16x16x32_bf16 v[102:105], v[184:187], v[206:209], v[102:105]
	v_mfma_f32_16x16x32_bf16 v[94:97], v[176:179], v[214:217], v[94:97]
	v_mfma_f32_16x16x32_bf16 v[86:89], v[184:187], v[214:217], v[86:89]
	v_mfma_f32_16x16x32_bf16 v[78:81], v[176:179], v[222:225], v[78:81]
	v_mfma_f32_16x16x32_bf16 v[70:73], v[184:187], v[222:225], v[70:73]
	v_mfma_f32_16x16x32_bf16 v[126:129], v[180:183], v[202:205], v[126:129]
	v_mfma_f32_16x16x32_bf16 v[118:121], v[188:191], v[202:205], v[118:121]
	v_mfma_f32_16x16x32_bf16 v[110:113], v[180:183], v[210:213], v[110:113]
	v_mfma_f32_16x16x32_bf16 v[102:105], v[188:191], v[210:213], v[102:105]
	v_mfma_f32_16x16x32_bf16 v[94:97], v[180:183], v[218:221], v[94:97]
	v_mfma_f32_16x16x32_bf16 v[86:89], v[188:191], v[218:221], v[86:89]
	v_mfma_f32_16x16x32_bf16 v[78:81], v[180:183], v[226:229], v[78:81]
	v_mfma_f32_16x16x32_bf16 v[70:73], v[188:191], v[226:229], v[70:73]
	s_barrier
	s_add_u32 s100, s34, 0x80
	s_addc_u32 s101, s35, 0
	s_add_i32 s59, s62, s38
	s_mov_b32 m0, s59
	ds_read_b128 v[198:201], v166 offset:16384
	ds_read_b128 v[202:205], v166 offset:17408
	ds_read_b128 v[206:209], v166 offset:18432
	ds_read_b128 v[210:213], v166 offset:19456
	ds_read_b128 v[214:217], v166 offset:20480
	ds_read_b128 v[218:221], v166 offset:21504
	ds_read_b128 v[222:225], v166 offset:22528
	ds_read_b128 v[226:229], v166 offset:23552
	global_load_lds_dwordx4 v134, s[28:29]
	s_add_i32 m0, s59, 0x2000
	s_add_u32 s60, s28, 0x80000
	s_addc_u32 s61, s29, 0
	s_add_i32 s59, s63, s38
	global_load_lds_dwordx4 v130, s[28:29]
	s_mov_b32 m0, s59
	s_nop 0
	global_load_lds_dwordx4 v134, s[60:61]
	s_add_i32 m0, s59, 0x2000
	s_nop 0
	global_load_lds_dwordx4 v130, s[60:61]
	s_mov_b32 m0, s44
	s_nop 0
	global_load_lds_dwordx4 v136, s[34:35]
	s_mov_b32 m0, s45
	s_nop 0
	global_load_lds_dwordx4 v132, s[34:35]
	s_waitcnt vmcnt(16)
	s_waitcnt lgkmcnt(0)
	v_mfma_f32_16x16x32_bf16 v[58:61], v[152:155], v[198:201], v[58:61]
	v_mfma_f32_16x16x32_bf16 v[50:53], v[168:171], v[198:201], v[50:53]
	v_mfma_f32_16x16x32_bf16 v[42:45], v[152:155], v[206:209], v[42:45]
	v_mfma_f32_16x16x32_bf16 v[34:37], v[168:171], v[206:209], v[34:37]
	s_barrier
	s_waitcnt lgkmcnt(0)
	v_mfma_f32_16x16x32_bf16 v[26:29], v[152:155], v[214:217], v[26:29]
	v_mfma_f32_16x16x32_bf16 v[18:21], v[168:171], v[214:217], v[18:21]
	v_mfma_f32_16x16x32_bf16 v[10:13], v[152:155], v[222:225], v[10:13]
	v_mfma_f32_16x16x32_bf16 v[6:9], v[168:171], v[222:225], v[6:9]
	v_mfma_f32_16x16x32_bf16 v[58:61], v[156:159], v[202:205], v[58:61]
	v_mfma_f32_16x16x32_bf16 v[50:53], v[172:175], v[202:205], v[50:53]
	v_mfma_f32_16x16x32_bf16 v[42:45], v[156:159], v[210:213], v[42:45]
	v_mfma_f32_16x16x32_bf16 v[34:37], v[172:175], v[210:213], v[34:37]
	v_mfma_f32_16x16x32_bf16 v[26:29], v[156:159], v[218:221], v[26:29]
	v_mfma_f32_16x16x32_bf16 v[18:21], v[172:175], v[218:221], v[18:21]
	v_mfma_f32_16x16x32_bf16 v[10:13], v[156:159], v[226:229], v[10:13]
	v_mfma_f32_16x16x32_bf16 v[6:9], v[172:175], v[226:229], v[6:9]
	v_mfma_f32_16x16x32_bf16 v[62:65], v[176:179], v[198:201], v[62:65]
	v_mfma_f32_16x16x32_bf16 v[54:57], v[184:187], v[198:201], v[54:57]
	v_mfma_f32_16x16x32_bf16 v[46:49], v[176:179], v[206:209], v[46:49]
	v_mfma_f32_16x16x32_bf16 v[38:41], v[184:187], v[206:209], v[38:41]
	v_mfma_f32_16x16x32_bf16 v[30:33], v[176:179], v[214:217], v[30:33]
	v_mfma_f32_16x16x32_bf16 v[22:25], v[184:187], v[214:217], v[22:25]
	v_mfma_f32_16x16x32_bf16 v[14:17], v[176:179], v[222:225], v[14:17]
	v_mfma_f32_16x16x32_bf16 v[2:5], v[184:187], v[222:225], v[2:5]
	v_mfma_f32_16x16x32_bf16 v[62:65], v[180:183], v[202:205], v[62:65]
	v_mfma_f32_16x16x32_bf16 v[54:57], v[188:191], v[202:205], v[54:57]
	v_mfma_f32_16x16x32_bf16 v[46:49], v[180:183], v[210:213], v[46:49]
	v_mfma_f32_16x16x32_bf16 v[38:41], v[188:191], v[210:213], v[38:41]
	v_mfma_f32_16x16x32_bf16 v[30:33], v[180:183], v[218:221], v[30:33]
	v_mfma_f32_16x16x32_bf16 v[22:25], v[188:191], v[218:221], v[22:25]
	v_mfma_f32_16x16x32_bf16 v[14:17], v[180:183], v[226:229], v[14:17]
	v_mfma_f32_16x16x32_bf16 v[2:5], v[188:191], v[226:229], v[2:5]
	s_barrier
; #define PG8_STAGE(bufoff, gbase, voff) do { _Pragma("unroll") for (int _i = 0; _i < 2; ++_i) \
;         __builtin_amdgcn_global_load_lds((const unsigned*)((const char*)(gbase) + (voff)[_i]), (LAS unsigned*)(lds + (bufoff) + ldsw + _i * 8192), 16, 0, 0); } while (0)
; #define PG8_LDA(dst, b, h) do { _Pragma("unroll") for (int m = 0; m < 4; ++m) _Pragma("unroll") for (int k = 0; k < 2; ++k) dst[m][k] = *(const LAS bf16x8*)(lds + PG8_SA(b, h) + aoff + m * 2048 + k * 1024); } while (0)
; #define PG8_LDB(dst, b, h) do { _Pragma("unroll") for (int n = 0; n < 2; ++n) _Pragma("unroll") for (int k = 0; k < 2; ++k) dst[n][k] = *(const LAS bf16x8*)(lds + PG8_SB(b, h) + boff + n * 2048 + k * 1024); } while (0)
; #define PG8_MMA(ai, bj, At, Bt) do { __builtin_amdgcn_s_setprio(1); _Pragma("unroll") for (int m = 0; m < 4; ++m) _Pragma("unroll") for (int n = 0; n < 2; ++n) _Pragma("unroll") for (int k = 0; k < 2; ++k) \
;         acc[ai][bj][m][n] = __builtin_amdgcn_mfma_f32_16x16x32_bf16(Bt[n][k], At[m][k], acc[ai][bj][m][n], 0, 0, 0); __builtin_amdgcn_s_setprio(0); } while (0)
; #define PG8_WAIT_V(n) asm volatile("s_waitcnt vmcnt(" #n ")" ::: "memory")
; #define PG8_WAIT_L(n) asm volatile("s_waitcnt lgkmcnt(" #n ")" ::: "memory")
; #define PG8_BAR __builtin_amdgcn_s_barrier()
; #define PG8_SCHED __builtin_amdgcn_sched_barrier(0)
; template <class Epi, class Sched, int KC, bool ALIGN_EPI = false, bool SP2 = false, bool ATILED = false>
; __device__ __forceinline__ void gemm_phase(LAS unsigned char* lds, const Gemm g, const Sched& S, const Epi& E, int wave_s) {
;     ...
;             PG8_LDB(B0, 1, 0); PG8_LDB(B1, 1, 1); PG8_SCHED; PG8_LDA(At, 1, 0); PG8_STAGE(PG8_SA(0, 1), a2 + hstepA, voffA);
;             PG8_WAIT_V(8); PG8_WAIT_L(0); PG8_BAR; PG8_MMA(0, 0, At, B0); PG8_MMA(0, 1, At, B1); PG8_BAR; PG8_SCHED;
;             PG8_LDA(At, 1, 1); PG8_STAGE(PG8_SB(1, 0), b3, voffB); PG8_STAGE(PG8_SB(1, 1), b3 + hstepB, voffB); PG8_STAGE(PG8_SA(1, 0), a3, voffA);
;             PG8_WAIT_V(8); PG8_WAIT_L(0); PG8_BAR; PG8_MMA(1, 0, At, B0); PG8_MMA(1, 1, At, B1); PG8_BAR; PG8_SCHED;
	s_add_i32 s59, 0, 0x18000
	v_add_u32_e32 v139, s59, v163
	s_add_i32 s60, 0, 0x1c000
	ds_read_b128 v[152:155], v139
	ds_read_b128 v[156:159], v139 offset:1024
	ds_read_b128 v[168:171], v139 offset:2048
	ds_read_b128 v[172:175], v139 offset:3072
	v_add_u32_e32 v139, s60, v163
	ds_read_b128 v[176:179], v139
	ds_read_b128 v[180:183], v139 offset:1024
	ds_read_b128 v[184:187], v139 offset:2048
	ds_read_b128 v[188:191], v139 offset:3072
	s_add_u32 s34, s34, 0x10000
	s_addc_u32 s35, s35, 0
	s_mov_b32 m0, s46
	ds_read_b128 v[198:201], v166 offset:32768
	ds_read_b128 v[202:205], v166 offset:33792
	ds_read_b128 v[206:209], v166 offset:34816
	ds_read_b128 v[210:213], v166 offset:35840
	ds_read_b128 v[214:217], v166 offset:36864
	ds_read_b128 v[218:221], v166 offset:37888
	ds_read_b128 v[222:225], v166 offset:38912
	ds_read_b128 v[226:229], v166 offset:39936
	global_load_lds_dwordx4 v136, s[34:35]
	s_mov_b32 m0, s47
	s_nop 0
	global_load_lds_dwordx4 v132, s[34:35]
	s_waitcnt vmcnt(8)
	s_waitcnt lgkmcnt(0)
	v_mfma_f32_16x16x32_bf16 v[122:125], v[152:155], v[198:201], v[122:125]
	v_mfma_f32_16x16x32_bf16 v[114:117], v[168:171], v[198:201], v[114:117]
	v_mfma_f32_16x16x32_bf16 v[106:109], v[152:155], v[206:209], v[106:109]
	v_mfma_f32_16x16x32_bf16 v[98:101], v[168:171], v[206:209], v[98:101]
	s_barrier
	s_waitcnt lgkmcnt(0)
	v_mfma_f32_16x16x32_bf16 v[90:93], v[152:155], v[214:217], v[90:93]
	v_mfma_f32_16x16x32_bf16 v[82:85], v[168:171], v[214:217], v[82:85]
	v_mfma_f32_16x16x32_bf16 v[74:77], v[152:155], v[222:225], v[74:77]
	v_mfma_f32_16x16x32_bf16 v[66:69], v[168:171], v[222:225], v[66:69]
	v_mfma_f32_16x16x32_bf16 v[122:125], v[156:159], v[202:205], v[122:125]
	v_mfma_f32_16x16x32_bf16 v[114:117], v[172:175], v[202:205], v[114:117]
	v_mfma_f32_16x16x32_bf16 v[106:109], v[156:159], v[210:213], v[106:109]
	v_mfma_f32_16x16x32_bf16 v[98:101], v[172:175], v[210:213], v[98:101]
	v_mfma_f32_16x16x32_bf16 v[90:93], v[156:159], v[218:221], v[90:93]
	v_mfma_f32_16x16x32_bf16 v[82:85], v[172:175], v[218:221], v[82:85]
	v_mfma_f32_16x16x32_bf16 v[74:77], v[156:159], v[226:229], v[74:77]
	v_mfma_f32_16x16x32_bf16 v[66:69], v[172:175], v[226:229], v[66:69]
	v_mfma_f32_16x16x32_bf16 v[126:129], v[176:179], v[198:201], v[126:129]
	v_mfma_f32_16x16x32_bf16 v[118:121], v[184:187], v[198:201], v[118:121]
	v_mfma_f32_16x16x32_bf16 v[110:113], v[176:179], v[206:209], v[110:113]
	v_mfma_f32_16x16x32_bf16 v[102:105], v[184:187], v[206:209], v[102:105]
	v_mfma_f32_16x16x32_bf16 v[94:97], v[176:179], v[214:217], v[94:97]
	v_mfma_f32_16x16x32_bf16 v[86:89], v[184:187], v[214:217], v[86:89]
	v_mfma_f32_16x16x32_bf16 v[78:81], v[176:179], v[222:225], v[78:81]
	v_mfma_f32_16x16x32_bf16 v[70:73], v[184:187], v[222:225], v[70:73]
	v_mfma_f32_16x16x32_bf16 v[126:129], v[180:183], v[202:205], v[126:129]
	v_mfma_f32_16x16x32_bf16 v[118:121], v[188:191], v[202:205], v[118:121]
	v_mfma_f32_16x16x32_bf16 v[110:113], v[180:183], v[210:213], v[110:113]
	v_mfma_f32_16x16x32_bf16 v[102:105], v[188:191], v[210:213], v[102:105]
	v_mfma_f32_16x16x32_bf16 v[94:97], v[180:183], v[218:221], v[94:97]
	v_mfma_f32_16x16x32_bf16 v[86:89], v[188:191], v[218:221], v[86:89]
	v_mfma_f32_16x16x32_bf16 v[78:81], v[180:183], v[226:229], v[78:81]
	v_mfma_f32_16x16x32_bf16 v[70:73], v[188:191], v[226:229], v[70:73]
	s_barrier
	s_add_u32 s98, s28, 0x80
	s_addc_u32 s99, s29, 0
	s_add_i32 s34, s59, s38
	s_mov_b32 m0, s34
	ds_read_b128 v[198:201], v166 offset:49152
	ds_read_b128 v[202:205], v166 offset:50176
	ds_read_b128 v[206:209], v166 offset:51200
	ds_read_b128 v[210:213], v166 offset:52224
	ds_read_b128 v[214:217], v166 offset:53248
	ds_read_b128 v[218:221], v166 offset:54272
	ds_read_b128 v[222:225], v166 offset:55296
	ds_read_b128 v[226:229], v166 offset:56320
	global_load_lds_dwordx4 v134, s[98:99]
	s_add_i32 m0, s34, 0x2000
	s_add_u32 s28, s28, 0x80080
	s_addc_u32 s29, s29, 0
	s_add_i32 s34, s60, s38
	global_load_lds_dwordx4 v130, s[98:99]
	s_mov_b32 m0, s34
	s_nop 0
	global_load_lds_dwordx4 v134, s[28:29]
	s_add_i32 m0, s34, 0x2000
	s_nop 0
	global_load_lds_dwordx4 v130, s[28:29]
	s_mov_b32 m0, s48
	s_nop 0
	global_load_lds_dwordx4 v136, s[100:101]
	s_mov_b32 m0, s49
	s_nop 0
	global_load_lds_dwordx4 v132, s[100:101]
	s_waitcnt vmcnt(8)
	s_waitcnt lgkmcnt(0)
	v_mfma_f32_16x16x32_bf16 v[58:61], v[152:155], v[198:201], v[58:61]
	v_mfma_f32_16x16x32_bf16 v[50:53], v[168:171], v[198:201], v[50:53]
	v_mfma_f32_16x16x32_bf16 v[42:45], v[152:155], v[206:209], v[42:45]
	v_mfma_f32_16x16x32_bf16 v[34:37], v[168:171], v[206:209], v[34:37]
	s_barrier
	s_waitcnt lgkmcnt(0)
	v_mfma_f32_16x16x32_bf16 v[26:29], v[152:155], v[214:217], v[26:29]
	v_mfma_f32_16x16x32_bf16 v[18:21], v[168:171], v[214:217], v[18:21]
	v_mfma_f32_16x16x32_bf16 v[10:13], v[152:155], v[222:225], v[10:13]
	v_mfma_f32_16x16x32_bf16 v[6:9], v[168:171], v[222:225], v[6:9]
	v_mfma_f32_16x16x32_bf16 v[58:61], v[156:159], v[202:205], v[58:61]
	v_mfma_f32_16x16x32_bf16 v[50:53], v[172:175], v[202:205], v[50:53]
	v_mfma_f32_16x16x32_bf16 v[42:45], v[156:159], v[210:213], v[42:45]
	v_mfma_f32_16x16x32_bf16 v[34:37], v[172:175], v[210:213], v[34:37]
	v_mfma_f32_16x16x32_bf16 v[26:29], v[156:159], v[218:221], v[26:29]
	v_mfma_f32_16x16x32_bf16 v[18:21], v[172:175], v[218:221], v[18:21]
	v_mfma_f32_16x16x32_bf16 v[10:13], v[156:159], v[226:229], v[10:13]
	v_mfma_f32_16x16x32_bf16 v[6:9], v[172:175], v[226:229], v[6:9]
	v_mfma_f32_16x16x32_bf16 v[62:65], v[176:179], v[198:201], v[62:65]
	v_mfma_f32_16x16x32_bf16 v[54:57], v[184:187], v[198:201], v[54:57]
	v_mfma_f32_16x16x32_bf16 v[46:49], v[176:179], v[206:209], v[46:49]
	v_mfma_f32_16x16x32_bf16 v[38:41], v[184:187], v[206:209], v[38:41]
	v_mfma_f32_16x16x32_bf16 v[30:33], v[176:179], v[214:217], v[30:33]
	v_mfma_f32_16x16x32_bf16 v[22:25], v[184:187], v[214:217], v[22:25]
	v_mfma_f32_16x16x32_bf16 v[14:17], v[176:179], v[222:225], v[14:17]
	v_mfma_f32_16x16x32_bf16 v[2:5], v[184:187], v[222:225], v[2:5]
	v_mfma_f32_16x16x32_bf16 v[62:65], v[180:183], v[202:205], v[62:65]
	v_mfma_f32_16x16x32_bf16 v[54:57], v[188:191], v[202:205], v[54:57]
	v_mfma_f32_16x16x32_bf16 v[46:49], v[180:183], v[210:213], v[46:49]
	v_mfma_f32_16x16x32_bf16 v[38:41], v[188:191], v[210:213], v[38:41]
	v_mfma_f32_16x16x32_bf16 v[30:33], v[180:183], v[218:221], v[30:33]
	v_mfma_f32_16x16x32_bf16 v[22:25], v[188:191], v[218:221], v[22:25]
	v_mfma_f32_16x16x32_bf16 v[14:17], v[180:183], v[226:229], v[14:17]
	v_mfma_f32_16x16x32_bf16 v[2:5], v[188:191], v[226:229], v[2:5]
	s_barrier
	s_add_i32 s57, s57, 2
	s_add_i32 s58, s58, 0x400000
	s_cmp_gt_u32 s57, 29
	s_mov_b64 s[28:29], s[30:31]
; #define PG8_STAGE(bufoff, gbase, voff) do { _Pragma("unroll") for (int _i = 0; _i < 2; ++_i) \
;         __builtin_amdgcn_global_load_lds((const unsigned*)((const char*)(gbase) + (voff)[_i]), (LAS unsigned*)(lds + (bufoff) + ldsw + _i * 8192), 16, 0, 0); } while (0)
; #define PG8_LDA(dst, b, h) do { _Pragma("unroll") for (int m = 0; m < 4; ++m) _Pragma("unroll") for (int k = 0; k < 2; ++k) dst[m][k] = *(const LAS bf16x8*)(lds + PG8_SA(b, h) + aoff + m * 2048 + k * 1024); } while (0)
; #define PG8_LDB(dst, b, h) do { _Pragma("unroll") for (int n = 0; n < 2; ++n) _Pragma("unroll") for (int k = 0; k < 2; ++k) dst[n][k] = *(const LAS bf16x8*)(lds + PG8_SB(b, h) + boff + n * 2048 + k * 1024); } while (0)
; #define PG8_MMA(ai, bj, At, Bt) do { __builtin_amdgcn_s_setprio(1); _Pragma("unroll") for (int m = 0; m < 4; ++m) _Pragma("unroll") for (int n = 0; n < 2; ++n) _Pragma("unroll") for (int k = 0; k < 2; ++k) \
;         acc[ai][bj][m][n] = __builtin_amdgcn_mfma_f32_16x16x32_bf16(Bt[n][k], At[m][k], acc[ai][bj][m][n], 0, 0, 0); __builtin_amdgcn_s_setprio(0); } while (0)
; #define PG8_WAIT_V(n) asm volatile("s_waitcnt vmcnt(" #n ")" ::: "memory")
; #define PG8_WAIT_L(n) asm volatile("s_waitcnt lgkmcnt(" #n ")" ::: "memory")
; #define PG8_BAR __builtin_amdgcn_s_barrier()
; #define PG8_SCHED __builtin_amdgcn_sched_barrier(0)
; template <class Epi, class Sched, int KC, bool ALIGN_EPI = false, bool SP2 = false, bool ATILED = false>
; __device__ __forceinline__ void gemm_phase(LAS unsigned char* lds, const Gemm g, const Sched& S, const Epi& E, int wave_s) {
;     ...
;             const bool last = (t == nt - 2);
;             const char* a1 = cA + PG8_AOFF(t + 1);
;             const char* a2 = last ? nA : cA + PG8_AOFF(t + 2); const char* b2 = last ? nB : cB + (size_t)(t + 2) * kstep;
;             const char* a3 = a2 + kstep; const char* b3 = b2 + kstep;
;             if (last && has_next) S.a_ready(nxt);
;             if constexpr (SP2) {
;             PG8_LDB(B0, 0, 0); PG8_LDB(B1, 0, 1); PG8_SCHED; PG8_LDA(At, 0, 0); PG8_STAGE(PG8_SA(1, 1), a1 + hstepA, voffA);
;             PG8_WAIT_V(8); PG8_WAIT_L(0); PG8_BAR; PG8_MMA(0, 0, At, B0); PG8_MMA(0, 1, At, B1); PG8_BAR; PG8_SCHED;
;             PG8_LDA(At, 0, 1); PG8_STAGE(PG8_SB(0, 0), b2, voffB); PG8_STAGE(PG8_SB(0, 1), b2 + hstepB, voffB); PG8_STAGE(PG8_SA(0, 0), a2, voffA);
.LBB0_233:
	s_add_i32 s30, s58, 0xffc00000
	s_and_b32 s30, s30, 0x3800000
	s_and_b32 s31, s28, 0x100
	s_or_b32 s59, s31, s30
	s_and_b32 s34, s58, 0x7800000
	s_add_u32 s30, s28, 0x100
	s_addc_u32 s31, s29, 0
	s_and_b32 s35, s30, 0x100
	s_or_b32 s34, s34, s35
	s_add_u32 s34, s26, s34
	s_addc_u32 s35, s27, 0
	s_add_u32 s28, s55, s28
	s_addc_u32 s29, s56, s29
	s_add_i32 s62, 0, 0x10000
	s_cmp_eq_u32 s57, 28
	s_cselect_b32 s35, s19, s35
	s_cselect_b32 s34, s53, s34
	v_add_u32_e32 v139, s62, v163
	s_cselect_b32 s29, s17, s29
	s_cselect_b32 s28, s54, s28
	s_add_i32 s63, 0, 0x14000
	ds_read_b128 v[152:155], v139
	ds_read_b128 v[156:159], v139 offset:1024
	ds_read_b128 v[168:171], v139 offset:2048
	ds_read_b128 v[172:175], v139 offset:3072
	v_add_u32_e32 v139, s63, v163
	ds_read_b128 v[176:179], v139
	ds_read_b128 v[180:183], v139 offset:1024
	ds_read_b128 v[184:187], v139 offset:2048
	ds_read_b128 v[188:191], v139 offset:3072
	s_add_u32 s59, s26, s59
	s_addc_u32 s61, s27, 0
	s_add_u32 s60, s59, 0x10080
	s_addc_u32 s61, s61, 0
	s_add_i32 m0, s44, 0xc000
	ds_read_b128 v[198:201], v166
	ds_read_b128 v[202:205], v166 offset:1024
	ds_read_b128 v[206:209], v166 offset:2048
	ds_read_b128 v[210:213], v166 offset:3072
	ds_read_b128 v[214:217], v166 offset:4096
	ds_read_b128 v[218:221], v166 offset:5120
	ds_read_b128 v[222:225], v166 offset:6144
	ds_read_b128 v[226:229], v166 offset:7168
	global_load_lds_dwordx4 v136, s[60:61]
	s_add_i32 m0, s44, 0xe000
	s_nop 0
	global_load_lds_dwordx4 v132, s[60:61]
	s_waitcnt vmcnt(8)
	s_waitcnt lgkmcnt(0)
	v_mfma_f32_16x16x32_bf16 v[122:125], v[152:155], v[198:201], v[122:125]
	v_mfma_f32_16x16x32_bf16 v[114:117], v[168:171], v[198:201], v[114:117]
	v_mfma_f32_16x16x32_bf16 v[106:109], v[152:155], v[206:209], v[106:109]
	v_mfma_f32_16x16x32_bf16 v[98:101], v[168:171], v[206:209], v[98:101]
	s_barrier
	s_waitcnt lgkmcnt(0)
	v_mfma_f32_16x16x32_bf16 v[90:93], v[152:155], v[214:217], v[90:93]
	v_mfma_f32_16x16x32_bf16 v[82:85], v[168:171], v[214:217], v[82:85]
	v_mfma_f32_16x16x32_bf16 v[74:77], v[152:155], v[222:225], v[74:77]
	v_mfma_f32_16x16x32_bf16 v[66:69], v[168:171], v[222:225], v[66:69]
	v_mfma_f32_16x16x32_bf16 v[122:125], v[156:159], v[202:205], v[122:125]
	v_mfma_f32_16x16x32_bf16 v[114:117], v[172:175], v[202:205], v[114:117]
	v_mfma_f32_16x16x32_bf16 v[106:109], v[156:159], v[210:213], v[106:109]
	v_mfma_f32_16x16x32_bf16 v[98:101], v[172:175], v[210:213], v[98:101]
	v_mfma_f32_16x16x32_bf16 v[90:93], v[156:159], v[218:221], v[90:93]
	v_mfma_f32_16x16x32_bf16 v[82:85], v[172:175], v[218:221], v[82:85]
	v_mfma_f32_16x16x32_bf16 v[74:77], v[156:159], v[226:229], v[74:77]
	v_mfma_f32_16x16x32_bf16 v[66:69], v[172:175], v[226:229], v[66:69]
	v_mfma_f32_16x16x32_bf16 v[126:129], v[176:179], v[198:201], v[126:129]
	v_mfma_f32_16x16x32_bf16 v[118:121], v[184:187], v[198:201], v[118:121]
	v_mfma_f32_16x16x32_bf16 v[110:113], v[176:179], v[206:209], v[110:113]
	v_mfma_f32_16x16x32_bf16 v[102:105], v[184:187], v[206:209], v[102:105]
	v_mfma_f32_16x16x32_bf16 v[94:97], v[176:179], v[214:217], v[94:97]
	v_mfma_f32_16x16x32_bf16 v[86:89], v[184:187], v[214:217], v[86:89]
	v_mfma_f32_16x16x32_bf16 v[78:81], v[176:179], v[222:225], v[78:81]
	v_mfma_f32_16x16x32_bf16 v[70:73], v[184:187], v[222:225], v[70:73]
	v_mfma_f32_16x16x32_bf16 v[126:129], v[180:183], v[202:205], v[126:129]
	v_mfma_f32_16x16x32_bf16 v[118:121], v[188:191], v[202:205], v[118:121]
	v_mfma_f32_16x16x32_bf16 v[110:113], v[180:183], v[210:213], v[110:113]
	v_mfma_f32_16x16x32_bf16 v[102:105], v[188:191], v[210:213], v[102:105]
	v_mfma_f32_16x16x32_bf16 v[94:97], v[180:183], v[218:221], v[94:97]
	v_mfma_f32_16x16x32_bf16 v[86:89], v[188:191], v[218:221], v[86:89]
	v_mfma_f32_16x16x32_bf16 v[78:81], v[180:183], v[226:229], v[78:81]
	v_mfma_f32_16x16x32_bf16 v[70:73], v[188:191], v[226:229], v[70:73]
	s_barrier
	s_add_u32 s100, s34, 0x80
	s_addc_u32 s101, s35, 0
	s_add_i32 s59, s62, s38
	s_mov_b32 m0, s59
	ds_read_b128 v[198:201], v166 offset:16384
	ds_read_b128 v[202:205], v166 offset:17408
	ds_read_b128 v[206:209], v166 offset:18432
	ds_read_b128 v[210:213], v166 offset:19456
	ds_read_b128 v[214:217], v166 offset:20480
	ds_read_b128 v[218:221], v166 offset:21504
	ds_read_b128 v[222:225], v166 offset:22528
	ds_read_b128 v[226:229], v166 offset:23552
	global_load_lds_dwordx4 v134, s[28:29]
	s_add_i32 m0, s59, 0x2000
	s_add_u32 s60, s28, 0x80000
	s_addc_u32 s61, s29, 0
	s_add_i32 s59, s63, s38
	global_load_lds_dwordx4 v130, s[28:29]
	s_mov_b32 m0, s59
	s_nop 0
	global_load_lds_dwordx4 v134, s[60:61]
	s_add_i32 m0, s59, 0x2000
	s_nop 0
	global_load_lds_dwordx4 v130, s[60:61]
	s_mov_b32 m0, s44
	s_nop 0
	global_load_lds_dwordx4 v136, s[34:35]
	s_mov_b32 m0, s45
	s_nop 0
	global_load_lds_dwordx4 v132, s[34:35]
	s_waitcnt vmcnt(8)
	s_waitcnt lgkmcnt(0)
	v_mfma_f32_16x16x32_bf16 v[58:61], v[152:155], v[198:201], v[58:61]
	v_mfma_f32_16x16x32_bf16 v[50:53], v[168:171], v[198:201], v[50:53]
	v_mfma_f32_16x16x32_bf16 v[42:45], v[152:155], v[206:209], v[42:45]
	v_mfma_f32_16x16x32_bf16 v[34:37], v[168:171], v[206:209], v[34:37]
	s_barrier
; #define PG8_STAGE(bufoff, gbase, voff) do { _Pragma("unroll") for (int _i = 0; _i < 2; ++_i) \
;         __builtin_amdgcn_global_load_lds((const unsigned*)((const char*)(gbase) + (voff)[_i]), (LAS unsigned*)(lds + (bufoff) + ldsw + _i * 8192), 16, 0, 0); } while (0)
; #define PG8_LDA(dst, b, h) do { _Pragma("unroll") for (int m = 0; m < 4; ++m) _Pragma("unroll") for (int k = 0; k < 2; ++k) dst[m][k] = *(const LAS bf16x8*)(lds + PG8_SA(b, h) + aoff + m * 2048 + k * 1024); } while (0)
; #define PG8_LDB(dst, b, h) do { _Pragma("unroll") for (int n = 0; n < 2; ++n) _Pragma("unroll") for (int k = 0; k < 2; ++k) dst[n][k] = *(const LAS bf16x8*)(lds + PG8_SB(b, h) + boff + n * 2048 + k * 1024); } while (0)
; #define PG8_MMA(ai, bj, At, Bt) do { __builtin_amdgcn_s_setprio(1); _Pragma("unroll") for (int m = 0; m < 4; ++m) _Pragma("unroll") for (int n = 0; n < 2; ++n) _Pragma("unroll") for (int k = 0; k < 2; ++k) \
;         acc[ai][bj][m][n] = __builtin_amdgcn_mfma_f32_16x16x32_bf16(Bt[n][k], At[m][k], acc[ai][bj][m][n], 0, 0, 0); __builtin_amdgcn_s_setprio(0); } while (0)
; #define PG8_WAIT_V(n) asm volatile("s_waitcnt vmcnt(" #n ")" ::: "memory")
; #define PG8_WAIT_L(n) asm volatile("s_waitcnt lgkmcnt(" #n ")" ::: "memory")
; #define PG8_BAR __builtin_amdgcn_s_barrier()
; #define PG8_SCHED __builtin_amdgcn_sched_barrier(0)
; template <class Epi, class Sched, int KC, bool ALIGN_EPI = false, bool SP2 = false, bool ATILED = false>
; __device__ __forceinline__ void gemm_phase(LAS unsigned char* lds, const Gemm g, const Sched& S, const Epi& E, int wave_s) {
;     ...
;             PG8_WAIT_V(8); PG8_WAIT_L(0); PG8_BAR; PG8_MMA(1, 0, At, B0); PG8_MMA(1, 1, At, B1); PG8_BAR; PG8_SCHED;
;             PG8_LDB(B0, 1, 0); PG8_LDB(B1, 1, 1); PG8_SCHED; PG8_LDA(At, 1, 0); PG8_STAGE(PG8_SA(0, 1), a2 + hstepA, voffA);
;             PG8_WAIT_V(8); PG8_WAIT_L(0); PG8_BAR; PG8_MMA(0, 0, At, B0); PG8_MMA(0, 1, At, B1); PG8_BAR; PG8_SCHED;
	s_waitcnt lgkmcnt(0)
	v_mfma_f32_16x16x32_bf16 v[26:29], v[152:155], v[214:217], v[26:29]
	v_mfma_f32_16x16x32_bf16 v[18:21], v[168:171], v[214:217], v[18:21]
	v_mfma_f32_16x16x32_bf16 v[10:13], v[152:155], v[222:225], v[10:13]
	v_mfma_f32_16x16x32_bf16 v[6:9], v[168:171], v[222:225], v[6:9]
	v_mfma_f32_16x16x32_bf16 v[58:61], v[156:159], v[202:205], v[58:61]
	v_mfma_f32_16x16x32_bf16 v[50:53], v[172:175], v[202:205], v[50:53]
	v_mfma_f32_16x16x32_bf16 v[42:45], v[156:159], v[210:213], v[42:45]
	v_mfma_f32_16x16x32_bf16 v[34:37], v[172:175], v[210:213], v[34:37]
	v_mfma_f32_16x16x32_bf16 v[26:29], v[156:159], v[218:221], v[26:29]
	v_mfma_f32_16x16x32_bf16 v[18:21], v[172:175], v[218:221], v[18:21]
	v_mfma_f32_16x16x32_bf16 v[10:13], v[156:159], v[226:229], v[10:13]
	v_mfma_f32_16x16x32_bf16 v[6:9], v[172:175], v[226:229], v[6:9]
	v_mfma_f32_16x16x32_bf16 v[62:65], v[176:179], v[198:201], v[62:65]
	v_mfma_f32_16x16x32_bf16 v[54:57], v[184:187], v[198:201], v[54:57]
	v_mfma_f32_16x16x32_bf16 v[46:49], v[176:179], v[206:209], v[46:49]
	v_mfma_f32_16x16x32_bf16 v[38:41], v[184:187], v[206:209], v[38:41]
	v_mfma_f32_16x16x32_bf16 v[30:33], v[176:179], v[214:217], v[30:33]
	v_mfma_f32_16x16x32_bf16 v[22:25], v[184:187], v[214:217], v[22:25]
	v_mfma_f32_16x16x32_bf16 v[14:17], v[176:179], v[222:225], v[14:17]
	v_mfma_f32_16x16x32_bf16 v[2:5], v[184:187], v[222:225], v[2:5]
	v_mfma_f32_16x16x32_bf16 v[62:65], v[180:183], v[202:205], v[62:65]
	v_mfma_f32_16x16x32_bf16 v[54:57], v[188:191], v[202:205], v[54:57]
	v_mfma_f32_16x16x32_bf16 v[46:49], v[180:183], v[210:213], v[46:49]
	v_mfma_f32_16x16x32_bf16 v[38:41], v[188:191], v[210:213], v[38:41]
	v_mfma_f32_16x16x32_bf16 v[30:33], v[180:183], v[218:221], v[30:33]
	v_mfma_f32_16x16x32_bf16 v[22:25], v[188:191], v[218:221], v[22:25]
	v_mfma_f32_16x16x32_bf16 v[14:17], v[180:183], v[226:229], v[14:17]
	v_mfma_f32_16x16x32_bf16 v[2:5], v[188:191], v[226:229], v[2:5]
	s_barrier
	s_add_i32 s59, 0, 0x18000
	v_add_u32_e32 v139, s59, v163
	s_add_i32 s60, 0, 0x1c000
	ds_read_b128 v[152:155], v139
	ds_read_b128 v[156:159], v139 offset:1024
	ds_read_b128 v[168:171], v139 offset:2048
	ds_read_b128 v[172:175], v139 offset:3072
	v_add_u32_e32 v139, s60, v163
	ds_read_b128 v[176:179], v139
	ds_read_b128 v[180:183], v139 offset:1024
	ds_read_b128 v[184:187], v139 offset:2048
	ds_read_b128 v[188:191], v139 offset:3072
	s_add_u32 s34, s34, 0x10000
	s_addc_u32 s35, s35, 0
	s_mov_b32 m0, s46
	ds_read_b128 v[198:201], v166 offset:32768
	ds_read_b128 v[202:205], v166 offset:33792
	ds_read_b128 v[206:209], v166 offset:34816
	ds_read_b128 v[210:213], v166 offset:35840
	ds_read_b128 v[214:217], v166 offset:36864
	ds_read_b128 v[218:221], v166 offset:37888
	ds_read_b128 v[222:225], v166 offset:38912
	ds_read_b128 v[226:229], v166 offset:39936
	global_load_lds_dwordx4 v136, s[34:35]
	s_mov_b32 m0, s47
	s_nop 0
	global_load_lds_dwordx4 v132, s[34:35]
	s_waitcnt vmcnt(8)
	s_waitcnt lgkmcnt(0)
	v_mfma_f32_16x16x32_bf16 v[122:125], v[152:155], v[198:201], v[122:125]
	v_mfma_f32_16x16x32_bf16 v[114:117], v[168:171], v[198:201], v[114:117]
	v_mfma_f32_16x16x32_bf16 v[106:109], v[152:155], v[206:209], v[106:109]
	v_mfma_f32_16x16x32_bf16 v[98:101], v[168:171], v[206:209], v[98:101]
	s_barrier
	s_waitcnt lgkmcnt(0)
	v_mfma_f32_16x16x32_bf16 v[90:93], v[152:155], v[214:217], v[90:93]
	v_mfma_f32_16x16x32_bf16 v[82:85], v[168:171], v[214:217], v[82:85]
	v_mfma_f32_16x16x32_bf16 v[74:77], v[152:155], v[222:225], v[74:77]
	v_mfma_f32_16x16x32_bf16 v[66:69], v[168:171], v[222:225], v[66:69]
	v_mfma_f32_16x16x32_bf16 v[122:125], v[156:159], v[202:205], v[122:125]
	v_mfma_f32_16x16x32_bf16 v[114:117], v[172:175], v[202:205], v[114:117]
	v_mfma_f32_16x16x32_bf16 v[106:109], v[156:159], v[210:213], v[106:109]
	v_mfma_f32_16x16x32_bf16 v[98:101], v[172:175], v[210:213], v[98:101]
	v_mfma_f32_16x16x32_bf16 v[90:93], v[156:159], v[218:221], v[90:93]
	v_mfma_f32_16x16x32_bf16 v[82:85], v[172:175], v[218:221], v[82:85]
	v_mfma_f32_16x16x32_bf16 v[74:77], v[156:159], v[226:229], v[74:77]
	v_mfma_f32_16x16x32_bf16 v[66:69], v[172:175], v[226:229], v[66:69]
	v_mfma_f32_16x16x32_bf16 v[126:129], v[176:179], v[198:201], v[126:129]
	v_mfma_f32_16x16x32_bf16 v[118:121], v[184:187], v[198:201], v[118:121]
	v_mfma_f32_16x16x32_bf16 v[110:113], v[176:179], v[206:209], v[110:113]
	v_mfma_f32_16x16x32_bf16 v[102:105], v[184:187], v[206:209], v[102:105]
	v_mfma_f32_16x16x32_bf16 v[94:97], v[176:179], v[214:217], v[94:97]
	v_mfma_f32_16x16x32_bf16 v[86:89], v[184:187], v[214:217], v[86:89]
	v_mfma_f32_16x16x32_bf16 v[78:81], v[176:179], v[222:225], v[78:81]
	v_mfma_f32_16x16x32_bf16 v[70:73], v[184:187], v[222:225], v[70:73]
	v_mfma_f32_16x16x32_bf16 v[126:129], v[180:183], v[202:205], v[126:129]
	v_mfma_f32_16x16x32_bf16 v[118:121], v[188:191], v[202:205], v[118:121]
	v_mfma_f32_16x16x32_bf16 v[110:113], v[180:183], v[210:213], v[110:113]
	v_mfma_f32_16x16x32_bf16 v[102:105], v[188:191], v[210:213], v[102:105]
	v_mfma_f32_16x16x32_bf16 v[94:97], v[180:183], v[218:221], v[94:97]
	v_mfma_f32_16x16x32_bf16 v[86:89], v[188:191], v[218:221], v[86:89]
	v_mfma_f32_16x16x32_bf16 v[78:81], v[180:183], v[226:229], v[78:81]
	v_mfma_f32_16x16x32_bf16 v[70:73], v[188:191], v[226:229], v[70:73]
	s_barrier
; #define PG8_STAGE(bufoff, gbase, voff) do { _Pragma("unroll") for (int _i = 0; _i < 2; ++_i) \
;         __builtin_amdgcn_global_load_lds((const unsigned*)((const char*)(gbase) + (voff)[_i]), (LAS unsigned*)(lds + (bufoff) + ldsw + _i * 8192), 16, 0, 0); } while (0)
; #define PG8_LDA(dst, b, h) do { _Pragma("unroll") for (int m = 0; m < 4; ++m) _Pragma("unroll") for (int k = 0; k < 2; ++k) dst[m][k] = *(const LAS bf16x8*)(lds + PG8_SA(b, h) + aoff + m * 2048 + k * 1024); } while (0)
; #define PG8_MMA(ai, bj, At, Bt) do { __builtin_amdgcn_s_setprio(1); _Pragma("unroll") for (int m = 0; m < 4; ++m) _Pragma("unroll") for (int n = 0; n < 2; ++n) _Pragma("unroll") for (int k = 0; k < 2; ++k) \
;         acc[ai][bj][m][n] = __builtin_amdgcn_mfma_f32_16x16x32_bf16(Bt[n][k], At[m][k], acc[ai][bj][m][n], 0, 0, 0); __builtin_amdgcn_s_setprio(0); } while (0)
; #define PG8_WAIT_V(n) asm volatile("s_waitcnt vmcnt(" #n ")" ::: "memory")
; #define PG8_WAIT_L(n) asm volatile("s_waitcnt lgkmcnt(" #n ")" ::: "memory")
; #define PG8_BAR __builtin_amdgcn_s_barrier()
; #define PG8_SCHED __builtin_amdgcn_sched_barrier(0)
; template <class Epi, class Sched, int KC, bool ALIGN_EPI = false, bool SP2 = false, bool ATILED = false>
; __device__ __forceinline__ void gemm_phase(LAS unsigned char* lds, const Gemm g, const Sched& S, const Epi& E, int wave_s) {
;     ...
;             PG8_LDA(At, 1, 1); PG8_STAGE(PG8_SB(1, 0), b3, voffB); PG8_STAGE(PG8_SB(1, 1), b3 + hstepB, voffB); PG8_STAGE(PG8_SA(1, 0), a3, voffA);
;             PG8_WAIT_V(8); PG8_WAIT_L(0); PG8_BAR; PG8_MMA(1, 0, At, B0); PG8_MMA(1, 1, At, B1); PG8_BAR; PG8_SCHED;
;     ...
;         if constexpr (ALIGN_EPI) { if (wr == 0) PG8_BAR; }
	s_add_u32 s98, s28, 0x80
	s_addc_u32 s99, s29, 0
	s_add_i32 s34, s59, s38
	s_mov_b32 m0, s34
	ds_read_b128 v[198:201], v166 offset:49152
	ds_read_b128 v[202:205], v166 offset:50176
	ds_read_b128 v[206:209], v166 offset:51200
	ds_read_b128 v[210:213], v166 offset:52224
	ds_read_b128 v[214:217], v166 offset:53248
	ds_read_b128 v[218:221], v166 offset:54272
	ds_read_b128 v[222:225], v166 offset:55296
	ds_read_b128 v[226:229], v166 offset:56320
	global_load_lds_dwordx4 v134, s[98:99]
	s_add_i32 m0, s34, 0x2000
	s_add_u32 s28, s28, 0x80080
	s_addc_u32 s29, s29, 0
	s_add_i32 s34, s60, s38
	global_load_lds_dwordx4 v130, s[98:99]
	s_mov_b32 m0, s34
	s_nop 0
	global_load_lds_dwordx4 v134, s[28:29]
	s_add_i32 m0, s34, 0x2000
	s_nop 0
	global_load_lds_dwordx4 v130, s[28:29]
	s_mov_b32 m0, s48
	s_nop 0
	global_load_lds_dwordx4 v136, s[100:101]
	s_mov_b32 m0, s49
	s_nop 0
	global_load_lds_dwordx4 v132, s[100:101]
	s_waitcnt vmcnt(8)
	s_waitcnt lgkmcnt(0)
	v_mfma_f32_16x16x32_bf16 v[58:61], v[152:155], v[198:201], v[58:61]
	v_mfma_f32_16x16x32_bf16 v[50:53], v[168:171], v[198:201], v[50:53]
	v_mfma_f32_16x16x32_bf16 v[42:45], v[152:155], v[206:209], v[42:45]
	v_mfma_f32_16x16x32_bf16 v[34:37], v[168:171], v[206:209], v[34:37]
	s_barrier
	s_waitcnt lgkmcnt(0)
	v_mfma_f32_16x16x32_bf16 v[26:29], v[152:155], v[214:217], v[26:29]
	v_mfma_f32_16x16x32_bf16 v[18:21], v[168:171], v[214:217], v[18:21]
	v_mfma_f32_16x16x32_bf16 v[10:13], v[152:155], v[222:225], v[10:13]
	v_mfma_f32_16x16x32_bf16 v[6:9], v[168:171], v[222:225], v[6:9]
	v_mfma_f32_16x16x32_bf16 v[58:61], v[156:159], v[202:205], v[58:61]
	v_mfma_f32_16x16x32_bf16 v[50:53], v[172:175], v[202:205], v[50:53]
	v_mfma_f32_16x16x32_bf16 v[42:45], v[156:159], v[210:213], v[42:45]
	v_mfma_f32_16x16x32_bf16 v[34:37], v[172:175], v[210:213], v[34:37]
	v_mfma_f32_16x16x32_bf16 v[26:29], v[156:159], v[218:221], v[26:29]
	v_mfma_f32_16x16x32_bf16 v[18:21], v[172:175], v[218:221], v[18:21]
	v_mfma_f32_16x16x32_bf16 v[10:13], v[156:159], v[226:229], v[10:13]
	v_mfma_f32_16x16x32_bf16 v[6:9], v[172:175], v[226:229], v[6:9]
	v_mfma_f32_16x16x32_bf16 v[62:65], v[176:179], v[198:201], v[62:65]
	v_mfma_f32_16x16x32_bf16 v[54:57], v[184:187], v[198:201], v[54:57]
	v_mfma_f32_16x16x32_bf16 v[46:49], v[176:179], v[206:209], v[46:49]
	v_mfma_f32_16x16x32_bf16 v[38:41], v[184:187], v[206:209], v[38:41]
	v_mfma_f32_16x16x32_bf16 v[30:33], v[176:179], v[214:217], v[30:33]
	v_mfma_f32_16x16x32_bf16 v[22:25], v[184:187], v[214:217], v[22:25]
	v_mfma_f32_16x16x32_bf16 v[14:17], v[176:179], v[222:225], v[14:17]
	v_mfma_f32_16x16x32_bf16 v[2:5], v[184:187], v[222:225], v[2:5]
	v_mfma_f32_16x16x32_bf16 v[62:65], v[180:183], v[202:205], v[62:65]
	v_mfma_f32_16x16x32_bf16 v[54:57], v[188:191], v[202:205], v[54:57]
	v_mfma_f32_16x16x32_bf16 v[46:49], v[180:183], v[210:213], v[46:49]
	v_mfma_f32_16x16x32_bf16 v[38:41], v[188:191], v[210:213], v[38:41]
	v_mfma_f32_16x16x32_bf16 v[30:33], v[180:183], v[218:221], v[30:33]
	v_mfma_f32_16x16x32_bf16 v[22:25], v[188:191], v[218:221], v[22:25]
	v_mfma_f32_16x16x32_bf16 v[14:17], v[180:183], v[226:229], v[14:17]
	v_mfma_f32_16x16x32_bf16 v[2:5], v[188:191], v[226:229], v[2:5]
	s_barrier
	s_add_i32 s57, s57, 2
	s_add_i32 s58, s58, 0x400000
	s_cmp_gt_u32 s57, 29
	s_mov_b64 s[28:29], s[30:31]
	s_cbranch_scc0 .LBB0_233
	s_and_b64 vcc, exec, s[14:15]
	s_cbranch_vccz .LBB0_236
	s_barrier

; #define PG8_STAGE(bufoff, gbase, voff) do { _Pragma("unroll") for (int _i = 0; _i < 2; ++_i) \
;         __builtin_amdgcn_global_load_lds((const unsigned*)((const char*)(gbase) + (voff)[_i]), (LAS unsigned*)(lds + (bufoff) + ldsw + _i * 8192), 16, 0, 0); } while (0)
; #define PG8_LDA(dst, b, h) do { _Pragma("unroll") for (int m = 0; m < 4; ++m) _Pragma("unroll") for (int k = 0; k < 2; ++k) dst[m][k] = *(const LAS bf16x8*)(lds + PG8_SA(b, h) + aoff + m * 2048 + k * 1024); } while (0)
; #define PG8_LDB(dst, b, h) do { _Pragma("unroll") for (int n = 0; n < 2; ++n) _Pragma("unroll") for (int k = 0; k < 2; ++k) dst[n][k] = *(const LAS bf16x8*)(lds + PG8_SB(b, h) + boff + n * 2048 + k * 1024); } while (0)
; #define PG8_WAIT_V(n) asm volatile("s_waitcnt vmcnt(" #n ")" ::: "memory")
; #define PG8_WAIT_L(n) asm volatile("s_waitcnt lgkmcnt(" #n ")" ::: "memory")
; #define PG8_BAR __builtin_amdgcn_s_barrier()
; #define PG8_SCHED __builtin_amdgcn_sched_barrier(0)
; template <class Epi, class Sched, int KC, bool ALIGN_EPI = false, bool SP2 = false, bool ATILED = false>
; __device__ __forceinline__ void gemm_phase(LAS unsigned char* lds, const Gemm g, const Sched& S, const Epi& E, int wave_s) {
;     ...
;         const bool has_next = S.next(ui + 1, nxt);
;         const char* nA = has_next ? (const char*)g.A + (size_t)nxt.pm * tstepA : cA; const char* nB = has_next ? (const char*)g.Bt + (size_t)nxt.pn * tstep : cB;
;         for (int t = 0; t < nt; t += 2) {
;             const bool last = (t == nt - 2);
;             const char* a1 = cA + PG8_AOFF(t + 1);
;             const char* a2 = last ? nA : cA + PG8_AOFF(t + 2); const char* b2 = last ? nB : cB + (size_t)(t + 2) * kstep;
;             const char* a3 = a2 + kstep; const char* b3 = b2 + kstep;
;             if (last && has_next) S.a_ready(nxt);
;             if constexpr (SP2) {
;             PG8_LDB(B0, 0, 0); PG8_LDB(B1, 0, 1); PG8_SCHED; PG8_LDA(At, 0, 0); PG8_STAGE(PG8_SA(1, 1), a1 + hstepA, voffA);
;             PG8_WAIT_V(8); PG8_WAIT_L(0); PG8_BAR; PG8_MMA(0, 0, At, B0); PG8_MMA(0, 1, At, B1); PG8_BAR; PG8_SCHED;
;     ...
; #pragma unroll
;         for (int a = 0; a < 2; ++a)
; #pragma unroll
;             for (int b = 0; b < 2; ++b)
; #pragma unroll
;                 for (int m = 0; m < 4; ++m)
; #pragma unroll
;                     for (int n = 0; n < 2; ++n) acc[a][b][m][n] = (f32x4){0.f, 0.f, 0.f, 0.f};
.LBB0_317:
	s_add_u32 s50, s22, 0x100
	v_mov_b32_e32 v2, 0
	s_addc_u32 s51, s23, 0
	s_mov_b32 s52, -2
	v_mov_b32_e32 v3, v2
	v_mov_b32_e32 v4, v2
	v_mov_b32_e32 v5, v2
	v_mov_b32_e32 v6, v2
	v_mov_b32_e32 v7, v2
	v_mov_b32_e32 v8, v2
	v_mov_b32_e32 v9, v2
	v_mov_b32_e32 v18, v2
	v_mov_b32_e32 v19, v2
	v_mov_b32_e32 v20, v2
	v_mov_b32_e32 v21, v2
	v_mov_b32_e32 v22, v2
	v_mov_b32_e32 v23, v2
	v_mov_b32_e32 v24, v2
	v_mov_b32_e32 v25, v2
	v_mov_b32_e32 v34, v2
	v_mov_b32_e32 v35, v2
	v_mov_b32_e32 v36, v2
	v_mov_b32_e32 v37, v2
	v_mov_b32_e32 v38, v2
	v_mov_b32_e32 v39, v2
	v_mov_b32_e32 v40, v2
	v_mov_b32_e32 v41, v2
	v_mov_b32_e32 v50, v2
	v_mov_b32_e32 v51, v2
	v_mov_b32_e32 v52, v2
	v_mov_b32_e32 v53, v2
	v_mov_b32_e32 v54, v2
	v_mov_b32_e32 v55, v2
	v_mov_b32_e32 v56, v2
	v_mov_b32_e32 v57, v2
	v_mov_b32_e32 v10, v2
	v_mov_b32_e32 v11, v2
	v_mov_b32_e32 v12, v2
	v_mov_b32_e32 v13, v2
	v_mov_b32_e32 v14, v2
	v_mov_b32_e32 v15, v2
	v_mov_b32_e32 v16, v2
	v_mov_b32_e32 v17, v2
	v_mov_b32_e32 v26, v2
	v_mov_b32_e32 v27, v2
	v_mov_b32_e32 v28, v2
	v_mov_b32_e32 v29, v2
	v_mov_b32_e32 v30, v2
	v_mov_b32_e32 v31, v2
	v_mov_b32_e32 v32, v2
	v_mov_b32_e32 v33, v2
	v_mov_b32_e32 v42, v2
	v_mov_b32_e32 v43, v2
	v_mov_b32_e32 v44, v2
	v_mov_b32_e32 v45, v2
	v_mov_b32_e32 v46, v2
	v_mov_b32_e32 v47, v2
	v_mov_b32_e32 v48, v2
	v_mov_b32_e32 v49, v2
	v_mov_b32_e32 v58, v2
	v_mov_b32_e32 v59, v2
	v_mov_b32_e32 v60, v2
	v_mov_b32_e32 v61, v2
	v_mov_b32_e32 v62, v2
	v_mov_b32_e32 v63, v2
	v_mov_b32_e32 v64, v2
	v_mov_b32_e32 v65, v2
	v_mov_b32_e32 v66, v2
	v_mov_b32_e32 v67, v2
	v_mov_b32_e32 v68, v2
	v_mov_b32_e32 v69, v2
	v_mov_b32_e32 v70, v2
	v_mov_b32_e32 v71, v2
	v_mov_b32_e32 v72, v2
	v_mov_b32_e32 v73, v2
	v_mov_b32_e32 v86, v2
	v_mov_b32_e32 v87, v2
	v_mov_b32_e32 v88, v2
	v_mov_b32_e32 v89, v2
	v_mov_b32_e32 v90, v2
	v_mov_b32_e32 v91, v2
	v_mov_b32_e32 v92, v2
	v_mov_b32_e32 v93, v2
	v_mov_b32_e32 v110, v2
	v_mov_b32_e32 v111, v2
	v_mov_b32_e32 v112, v2
	v_mov_b32_e32 v113, v2
	v_mov_b32_e32 v118, v2
	v_mov_b32_e32 v119, v2
	v_mov_b32_e32 v120, v2
	v_mov_b32_e32 v121, v2
	v_mov_b32_e32 v138, v2
	v_mov_b32_e32 v139, v2
	v_mov_b32_e32 v140, v2
	v_mov_b32_e32 v141, v2
	v_mov_b32_e32 v142, v2
	v_mov_b32_e32 v143, v2
	v_mov_b32_e32 v144, v2
	v_mov_b32_e32 v145, v2
	v_mov_b32_e32 v74, v2
	v_mov_b32_e32 v75, v2
	v_mov_b32_e32 v76, v2
	v_mov_b32_e32 v77, v2
	v_mov_b32_e32 v78, v2
	v_mov_b32_e32 v79, v2
	v_mov_b32_e32 v80, v2
	v_mov_b32_e32 v81, v2
	v_mov_b32_e32 v98, v2
	v_mov_b32_e32 v99, v2
	v_mov_b32_e32 v100, v2
	v_mov_b32_e32 v101, v2
	v_mov_b32_e32 v102, v2
	v_mov_b32_e32 v103, v2
	v_mov_b32_e32 v104, v2
	v_mov_b32_e32 v105, v2
	v_mov_b32_e32 v122, v2
	v_mov_b32_e32 v123, v2
	v_mov_b32_e32 v124, v2
	v_mov_b32_e32 v125, v2
	v_mov_b32_e32 v126, v2
	v_mov_b32_e32 v127, v2
	v_mov_b32_e32 v128, v2
	v_mov_b32_e32 v129, v2
	v_mov_b32_e32 v158, v2
	v_mov_b32_e32 v159, v2
	v_mov_b32_e32 v160, v2
	v_mov_b32_e32 v161, v2
	v_mov_b32_e32 v162, v2
	v_mov_b32_e32 v163, v2
	v_mov_b32_e32 v164, v2
	v_mov_b32_e32 v165, v2
	s_add_u32 s8, s20, 0x100
	s_addc_u32 s9, s21, 0
	s_add_i32 s53, 0, 0x10000
	s_cmpk_eq_i32 s52, 0x54
	s_cselect_b32 s25, s17, s9
	s_cselect_b32 s24, s16, s8
	s_cselect_b32 s23, s11, s51
	s_cselect_b32 s22, s10, s50
	s_add_i32 s54, 0, 0x14000
	v_add_u32_e32 v114, s53, v249
	v_add_u32_e32 v150, s54, v249
	ds_read_b128 v[82:85], v114
	ds_read_b128 v[94:97], v114 offset:1024
	ds_read_b128 v[106:109], v114 offset:2048
	ds_read_b128 v[114:117], v114 offset:3072
	ds_read_b128 v[130:133], v150
	ds_read_b128 v[134:137], v150 offset:1024
	ds_read_b128 v[146:149], v150 offset:2048
	ds_read_b128 v[150:153], v150 offset:3072
	s_add_i32 m0, s36, 0xc000
	ds_read_b128 v[154:157], v251
	ds_read_b128 v[166:169], v251 offset:1024
	ds_read_b128 v[170:173], v251 offset:2048
	ds_read_b128 v[174:177], v251 offset:3072
	ds_read_b128 v[178:181], v251 offset:4096
	ds_read_b128 v[182:185], v251 offset:5120
	ds_read_b128 v[186:189], v251 offset:6144
	ds_read_b128 v[194:197], v251 offset:7168
	global_load_lds_dwordx4 v204, s[20:21]
	s_add_i32 m0, s36, 0xe000
	s_nop 0
	global_load_lds_dwordx4 v202, s[20:21]
	s_waitcnt vmcnt(32)
	s_waitcnt lgkmcnt(0)
	v_mfma_f32_16x16x32_bf16 v[162:165], v[82:85], v[154:157], v[162:165]
	v_mfma_f32_16x16x32_bf16 v[158:161], v[106:109], v[154:157], v[158:161]
	v_mfma_f32_16x16x32_bf16 v[126:129], v[82:85], v[170:173], v[126:129]
	v_mfma_f32_16x16x32_bf16 v[122:125], v[106:109], v[170:173], v[122:125]
	s_barrier
	s_waitcnt lgkmcnt(0)
	v_mfma_f32_16x16x32_bf16 v[102:105], v[82:85], v[178:181], v[102:105]
	v_mfma_f32_16x16x32_bf16 v[98:101], v[106:109], v[178:181], v[98:101]
	v_mfma_f32_16x16x32_bf16 v[78:81], v[82:85], v[186:189], v[78:81]
	v_mfma_f32_16x16x32_bf16 v[74:77], v[106:109], v[186:189], v[74:77]
	v_mfma_f32_16x16x32_bf16 v[162:165], v[94:97], v[166:169], v[162:165]
	v_mfma_f32_16x16x32_bf16 v[158:161], v[114:117], v[166:169], v[158:161]
	v_mfma_f32_16x16x32_bf16 v[126:129], v[94:97], v[174:177], v[126:129]
	v_mfma_f32_16x16x32_bf16 v[122:125], v[114:117], v[174:177], v[122:125]
	v_mfma_f32_16x16x32_bf16 v[102:105], v[94:97], v[182:185], v[102:105]
	v_mfma_f32_16x16x32_bf16 v[98:101], v[114:117], v[182:185], v[98:101]
	v_mfma_f32_16x16x32_bf16 v[78:81], v[94:97], v[194:197], v[78:81]
	v_mfma_f32_16x16x32_bf16 v[74:77], v[114:117], v[194:197], v[74:77]
	v_mfma_f32_16x16x32_bf16 v[142:145], v[130:133], v[154:157], v[142:145]
	v_mfma_f32_16x16x32_bf16 v[138:141], v[146:149], v[154:157], v[138:141]
	v_mfma_f32_16x16x32_bf16 v[118:121], v[130:133], v[170:173], v[118:121]
	v_mfma_f32_16x16x32_bf16 v[110:113], v[146:149], v[170:173], v[110:113]
	v_mfma_f32_16x16x32_bf16 v[90:93], v[130:133], v[178:181], v[90:93]
	v_mfma_f32_16x16x32_bf16 v[86:89], v[146:149], v[178:181], v[86:89]
	v_mfma_f32_16x16x32_bf16 v[70:73], v[130:133], v[186:189], v[70:73]
	v_mfma_f32_16x16x32_bf16 v[66:69], v[146:149], v[186:189], v[66:69]
	v_mfma_f32_16x16x32_bf16 v[142:145], v[134:137], v[166:169], v[142:145]
	v_mfma_f32_16x16x32_bf16 v[138:141], v[150:153], v[166:169], v[138:141]
	v_mfma_f32_16x16x32_bf16 v[118:121], v[134:137], v[174:177], v[118:121]
	v_mfma_f32_16x16x32_bf16 v[110:113], v[150:153], v[174:177], v[110:113]
	v_mfma_f32_16x16x32_bf16 v[90:93], v[134:137], v[182:185], v[90:93]
	v_mfma_f32_16x16x32_bf16 v[86:89], v[150:153], v[182:185], v[86:89]
	v_mfma_f32_16x16x32_bf16 v[70:73], v[134:137], v[194:197], v[70:73]
	v_mfma_f32_16x16x32_bf16 v[66:69], v[150:153], v[194:197], v[66:69]
	s_barrier
; #define PG8_STAGE(bufoff, gbase, voff) do { _Pragma("unroll") for (int _i = 0; _i < 2; ++_i) \
;         __builtin_amdgcn_global_load_lds((const unsigned*)((const char*)(gbase) + (voff)[_i]), (LAS unsigned*)(lds + (bufoff) + ldsw + _i * 8192), 16, 0, 0); } while (0)
; #define PG8_LDA(dst, b, h) do { _Pragma("unroll") for (int m = 0; m < 4; ++m) _Pragma("unroll") for (int k = 0; k < 2; ++k) dst[m][k] = *(const LAS bf16x8*)(lds + PG8_SA(b, h) + aoff + m * 2048 + k * 1024); } while (0)
; #define PG8_LDB(dst, b, h) do { _Pragma("unroll") for (int n = 0; n < 2; ++n) _Pragma("unroll") for (int k = 0; k < 2; ++k) dst[n][k] = *(const LAS bf16x8*)(lds + PG8_SB(b, h) + boff + n * 2048 + k * 1024); } while (0)
; #define PG8_MMA(ai, bj, At, Bt) do { __builtin_amdgcn_s_setprio(1); _Pragma("unroll") for (int m = 0; m < 4; ++m) _Pragma("unroll") for (int n = 0; n < 2; ++n) _Pragma("unroll") for (int k = 0; k < 2; ++k) \
;         acc[ai][bj][m][n] = __builtin_amdgcn_mfma_f32_16x16x32_bf16(Bt[n][k], At[m][k], acc[ai][bj][m][n], 0, 0, 0); __builtin_amdgcn_s_setprio(0); } while (0)
; #define PG8_WAIT_V(n) asm volatile("s_waitcnt vmcnt(" #n ")" ::: "memory")
; #define PG8_WAIT_L(n) asm volatile("s_waitcnt lgkmcnt(" #n ")" ::: "memory")
; #define PG8_BAR __builtin_amdgcn_s_barrier()
; #define PG8_SCHED __builtin_amdgcn_sched_barrier(0)
; template <class Epi, class Sched, int KC, bool ALIGN_EPI = false, bool SP2 = false, bool ATILED = false>
; __device__ __forceinline__ void gemm_phase(LAS unsigned char* lds, const Gemm g, const Sched& S, const Epi& E, int wave_s) {
;     ...
;             PG8_WAIT_V(8); PG8_WAIT_L(0); PG8_BAR; PG8_MMA(0, 0, At, B0); PG8_MMA(0, 1, At, B1); PG8_BAR; PG8_SCHED;
;             PG8_LDA(At, 0, 1); PG8_STAGE(PG8_SB(0, 0), b2, voffB); PG8_STAGE(PG8_SB(0, 1), b2 + hstepB, voffB); PG8_STAGE(PG8_SA(0, 0), a2, voffA);
;             PG8_WAIT_V(8); PG8_WAIT_L(0); PG8_BAR; PG8_MMA(1, 0, At, B0); PG8_MMA(1, 1, At, B1); PG8_BAR; PG8_SCHED;
;             PG8_LDB(B0, 1, 0); PG8_LDB(B1, 1, 1); PG8_SCHED; PG8_LDA(At, 1, 0); PG8_STAGE(PG8_SA(0, 1), a2 + hstepA, voffA);
;             PG8_WAIT_V(8); PG8_WAIT_L(0); PG8_BAR; PG8_MMA(0, 0, At, B0); PG8_MMA(0, 1, At, B1); PG8_BAR; PG8_SCHED;
	s_add_i32 s20, s53, s35
	s_mov_b32 m0, s20
	ds_read_b128 v[154:157], v251 offset:16384
	ds_read_b128 v[166:169], v251 offset:17408
	ds_read_b128 v[170:173], v251 offset:18432
	ds_read_b128 v[174:177], v251 offset:19456
	ds_read_b128 v[178:181], v251 offset:20480
	ds_read_b128 v[182:185], v251 offset:21504
	ds_read_b128 v[186:189], v251 offset:22528
	ds_read_b128 v[194:197], v251 offset:23552
	global_load_lds_dwordx4 v0, s[22:23]
	s_add_i32 m0, s20, 0x2000
	s_add_u32 s20, s22, 0x58000
	s_addc_u32 s21, s23, 0
	s_add_i32 s53, s54, s35
	global_load_lds_dwordx4 v198, s[22:23]
	s_mov_b32 m0, s53
	s_nop 0
	global_load_lds_dwordx4 v0, s[20:21]
	s_add_i32 m0, s53, 0x2000
	s_nop 0
	global_load_lds_dwordx4 v198, s[20:21]
	s_mov_b32 m0, s36
	s_nop 0
	global_load_lds_dwordx4 v190, s[24:25]
	s_mov_b32 m0, s37
	s_nop 0
	global_load_lds_dwordx4 v192, s[24:25]
	s_waitcnt vmcnt(32)
	s_waitcnt lgkmcnt(0)
	v_mfma_f32_16x16x32_bf16 v[62:65], v[82:85], v[154:157], v[62:65]
	v_mfma_f32_16x16x32_bf16 v[58:61], v[106:109], v[154:157], v[58:61]
	v_mfma_f32_16x16x32_bf16 v[46:49], v[82:85], v[170:173], v[46:49]
	v_mfma_f32_16x16x32_bf16 v[42:45], v[106:109], v[170:173], v[42:45]
	s_barrier
	s_waitcnt lgkmcnt(0)
	v_mfma_f32_16x16x32_bf16 v[30:33], v[82:85], v[178:181], v[30:33]
	v_mfma_f32_16x16x32_bf16 v[26:29], v[106:109], v[178:181], v[26:29]
	v_mfma_f32_16x16x32_bf16 v[14:17], v[82:85], v[186:189], v[14:17]
	v_mfma_f32_16x16x32_bf16 v[10:13], v[106:109], v[186:189], v[10:13]
	v_mfma_f32_16x16x32_bf16 v[62:65], v[94:97], v[166:169], v[62:65]
	v_mfma_f32_16x16x32_bf16 v[58:61], v[114:117], v[166:169], v[58:61]
	v_mfma_f32_16x16x32_bf16 v[46:49], v[94:97], v[174:177], v[46:49]
	v_mfma_f32_16x16x32_bf16 v[42:45], v[114:117], v[174:177], v[42:45]
	v_mfma_f32_16x16x32_bf16 v[30:33], v[94:97], v[182:185], v[30:33]
	v_mfma_f32_16x16x32_bf16 v[26:29], v[114:117], v[182:185], v[26:29]
	v_mfma_f32_16x16x32_bf16 v[14:17], v[94:97], v[194:197], v[14:17]
	v_mfma_f32_16x16x32_bf16 v[10:13], v[114:117], v[194:197], v[10:13]
	v_mfma_f32_16x16x32_bf16 v[54:57], v[130:133], v[154:157], v[54:57]
	v_mfma_f32_16x16x32_bf16 v[50:53], v[146:149], v[154:157], v[50:53]
	v_mfma_f32_16x16x32_bf16 v[38:41], v[130:133], v[170:173], v[38:41]
	v_mfma_f32_16x16x32_bf16 v[34:37], v[146:149], v[170:173], v[34:37]
	v_mfma_f32_16x16x32_bf16 v[22:25], v[130:133], v[178:181], v[22:25]
	v_mfma_f32_16x16x32_bf16 v[18:21], v[146:149], v[178:181], v[18:21]
	v_mfma_f32_16x16x32_bf16 v[6:9], v[130:133], v[186:189], v[6:9]
	v_mfma_f32_16x16x32_bf16 v[2:5], v[146:149], v[186:189], v[2:5]
	v_mfma_f32_16x16x32_bf16 v[54:57], v[134:137], v[166:169], v[54:57]
	v_mfma_f32_16x16x32_bf16 v[50:53], v[150:153], v[166:169], v[50:53]
	v_mfma_f32_16x16x32_bf16 v[38:41], v[134:137], v[174:177], v[38:41]
	v_mfma_f32_16x16x32_bf16 v[34:37], v[150:153], v[174:177], v[34:37]
	v_mfma_f32_16x16x32_bf16 v[22:25], v[134:137], v[182:185], v[22:25]
	v_mfma_f32_16x16x32_bf16 v[18:21], v[150:153], v[182:185], v[18:21]
	v_mfma_f32_16x16x32_bf16 v[6:9], v[134:137], v[194:197], v[6:9]
	v_mfma_f32_16x16x32_bf16 v[2:5], v[150:153], v[194:197], v[2:5]
	s_barrier
	s_add_i32 s53, 0, 0x18000
	s_add_i32 s54, 0, 0x1c000
	v_add_u32_e32 v114, s53, v249
	v_add_u32_e32 v150, s54, v249
	ds_read_b128 v[82:85], v114
	ds_read_b128 v[94:97], v114 offset:1024
	ds_read_b128 v[106:109], v114 offset:2048
	ds_read_b128 v[114:117], v114 offset:3072
	ds_read_b128 v[130:133], v150
	ds_read_b128 v[134:137], v150 offset:1024
	ds_read_b128 v[146:149], v150 offset:2048
	ds_read_b128 v[150:153], v150 offset:3072
	s_add_u32 s20, s24, 0x160000
	s_addc_u32 s21, s25, 0
	s_mov_b32 m0, s38
	ds_read_b128 v[154:157], v251 offset:32768
	ds_read_b128 v[166:169], v251 offset:33792
	ds_read_b128 v[170:173], v251 offset:34816
	ds_read_b128 v[174:177], v251 offset:35840
	ds_read_b128 v[178:181], v251 offset:36864
	ds_read_b128 v[182:185], v251 offset:37888
	ds_read_b128 v[186:189], v251 offset:38912
	ds_read_b128 v[194:197], v251 offset:39936
	global_load_lds_dwordx4 v190, s[20:21]
	s_mov_b32 m0, s39
	s_nop 0
	global_load_lds_dwordx4 v192, s[20:21]
	s_waitcnt vmcnt(8)
	s_waitcnt lgkmcnt(0)
	v_mfma_f32_16x16x32_bf16 v[162:165], v[82:85], v[154:157], v[162:165]
	v_mfma_f32_16x16x32_bf16 v[158:161], v[106:109], v[154:157], v[158:161]
	v_mfma_f32_16x16x32_bf16 v[126:129], v[82:85], v[170:173], v[126:129]
	v_mfma_f32_16x16x32_bf16 v[122:125], v[106:109], v[170:173], v[122:125]
	s_barrier
	s_waitcnt lgkmcnt(0)
	v_mfma_f32_16x16x32_bf16 v[102:105], v[82:85], v[178:181], v[102:105]
	v_mfma_f32_16x16x32_bf16 v[98:101], v[106:109], v[178:181], v[98:101]
	v_mfma_f32_16x16x32_bf16 v[78:81], v[82:85], v[186:189], v[78:81]
	v_mfma_f32_16x16x32_bf16 v[74:77], v[106:109], v[186:189], v[74:77]
	v_mfma_f32_16x16x32_bf16 v[162:165], v[94:97], v[166:169], v[162:165]
	v_mfma_f32_16x16x32_bf16 v[158:161], v[114:117], v[166:169], v[158:161]
	v_mfma_f32_16x16x32_bf16 v[126:129], v[94:97], v[174:177], v[126:129]
	v_mfma_f32_16x16x32_bf16 v[122:125], v[114:117], v[174:177], v[122:125]
	v_mfma_f32_16x16x32_bf16 v[102:105], v[94:97], v[182:185], v[102:105]
	v_mfma_f32_16x16x32_bf16 v[98:101], v[114:117], v[182:185], v[98:101]
	v_mfma_f32_16x16x32_bf16 v[78:81], v[94:97], v[194:197], v[78:81]
	v_mfma_f32_16x16x32_bf16 v[74:77], v[114:117], v[194:197], v[74:77]
	v_mfma_f32_16x16x32_bf16 v[142:145], v[130:133], v[154:157], v[142:145]
	v_mfma_f32_16x16x32_bf16 v[138:141], v[146:149], v[154:157], v[138:141]
	v_mfma_f32_16x16x32_bf16 v[118:121], v[130:133], v[170:173], v[118:121]
	v_mfma_f32_16x16x32_bf16 v[110:113], v[146:149], v[170:173], v[110:113]
	v_mfma_f32_16x16x32_bf16 v[90:93], v[130:133], v[178:181], v[90:93]
	v_mfma_f32_16x16x32_bf16 v[86:89], v[146:149], v[178:181], v[86:89]
	v_mfma_f32_16x16x32_bf16 v[70:73], v[130:133], v[186:189], v[70:73]
	v_mfma_f32_16x16x32_bf16 v[66:69], v[146:149], v[186:189], v[66:69]
	v_mfma_f32_16x16x32_bf16 v[142:145], v[134:137], v[166:169], v[142:145]
	v_mfma_f32_16x16x32_bf16 v[138:141], v[150:153], v[166:169], v[138:141]
	v_mfma_f32_16x16x32_bf16 v[118:121], v[134:137], v[174:177], v[118:121]
	v_mfma_f32_16x16x32_bf16 v[110:113], v[150:153], v[174:177], v[110:113]
	v_mfma_f32_16x16x32_bf16 v[90:93], v[134:137], v[182:185], v[90:93]
	v_mfma_f32_16x16x32_bf16 v[86:89], v[150:153], v[182:185], v[86:89]
	v_mfma_f32_16x16x32_bf16 v[70:73], v[134:137], v[194:197], v[70:73]
	v_mfma_f32_16x16x32_bf16 v[66:69], v[150:153], v[194:197], v[66:69]
	s_barrier
; #define PG8_STAGE(bufoff, gbase, voff) do { _Pragma("unroll") for (int _i = 0; _i < 2; ++_i) \
;         __builtin_amdgcn_global_load_lds((const unsigned*)((const char*)(gbase) + (voff)[_i]), (LAS unsigned*)(lds + (bufoff) + ldsw + _i * 8192), 16, 0, 0); } while (0)
; #define PG8_LDA(dst, b, h) do { _Pragma("unroll") for (int m = 0; m < 4; ++m) _Pragma("unroll") for (int k = 0; k < 2; ++k) dst[m][k] = *(const LAS bf16x8*)(lds + PG8_SA(b, h) + aoff + m * 2048 + k * 1024); } while (0)
; #define PG8_LDB(dst, b, h) do { _Pragma("unroll") for (int n = 0; n < 2; ++n) _Pragma("unroll") for (int k = 0; k < 2; ++k) dst[n][k] = *(const LAS bf16x8*)(lds + PG8_SB(b, h) + boff + n * 2048 + k * 1024); } while (0)
; #define PG8_MMA(ai, bj, At, Bt) do { __builtin_amdgcn_s_setprio(1); _Pragma("unroll") for (int m = 0; m < 4; ++m) _Pragma("unroll") for (int n = 0; n < 2; ++n) _Pragma("unroll") for (int k = 0; k < 2; ++k) \
;         acc[ai][bj][m][n] = __builtin_amdgcn_mfma_f32_16x16x32_bf16(Bt[n][k], At[m][k], acc[ai][bj][m][n], 0, 0, 0); __builtin_amdgcn_s_setprio(0); } while (0)
; template <class Epi, class Sched, int KC, bool ALIGN_EPI = false, bool SP2 = false, bool ATILED = false>
; __device__ __forceinline__ void gemm_phase(LAS unsigned char* lds, const Gemm g, const Sched& S, const Epi& E, int wave_s) {
;     ...
;             if constexpr (SP2) {
;             PG8_LDB(B0, 0, 0); PG8_LDB(B1, 0, 1); PG8_SCHED; PG8_LDA(At, 0, 0); PG8_STAGE(PG8_SA(1, 1), a1 + hstepA, voffA);
;             PG8_WAIT_V(8); PG8_WAIT_L(0); PG8_BAR; PG8_MMA(0, 0, At, B0); PG8_MMA(0, 1, At, B1); PG8_BAR; PG8_SCHED;
;             PG8_LDA(At, 0, 1); PG8_STAGE(PG8_SB(0, 0), b2, voffB); PG8_STAGE(PG8_SB(0, 1), b2 + hstepB, voffB); PG8_STAGE(PG8_SA(0, 0), a2, voffA);
;             PG8_WAIT_V(8); PG8_WAIT_L(0); PG8_BAR; PG8_MMA(1, 0, At, B0); PG8_MMA(1, 1, At, B1); PG8_BAR; PG8_SCHED;
;             PG8_LDB(B0, 1, 0); PG8_LDB(B1, 1, 1); PG8_SCHED; PG8_LDA(At, 1, 0); PG8_STAGE(PG8_SA(0, 1), a2 + hstepA, voffA);
;             PG8_WAIT_V(8); PG8_WAIT_L(0); PG8_BAR; PG8_MMA(0, 0, At, B0); PG8_MMA(0, 1, At, B1); PG8_BAR; PG8_SCHED;
;             PG8_LDA(At, 1, 1); PG8_STAGE(PG8_SB(1, 0), b3, voffB); PG8_STAGE(PG8_SB(1, 1), b3 + hstepB, voffB); PG8_STAGE(PG8_SA(1, 0), a3, voffA);
;             PG8_WAIT_V(8); PG8_WAIT_L(0); PG8_BAR; PG8_MMA(1, 0, At, B0); PG8_MMA(1, 1, At, B1); PG8_BAR; PG8_SCHED;
	s_add_u32 s98, s22, 0x80
	s_addc_u32 s99, s23, 0
	s_add_u32 s100, s24, 0x80
	s_addc_u32 s101, s25, 0
	s_add_i32 s20, s53, s35
	s_mov_b32 m0, s20
	ds_read_b128 v[154:157], v251 offset:49152
	ds_read_b128 v[166:169], v251 offset:50176
	ds_read_b128 v[170:173], v251 offset:51200
	ds_read_b128 v[174:177], v251 offset:52224
	ds_read_b128 v[178:181], v251 offset:53248
	ds_read_b128 v[182:185], v251 offset:54272
	ds_read_b128 v[186:189], v251 offset:55296
	ds_read_b128 v[194:197], v251 offset:56320
	global_load_lds_dwordx4 v0, s[98:99]
	s_add_i32 m0, s20, 0x2000
	s_add_u32 s20, s22, 0x58080
	s_addc_u32 s21, s23, 0
	s_add_i32 s22, s54, s35
	global_load_lds_dwordx4 v198, s[98:99]
	s_mov_b32 m0, s22
	s_nop 0
	global_load_lds_dwordx4 v0, s[20:21]
	s_add_i32 m0, s22, 0x2000
	s_nop 0
	global_load_lds_dwordx4 v198, s[20:21]
	s_mov_b32 m0, s43
	s_nop 0
	global_load_lds_dwordx4 v190, s[100:101]
	s_mov_b32 m0, s44
	s_nop 0
	global_load_lds_dwordx4 v192, s[100:101]
	s_waitcnt vmcnt(8)
	s_waitcnt lgkmcnt(0)
	v_mfma_f32_16x16x32_bf16 v[62:65], v[82:85], v[154:157], v[62:65]
	v_mfma_f32_16x16x32_bf16 v[58:61], v[106:109], v[154:157], v[58:61]
	v_mfma_f32_16x16x32_bf16 v[46:49], v[82:85], v[170:173], v[46:49]
	v_mfma_f32_16x16x32_bf16 v[42:45], v[106:109], v[170:173], v[42:45]
	s_barrier
	s_waitcnt lgkmcnt(0)
	v_mfma_f32_16x16x32_bf16 v[30:33], v[82:85], v[178:181], v[30:33]
	v_mfma_f32_16x16x32_bf16 v[26:29], v[106:109], v[178:181], v[26:29]
	v_mfma_f32_16x16x32_bf16 v[14:17], v[82:85], v[186:189], v[14:17]
	v_mfma_f32_16x16x32_bf16 v[10:13], v[106:109], v[186:189], v[10:13]
	v_mfma_f32_16x16x32_bf16 v[62:65], v[94:97], v[166:169], v[62:65]
	v_mfma_f32_16x16x32_bf16 v[58:61], v[114:117], v[166:169], v[58:61]
	v_mfma_f32_16x16x32_bf16 v[46:49], v[94:97], v[174:177], v[46:49]
	v_mfma_f32_16x16x32_bf16 v[42:45], v[114:117], v[174:177], v[42:45]
	v_mfma_f32_16x16x32_bf16 v[30:33], v[94:97], v[182:185], v[30:33]
	v_mfma_f32_16x16x32_bf16 v[26:29], v[114:117], v[182:185], v[26:29]
	v_mfma_f32_16x16x32_bf16 v[14:17], v[94:97], v[194:197], v[14:17]
	v_mfma_f32_16x16x32_bf16 v[10:13], v[114:117], v[194:197], v[10:13]
	v_mfma_f32_16x16x32_bf16 v[54:57], v[130:133], v[154:157], v[54:57]
	v_mfma_f32_16x16x32_bf16 v[50:53], v[146:149], v[154:157], v[50:53]
	v_mfma_f32_16x16x32_bf16 v[38:41], v[130:133], v[170:173], v[38:41]
	v_mfma_f32_16x16x32_bf16 v[34:37], v[146:149], v[170:173], v[34:37]
	v_mfma_f32_16x16x32_bf16 v[22:25], v[130:133], v[178:181], v[22:25]
	v_mfma_f32_16x16x32_bf16 v[18:21], v[146:149], v[178:181], v[18:21]
	v_mfma_f32_16x16x32_bf16 v[6:9], v[130:133], v[186:189], v[6:9]
	v_mfma_f32_16x16x32_bf16 v[2:5], v[146:149], v[186:189], v[2:5]
	v_mfma_f32_16x16x32_bf16 v[54:57], v[134:137], v[166:169], v[54:57]
	v_mfma_f32_16x16x32_bf16 v[50:53], v[150:153], v[166:169], v[50:53]
	v_mfma_f32_16x16x32_bf16 v[38:41], v[134:137], v[174:177], v[38:41]
	v_mfma_f32_16x16x32_bf16 v[34:37], v[150:153], v[174:177], v[34:37]
	v_mfma_f32_16x16x32_bf16 v[22:25], v[134:137], v[182:185], v[22:25]
	v_mfma_f32_16x16x32_bf16 v[18:21], v[150:153], v[182:185], v[18:21]
	v_mfma_f32_16x16x32_bf16 v[6:9], v[134:137], v[194:197], v[6:9]
	v_mfma_f32_16x16x32_bf16 v[2:5], v[150:153], v[194:197], v[2:5]
	s_barrier
	s_add_i32 s52, s52, 2
	s_add_u32 s50, s50, 0x100
	s_addc_u32 s51, s51, 0
	s_cmpk_gt_u32 s52, 0x55
	s_mov_b64 s[20:21], s[8:9]
.LBB0_318:
	s_add_u32 s8, s20, 0x100
	s_addc_u32 s9, s21, 0
	s_add_i32 s53, 0, 0x10000
	s_cmpk_eq_i32 s52, 0x54
	s_cselect_b32 s25, s17, s9
	s_cselect_b32 s24, s16, s8
	s_cselect_b32 s23, s11, s51
	s_cselect_b32 s22, s10, s50
	s_add_i32 s54, 0, 0x14000
	v_add_u32_e32 v114, s53, v249
	v_add_u32_e32 v150, s54, v249
	ds_read_b128 v[82:85], v114
	ds_read_b128 v[94:97], v114 offset:1024
	ds_read_b128 v[106:109], v114 offset:2048
	ds_read_b128 v[114:117], v114 offset:3072
	ds_read_b128 v[130:133], v150
	ds_read_b128 v[134:137], v150 offset:1024
	ds_read_b128 v[146:149], v150 offset:2048
	ds_read_b128 v[150:153], v150 offset:3072
	s_add_i32 m0, s36, 0xc000
	ds_read_b128 v[154:157], v251
	ds_read_b128 v[166:169], v251 offset:1024
	ds_read_b128 v[170:173], v251 offset:2048
	ds_read_b128 v[174:177], v251 offset:3072
	ds_read_b128 v[178:181], v251 offset:4096
	ds_read_b128 v[182:185], v251 offset:5120
	ds_read_b128 v[186:189], v251 offset:6144
	ds_read_b128 v[194:197], v251 offset:7168
	global_load_lds_dwordx4 v204, s[20:21]
	s_add_i32 m0, s36, 0xe000
	s_nop 0
	global_load_lds_dwordx4 v202, s[20:21]
	s_waitcnt vmcnt(8)
	s_waitcnt lgkmcnt(0)
	v_mfma_f32_16x16x32_bf16 v[162:165], v[82:85], v[154:157], v[162:165]
	v_mfma_f32_16x16x32_bf16 v[158:161], v[106:109], v[154:157], v[158:161]
	v_mfma_f32_16x16x32_bf16 v[126:129], v[82:85], v[170:173], v[126:129]
	v_mfma_f32_16x16x32_bf16 v[122:125], v[106:109], v[170:173], v[122:125]
	s_barrier
; #define PG8_STAGE(bufoff, gbase, voff) do { _Pragma("unroll") for (int _i = 0; _i < 2; ++_i) \
;         __builtin_amdgcn_global_load_lds((const unsigned*)((const char*)(gbase) + (voff)[_i]), (LAS unsigned*)(lds + (bufoff) + ldsw + _i * 8192), 16, 0, 0); } while (0)
; #define PG8_LDA(dst, b, h) do { _Pragma("unroll") for (int m = 0; m < 4; ++m) _Pragma("unroll") for (int k = 0; k < 2; ++k) dst[m][k] = *(const LAS bf16x8*)(lds + PG8_SA(b, h) + aoff + m * 2048 + k * 1024); } while (0)
; #define PG8_LDB(dst, b, h) do { _Pragma("unroll") for (int n = 0; n < 2; ++n) _Pragma("unroll") for (int k = 0; k < 2; ++k) dst[n][k] = *(const LAS bf16x8*)(lds + PG8_SB(b, h) + boff + n * 2048 + k * 1024); } while (0)
; #define PG8_MMA(ai, bj, At, Bt) do { __builtin_amdgcn_s_setprio(1); _Pragma("unroll") for (int m = 0; m < 4; ++m) _Pragma("unroll") for (int n = 0; n < 2; ++n) _Pragma("unroll") for (int k = 0; k < 2; ++k) \
;         acc[ai][bj][m][n] = __builtin_amdgcn_mfma_f32_16x16x32_bf16(Bt[n][k], At[m][k], acc[ai][bj][m][n], 0, 0, 0); __builtin_amdgcn_s_setprio(0); } while (0)
; #define PG8_WAIT_V(n) asm volatile("s_waitcnt vmcnt(" #n ")" ::: "memory")
; #define PG8_WAIT_L(n) asm volatile("s_waitcnt lgkmcnt(" #n ")" ::: "memory")
; #define PG8_BAR __builtin_amdgcn_s_barrier()
; #define PG8_SCHED __builtin_amdgcn_sched_barrier(0)
; template <class Epi, class Sched, int KC, bool ALIGN_EPI = false, bool SP2 = false, bool ATILED = false>
; __device__ __forceinline__ void gemm_phase(LAS unsigned char* lds, const Gemm g, const Sched& S, const Epi& E, int wave_s) {
;     ...
;             PG8_WAIT_V(8); PG8_WAIT_L(0); PG8_BAR; PG8_MMA(0, 0, At, B0); PG8_MMA(0, 1, At, B1); PG8_BAR; PG8_SCHED;
;             PG8_LDA(At, 0, 1); PG8_STAGE(PG8_SB(0, 0), b2, voffB); PG8_STAGE(PG8_SB(0, 1), b2 + hstepB, voffB); PG8_STAGE(PG8_SA(0, 0), a2, voffA);
;             PG8_WAIT_V(8); PG8_WAIT_L(0); PG8_BAR; PG8_MMA(1, 0, At, B0); PG8_MMA(1, 1, At, B1); PG8_BAR; PG8_SCHED;
;             PG8_LDB(B0, 1, 0); PG8_LDB(B1, 1, 1); PG8_SCHED; PG8_LDA(At, 1, 0); PG8_STAGE(PG8_SA(0, 1), a2 + hstepA, voffA);
	s_waitcnt lgkmcnt(0)
	v_mfma_f32_16x16x32_bf16 v[102:105], v[82:85], v[178:181], v[102:105]
	v_mfma_f32_16x16x32_bf16 v[98:101], v[106:109], v[178:181], v[98:101]
	v_mfma_f32_16x16x32_bf16 v[78:81], v[82:85], v[186:189], v[78:81]
	v_mfma_f32_16x16x32_bf16 v[74:77], v[106:109], v[186:189], v[74:77]
	v_mfma_f32_16x16x32_bf16 v[162:165], v[94:97], v[166:169], v[162:165]
	v_mfma_f32_16x16x32_bf16 v[158:161], v[114:117], v[166:169], v[158:161]
	v_mfma_f32_16x16x32_bf16 v[126:129], v[94:97], v[174:177], v[126:129]
	v_mfma_f32_16x16x32_bf16 v[122:125], v[114:117], v[174:177], v[122:125]
	v_mfma_f32_16x16x32_bf16 v[102:105], v[94:97], v[182:185], v[102:105]
	v_mfma_f32_16x16x32_bf16 v[98:101], v[114:117], v[182:185], v[98:101]
	v_mfma_f32_16x16x32_bf16 v[78:81], v[94:97], v[194:197], v[78:81]
	v_mfma_f32_16x16x32_bf16 v[74:77], v[114:117], v[194:197], v[74:77]
	v_mfma_f32_16x16x32_bf16 v[142:145], v[130:133], v[154:157], v[142:145]
	v_mfma_f32_16x16x32_bf16 v[138:141], v[146:149], v[154:157], v[138:141]
	v_mfma_f32_16x16x32_bf16 v[118:121], v[130:133], v[170:173], v[118:121]
	v_mfma_f32_16x16x32_bf16 v[110:113], v[146:149], v[170:173], v[110:113]
	v_mfma_f32_16x16x32_bf16 v[90:93], v[130:133], v[178:181], v[90:93]
	v_mfma_f32_16x16x32_bf16 v[86:89], v[146:149], v[178:181], v[86:89]
	v_mfma_f32_16x16x32_bf16 v[70:73], v[130:133], v[186:189], v[70:73]
	v_mfma_f32_16x16x32_bf16 v[66:69], v[146:149], v[186:189], v[66:69]
	v_mfma_f32_16x16x32_bf16 v[142:145], v[134:137], v[166:169], v[142:145]
	v_mfma_f32_16x16x32_bf16 v[138:141], v[150:153], v[166:169], v[138:141]
	v_mfma_f32_16x16x32_bf16 v[118:121], v[134:137], v[174:177], v[118:121]
	v_mfma_f32_16x16x32_bf16 v[110:113], v[150:153], v[174:177], v[110:113]
	v_mfma_f32_16x16x32_bf16 v[90:93], v[134:137], v[182:185], v[90:93]
	v_mfma_f32_16x16x32_bf16 v[86:89], v[150:153], v[182:185], v[86:89]
	v_mfma_f32_16x16x32_bf16 v[70:73], v[134:137], v[194:197], v[70:73]
	v_mfma_f32_16x16x32_bf16 v[66:69], v[150:153], v[194:197], v[66:69]
	s_barrier
	s_add_i32 s20, s53, s35
	s_mov_b32 m0, s20
	ds_read_b128 v[154:157], v251 offset:16384
	ds_read_b128 v[166:169], v251 offset:17408
	ds_read_b128 v[170:173], v251 offset:18432
	ds_read_b128 v[174:177], v251 offset:19456
	ds_read_b128 v[178:181], v251 offset:20480
	ds_read_b128 v[182:185], v251 offset:21504
	ds_read_b128 v[186:189], v251 offset:22528
	ds_read_b128 v[194:197], v251 offset:23552
	global_load_lds_dwordx4 v0, s[22:23]
	s_add_i32 m0, s20, 0x2000
	s_add_u32 s20, s22, 0x58000
	s_addc_u32 s21, s23, 0
	s_add_i32 s53, s54, s35
	global_load_lds_dwordx4 v198, s[22:23]
	s_mov_b32 m0, s53
	s_nop 0
	global_load_lds_dwordx4 v0, s[20:21]
	s_add_i32 m0, s53, 0x2000
	s_nop 0
	global_load_lds_dwordx4 v198, s[20:21]
	s_mov_b32 m0, s36
	s_nop 0
	global_load_lds_dwordx4 v190, s[24:25]
	s_mov_b32 m0, s37
	s_nop 0
	global_load_lds_dwordx4 v192, s[24:25]
	s_waitcnt vmcnt(8)
	s_waitcnt lgkmcnt(0)
	v_mfma_f32_16x16x32_bf16 v[62:65], v[82:85], v[154:157], v[62:65]
	v_mfma_f32_16x16x32_bf16 v[58:61], v[106:109], v[154:157], v[58:61]
	v_mfma_f32_16x16x32_bf16 v[46:49], v[82:85], v[170:173], v[46:49]
	v_mfma_f32_16x16x32_bf16 v[42:45], v[106:109], v[170:173], v[42:45]
	s_barrier
	s_waitcnt lgkmcnt(0)
	v_mfma_f32_16x16x32_bf16 v[30:33], v[82:85], v[178:181], v[30:33]
	v_mfma_f32_16x16x32_bf16 v[26:29], v[106:109], v[178:181], v[26:29]
	v_mfma_f32_16x16x32_bf16 v[14:17], v[82:85], v[186:189], v[14:17]
	v_mfma_f32_16x16x32_bf16 v[10:13], v[106:109], v[186:189], v[10:13]
	v_mfma_f32_16x16x32_bf16 v[62:65], v[94:97], v[166:169], v[62:65]
	v_mfma_f32_16x16x32_bf16 v[58:61], v[114:117], v[166:169], v[58:61]
	v_mfma_f32_16x16x32_bf16 v[46:49], v[94:97], v[174:177], v[46:49]
	v_mfma_f32_16x16x32_bf16 v[42:45], v[114:117], v[174:177], v[42:45]
	v_mfma_f32_16x16x32_bf16 v[30:33], v[94:97], v[182:185], v[30:33]
	v_mfma_f32_16x16x32_bf16 v[26:29], v[114:117], v[182:185], v[26:29]
	v_mfma_f32_16x16x32_bf16 v[14:17], v[94:97], v[194:197], v[14:17]
	v_mfma_f32_16x16x32_bf16 v[10:13], v[114:117], v[194:197], v[10:13]
	v_mfma_f32_16x16x32_bf16 v[54:57], v[130:133], v[154:157], v[54:57]
	v_mfma_f32_16x16x32_bf16 v[50:53], v[146:149], v[154:157], v[50:53]
	v_mfma_f32_16x16x32_bf16 v[38:41], v[130:133], v[170:173], v[38:41]
	v_mfma_f32_16x16x32_bf16 v[34:37], v[146:149], v[170:173], v[34:37]
	v_mfma_f32_16x16x32_bf16 v[22:25], v[130:133], v[178:181], v[22:25]
	v_mfma_f32_16x16x32_bf16 v[18:21], v[146:149], v[178:181], v[18:21]
	v_mfma_f32_16x16x32_bf16 v[6:9], v[130:133], v[186:189], v[6:9]
	v_mfma_f32_16x16x32_bf16 v[2:5], v[146:149], v[186:189], v[2:5]
	v_mfma_f32_16x16x32_bf16 v[54:57], v[134:137], v[166:169], v[54:57]
	v_mfma_f32_16x16x32_bf16 v[50:53], v[150:153], v[166:169], v[50:53]
	v_mfma_f32_16x16x32_bf16 v[38:41], v[134:137], v[174:177], v[38:41]
	v_mfma_f32_16x16x32_bf16 v[34:37], v[150:153], v[174:177], v[34:37]
	v_mfma_f32_16x16x32_bf16 v[22:25], v[134:137], v[182:185], v[22:25]
	v_mfma_f32_16x16x32_bf16 v[18:21], v[150:153], v[182:185], v[18:21]
	v_mfma_f32_16x16x32_bf16 v[6:9], v[134:137], v[194:197], v[6:9]
	v_mfma_f32_16x16x32_bf16 v[2:5], v[150:153], v[194:197], v[2:5]
	s_barrier
; #define PG8_STAGE(bufoff, gbase, voff) do { _Pragma("unroll") for (int _i = 0; _i < 2; ++_i) \
;         __builtin_amdgcn_global_load_lds((const unsigned*)((const char*)(gbase) + (voff)[_i]), (LAS unsigned*)(lds + (bufoff) + ldsw + _i * 8192), 16, 0, 0); } while (0)
; #define PG8_LDA(dst, b, h) do { _Pragma("unroll") for (int m = 0; m < 4; ++m) _Pragma("unroll") for (int k = 0; k < 2; ++k) dst[m][k] = *(const LAS bf16x8*)(lds + PG8_SA(b, h) + aoff + m * 2048 + k * 1024); } while (0)
; #define PG8_LDB(dst, b, h) do { _Pragma("unroll") for (int n = 0; n < 2; ++n) _Pragma("unroll") for (int k = 0; k < 2; ++k) dst[n][k] = *(const LAS bf16x8*)(lds + PG8_SB(b, h) + boff + n * 2048 + k * 1024); } while (0)
; #define PG8_MMA(ai, bj, At, Bt) do { __builtin_amdgcn_s_setprio(1); _Pragma("unroll") for (int m = 0; m < 4; ++m) _Pragma("unroll") for (int n = 0; n < 2; ++n) _Pragma("unroll") for (int k = 0; k < 2; ++k) \
;         acc[ai][bj][m][n] = __builtin_amdgcn_mfma_f32_16x16x32_bf16(Bt[n][k], At[m][k], acc[ai][bj][m][n], 0, 0, 0); __builtin_amdgcn_s_setprio(0); } while (0)
; #define PG8_WAIT_V(n) asm volatile("s_waitcnt vmcnt(" #n ")" ::: "memory")
; #define PG8_WAIT_L(n) asm volatile("s_waitcnt lgkmcnt(" #n ")" ::: "memory")
; #define PG8_BAR __builtin_amdgcn_s_barrier()
; #define PG8_SCHED __builtin_amdgcn_sched_barrier(0)
; template <class Epi, class Sched, int KC, bool ALIGN_EPI = false, bool SP2 = false, bool ATILED = false>
; __device__ __forceinline__ void gemm_phase(LAS unsigned char* lds, const Gemm g, const Sched& S, const Epi& E, int wave_s) {
;     ...
;             PG8_LDB(B0, 1, 0); PG8_LDB(B1, 1, 1); PG8_SCHED; PG8_LDA(At, 1, 0); PG8_STAGE(PG8_SA(0, 1), a2 + hstepA, voffA);
;             PG8_WAIT_V(8); PG8_WAIT_L(0); PG8_BAR; PG8_MMA(0, 0, At, B0); PG8_MMA(0, 1, At, B1); PG8_BAR; PG8_SCHED;
;             PG8_LDA(At, 1, 1); PG8_STAGE(PG8_SB(1, 0), b3, voffB); PG8_STAGE(PG8_SB(1, 1), b3 + hstepB, voffB); PG8_STAGE(PG8_SA(1, 0), a3, voffA);
;             PG8_WAIT_V(8); PG8_WAIT_L(0); PG8_BAR; PG8_MMA(1, 0, At, B0); PG8_MMA(1, 1, At, B1); PG8_BAR; PG8_SCHED;
	s_add_i32 s53, 0, 0x18000
	s_add_i32 s54, 0, 0x1c000
	v_add_u32_e32 v114, s53, v249
	v_add_u32_e32 v150, s54, v249
	ds_read_b128 v[82:85], v114
	ds_read_b128 v[94:97], v114 offset:1024
	ds_read_b128 v[106:109], v114 offset:2048
	ds_read_b128 v[114:117], v114 offset:3072
	ds_read_b128 v[130:133], v150
	ds_read_b128 v[134:137], v150 offset:1024
	ds_read_b128 v[146:149], v150 offset:2048
	ds_read_b128 v[150:153], v150 offset:3072
	s_add_u32 s20, s24, 0x160000
	s_addc_u32 s21, s25, 0
	s_mov_b32 m0, s38
	ds_read_b128 v[154:157], v251 offset:32768
	ds_read_b128 v[166:169], v251 offset:33792
	ds_read_b128 v[170:173], v251 offset:34816
	ds_read_b128 v[174:177], v251 offset:35840
	ds_read_b128 v[178:181], v251 offset:36864
	ds_read_b128 v[182:185], v251 offset:37888
	ds_read_b128 v[186:189], v251 offset:38912
	ds_read_b128 v[194:197], v251 offset:39936
	global_load_lds_dwordx4 v190, s[20:21]
	s_mov_b32 m0, s39
	s_nop 0
	global_load_lds_dwordx4 v192, s[20:21]
	s_waitcnt vmcnt(8)
	s_waitcnt lgkmcnt(0)
	v_mfma_f32_16x16x32_bf16 v[162:165], v[82:85], v[154:157], v[162:165]
	v_mfma_f32_16x16x32_bf16 v[158:161], v[106:109], v[154:157], v[158:161]
	v_mfma_f32_16x16x32_bf16 v[126:129], v[82:85], v[170:173], v[126:129]
	v_mfma_f32_16x16x32_bf16 v[122:125], v[106:109], v[170:173], v[122:125]
	s_barrier
	s_waitcnt lgkmcnt(0)
	v_mfma_f32_16x16x32_bf16 v[102:105], v[82:85], v[178:181], v[102:105]
	v_mfma_f32_16x16x32_bf16 v[98:101], v[106:109], v[178:181], v[98:101]
	v_mfma_f32_16x16x32_bf16 v[78:81], v[82:85], v[186:189], v[78:81]
	v_mfma_f32_16x16x32_bf16 v[74:77], v[106:109], v[186:189], v[74:77]
	v_mfma_f32_16x16x32_bf16 v[162:165], v[94:97], v[166:169], v[162:165]
	v_mfma_f32_16x16x32_bf16 v[158:161], v[114:117], v[166:169], v[158:161]
	v_mfma_f32_16x16x32_bf16 v[126:129], v[94:97], v[174:177], v[126:129]
	v_mfma_f32_16x16x32_bf16 v[122:125], v[114:117], v[174:177], v[122:125]
	v_mfma_f32_16x16x32_bf16 v[102:105], v[94:97], v[182:185], v[102:105]
	v_mfma_f32_16x16x32_bf16 v[98:101], v[114:117], v[182:185], v[98:101]
	v_mfma_f32_16x16x32_bf16 v[78:81], v[94:97], v[194:197], v[78:81]
	v_mfma_f32_16x16x32_bf16 v[74:77], v[114:117], v[194:197], v[74:77]
	v_mfma_f32_16x16x32_bf16 v[142:145], v[130:133], v[154:157], v[142:145]
	v_mfma_f32_16x16x32_bf16 v[138:141], v[146:149], v[154:157], v[138:141]
	v_mfma_f32_16x16x32_bf16 v[118:121], v[130:133], v[170:173], v[118:121]
	v_mfma_f32_16x16x32_bf16 v[110:113], v[146:149], v[170:173], v[110:113]
	v_mfma_f32_16x16x32_bf16 v[90:93], v[130:133], v[178:181], v[90:93]
	v_mfma_f32_16x16x32_bf16 v[86:89], v[146:149], v[178:181], v[86:89]
	v_mfma_f32_16x16x32_bf16 v[70:73], v[130:133], v[186:189], v[70:73]
	v_mfma_f32_16x16x32_bf16 v[66:69], v[146:149], v[186:189], v[66:69]
	v_mfma_f32_16x16x32_bf16 v[142:145], v[134:137], v[166:169], v[142:145]
	v_mfma_f32_16x16x32_bf16 v[138:141], v[150:153], v[166:169], v[138:141]
	v_mfma_f32_16x16x32_bf16 v[118:121], v[134:137], v[174:177], v[118:121]
	v_mfma_f32_16x16x32_bf16 v[110:113], v[150:153], v[174:177], v[110:113]
	v_mfma_f32_16x16x32_bf16 v[90:93], v[134:137], v[182:185], v[90:93]
	v_mfma_f32_16x16x32_bf16 v[86:89], v[150:153], v[182:185], v[86:89]
	v_mfma_f32_16x16x32_bf16 v[70:73], v[134:137], v[194:197], v[70:73]
	v_mfma_f32_16x16x32_bf16 v[66:69], v[150:153], v[194:197], v[66:69]
	s_barrier
	s_add_u32 s98, s22, 0x80
	s_addc_u32 s99, s23, 0
	s_add_u32 s100, s24, 0x80
	s_addc_u32 s101, s25, 0
	s_add_i32 s20, s53, s35
	s_mov_b32 m0, s20
	ds_read_b128 v[154:157], v251 offset:49152
	ds_read_b128 v[166:169], v251 offset:50176
	ds_read_b128 v[170:173], v251 offset:51200
	ds_read_b128 v[174:177], v251 offset:52224
	ds_read_b128 v[178:181], v251 offset:53248
	ds_read_b128 v[182:185], v251 offset:54272
	ds_read_b128 v[186:189], v251 offset:55296
	ds_read_b128 v[194:197], v251 offset:56320
	global_load_lds_dwordx4 v0, s[98:99]
	s_add_i32 m0, s20, 0x2000
	s_add_u32 s20, s22, 0x58080
	s_addc_u32 s21, s23, 0
	s_add_i32 s22, s54, s35
	global_load_lds_dwordx4 v198, s[98:99]
	s_mov_b32 m0, s22
	s_nop 0
	global_load_lds_dwordx4 v0, s[20:21]
	s_add_i32 m0, s22, 0x2000
	s_nop 0
	global_load_lds_dwordx4 v198, s[20:21]
	s_mov_b32 m0, s43
	s_nop 0
	global_load_lds_dwordx4 v190, s[100:101]
	s_mov_b32 m0, s44
	s_nop 0
	global_load_lds_dwordx4 v192, s[100:101]
	s_waitcnt vmcnt(8)
	s_waitcnt lgkmcnt(0)
	v_mfma_f32_16x16x32_bf16 v[62:65], v[82:85], v[154:157], v[62:65]
	v_mfma_f32_16x16x32_bf16 v[58:61], v[106:109], v[154:157], v[58:61]
	v_mfma_f32_16x16x32_bf16 v[46:49], v[82:85], v[170:173], v[46:49]
	v_mfma_f32_16x16x32_bf16 v[42:45], v[106:109], v[170:173], v[42:45]
	s_barrier
; #define GAS __attribute__((address_space(1)))
;     DI void operator()(const f32x4 (&acc)[2][2][4][2], const Unit& u, int wr, int wc, int fr, int fq) const {
;         const int row0 = u.pm * BM + wr * 64 + fr, col0 = u.pn * BM + wc * 64 + 8 * fq;
;         const size_t hbase = (size_t)u.pn * ((size_t)M * 256) + wc * 64 + 8 * fq;
;         u32x4 H[2][4][2];
; #pragma unroll
;         for (int ai = 0; ai < 2; ++ai)
; #pragma unroll
;             for (int m = 0; m < 4; ++m)
; #pragma unroll
;                 for (int bj = 0; bj < 2; ++bj) H[ai][m][bj] = *(const GAS u32x4*)(hi + hbase + (size_t)(row0 + ai * HALF + m * 16) * 256 + bj * 32);
;         asm volatile("" ::: "memory");
; #pragma unroll
;         for (int ai = 0; ai < 2; ++ai) {
; #pragma unroll
;             for (int m = 0; m < 4; ++m) {
;                 const int r = row0 + ai * HALF + m * 16; const size_t off = (size_t)r * DM + col0; float ss = 0.f;
; #pragma unroll
;                 for (int bj = 0; bj < 2; ++bj) {
;                     const u32x4 h = H[ai][m][bj];
;                     const f32x4 a0 = acc[ai][bj][m][0], a1 = acc[ai][bj][m][1];
;                     float v[8];
;                     v[0] = bflo(h.x) + a0[0] * scale; v[1] = bfhi(h.x) + a0[1] * scale;
;                     v[2] = bflo(h.y) + a0[2] * scale; v[3] = bfhi(h.y) + a0[3] * scale;
;                     v[4] = bflo(h.z) + a1[0] * scale; v[5] = bfhi(h.z) + a1[1] * scale;
;                     v[6] = bflo(h.w) + a1[2] * scale; v[7] = bfhi(h.w) + a1[3] * scale;
; #pragma unroll
;                     for (int e = 0; e < 8; ++e) ss += v[e] * v[e];
;                     u32x4 nh;
;                     nh.x = cvtpk(v[0], v[1]); nh.y = cvtpk(v[2], v[3]); nh.z = cvtpk(v[4], v[5]); nh.w = cvtpk(v[6], v[7]);
; template <class Epi, class Sched, int KC, bool ALIGN_EPI = false, bool SP2 = false, bool ATILED = false>
; __device__ __forceinline__ void gemm_phase(LAS unsigned char* lds, const Gemm g, const Sched& S, const Epi& E, int wave_s) {
;     ...
;             PG8_WAIT_V(8); PG8_WAIT_L(0); PG8_BAR; PG8_MMA(0, 0, At, B0); PG8_MMA(0, 1, At, B1); PG8_BAR; PG8_SCHED;
;             PG8_LDA(At, 1, 1); PG8_STAGE(PG8_SB(1, 0), b3, voffB); PG8_STAGE(PG8_SB(1, 1), b3 + hstepB, voffB); PG8_STAGE(PG8_SA(1, 0), a3, voffA);
;             PG8_WAIT_V(8); PG8_WAIT_L(0); PG8_BAR; PG8_MMA(1, 0, At, B0); PG8_MMA(1, 1, At, B1); PG8_BAR; PG8_SCHED;
	s_waitcnt lgkmcnt(0)
	v_mfma_f32_16x16x32_bf16 v[30:33], v[82:85], v[178:181], v[30:33]
	v_mfma_f32_16x16x32_bf16 v[26:29], v[106:109], v[178:181], v[26:29]
	v_mfma_f32_16x16x32_bf16 v[14:17], v[82:85], v[186:189], v[14:17]
	v_mfma_f32_16x16x32_bf16 v[10:13], v[106:109], v[186:189], v[10:13]
	v_mfma_f32_16x16x32_bf16 v[62:65], v[94:97], v[166:169], v[62:65]
	v_mfma_f32_16x16x32_bf16 v[58:61], v[114:117], v[166:169], v[58:61]
	v_mfma_f32_16x16x32_bf16 v[46:49], v[94:97], v[174:177], v[46:49]
	v_mfma_f32_16x16x32_bf16 v[42:45], v[114:117], v[174:177], v[42:45]
	v_mfma_f32_16x16x32_bf16 v[30:33], v[94:97], v[182:185], v[30:33]
	v_mfma_f32_16x16x32_bf16 v[26:29], v[114:117], v[182:185], v[26:29]
	v_mfma_f32_16x16x32_bf16 v[14:17], v[94:97], v[194:197], v[14:17]
	v_mfma_f32_16x16x32_bf16 v[10:13], v[114:117], v[194:197], v[10:13]
	v_mfma_f32_16x16x32_bf16 v[54:57], v[130:133], v[154:157], v[54:57]
	v_mfma_f32_16x16x32_bf16 v[50:53], v[146:149], v[154:157], v[50:53]
	v_mfma_f32_16x16x32_bf16 v[38:41], v[130:133], v[170:173], v[38:41]
	v_mfma_f32_16x16x32_bf16 v[34:37], v[146:149], v[170:173], v[34:37]
	v_mfma_f32_16x16x32_bf16 v[22:25], v[130:133], v[178:181], v[22:25]
	v_mfma_f32_16x16x32_bf16 v[18:21], v[146:149], v[178:181], v[18:21]
	v_mfma_f32_16x16x32_bf16 v[6:9], v[130:133], v[186:189], v[6:9]
	v_mfma_f32_16x16x32_bf16 v[2:5], v[146:149], v[186:189], v[2:5]
	v_mfma_f32_16x16x32_bf16 v[54:57], v[134:137], v[166:169], v[54:57]
	v_mfma_f32_16x16x32_bf16 v[50:53], v[150:153], v[166:169], v[50:53]
	v_mfma_f32_16x16x32_bf16 v[38:41], v[134:137], v[174:177], v[38:41]
	v_mfma_f32_16x16x32_bf16 v[34:37], v[150:153], v[174:177], v[34:37]
	v_mfma_f32_16x16x32_bf16 v[22:25], v[134:137], v[182:185], v[22:25]
	v_mfma_f32_16x16x32_bf16 v[18:21], v[150:153], v[182:185], v[18:21]
	v_mfma_f32_16x16x32_bf16 v[6:9], v[134:137], v[194:197], v[6:9]
	v_mfma_f32_16x16x32_bf16 v[2:5], v[150:153], v[194:197], v[2:5]
	s_barrier
	s_add_i32 s52, s52, 2
	s_add_u32 s50, s50, 0x100
	s_addc_u32 s51, s51, 0
	s_cmpk_gt_u32 s52, 0x55
	s_mov_b64 s[20:21], s[8:9]
	s_cbranch_scc0 .LBB0_318
	v_lshl_add_u32 v206, s19, 8, v248
	s_ashr_i32 s19, s18, 31
	s_lshl_b64 s[8:9], s[18:19], 23
	v_ashrrev_i32_e32 v207, 31, v206
	v_or_b32_e32 v236, 16, v206
	v_lshl_add_u64 v[82:83], v[200:201], 0, s[8:9]
	v_lshlrev_b64 v[84:85], 9, v[206:207]
	v_ashrrev_i32_e32 v237, 31, v236
	v_or_b32_e32 v232, 32, v206
	v_lshl_add_u64 v[238:239], v[82:83], 0, v[84:85]
	v_lshlrev_b64 v[84:85], 9, v[236:237]
	v_ashrrev_i32_e32 v233, 31, v232
	v_or_b32_e32 v228, 48, v206
	v_lshl_add_u64 v[234:235], v[82:83], 0, v[84:85]
	v_lshlrev_b64 v[84:85], 9, v[232:233]
	v_ashrrev_i32_e32 v229, 31, v228
	v_add_u32_e32 v224, 0x80, v206
	v_lshl_add_u64 v[230:231], v[82:83], 0, v[84:85]
	v_lshlrev_b64 v[84:85], 9, v[228:229]
	v_ashrrev_i32_e32 v225, 31, v224
	v_add_u32_e32 v220, 0x90, v206
	global_load_dwordx4 v[194:197], v[238:239], off
	global_load_dwordx4 v[186:189], v[238:239], off offset:64
	v_lshl_add_u64 v[226:227], v[82:83], 0, v[84:85]
	v_lshlrev_b64 v[84:85], 9, v[224:225]
	v_ashrrev_i32_e32 v221, 31, v220
	v_add_u32_e32 v216, 0xa0, v206
	v_lshl_add_u64 v[222:223], v[82:83], 0, v[84:85]
	v_lshlrev_b64 v[84:85], 9, v[220:221]
	v_ashrrev_i32_e32 v217, 31, v216
	v_add_u32_e32 v210, 0xb0, v206
	v_lshl_add_u64 v[218:219], v[82:83], 0, v[84:85]
	v_lshlrev_b64 v[84:85], 9, v[216:217]
	v_ashrrev_i32_e32 v211, 31, v210
	v_lshl_add_u64 v[214:215], v[82:83], 0, v[84:85]
	v_lshlrev_b64 v[84:85], 9, v[210:211]
	v_lshl_add_u64 v[208:209], v[82:83], 0, v[84:85]
	global_load_dwordx4 v[182:185], v[234:235], off
	global_load_dwordx4 v[178:181], v[234:235], off offset:64
	global_load_dwordx4 v[174:177], v[230:231], off
	global_load_dwordx4 v[170:173], v[230:231], off offset:64
	global_load_dwordx4 v[166:169], v[226:227], off
	global_load_dwordx4 v[154:157], v[226:227], off offset:64
	global_load_dwordx4 v[150:153], v[222:223], off
	global_load_dwordx4 v[146:149], v[222:223], off offset:64
	global_load_dwordx4 v[134:137], v[218:219], off
	global_load_dwordx4 v[130:133], v[218:219], off offset:64
	global_load_dwordx4 v[114:117], v[214:215], off
	global_load_dwordx4 v[106:109], v[214:215], off offset:64
	global_load_dwordx4 v[94:97], v[208:209], off
	global_load_dwordx4 v[82:85], v[208:209], off offset:64
	v_lshl_or_b32 v212, s18, 8, v250
	v_ashrrev_i32_e32 v213, 31, v212
	v_lshlrev_b64 v[240:241], 11, v[206:207]
	v_lshl_add_u64 v[240:241], v[240:241], 0, v[212:213]
	s_andn2_b64 vcc, exec, s[14:15]
	v_lshl_add_u64 v[240:241], v[240:241], 2, s[12:13]
	s_waitcnt vmcnt(0)
	v_lshlrev_b32_e32 v252, 16, v194
	v_and_b32_e32 v253, 0xffff0000, v194
	v_lshlrev_b32_e32 v194, 16, v195
	v_and_b32_e32 v195, 0xffff0000, v195
	v_pk_fma_f32 v[164:165], v[164:165], 0.5, v[194:195] op_sel_hi:[1,0,1]
	v_lshlrev_b32_e32 v194, 16, v196
	v_and_b32_e32 v195, 0xffff0000, v196
	v_pk_fma_f32 v[158:159], v[158:159], 0.5, v[194:195] op_sel_hi:[1,0,1]
	v_lshlrev_b32_e32 v194, 16, v197
	v_and_b32_e32 v195, 0xffff0000, v197
	v_pk_fma_f32 v[162:163], v[162:163], 0.5, v[252:253] op_sel_hi:[1,0,1]
	v_pk_fma_f32 v[160:161], v[160:161], 0.5, v[194:195] op_sel_hi:[1,0,1]
	v_cvt_pk_bf16_f32 v194, v162, v163
	v_cvt_pk_bf16_f32 v195, v164, v165
	v_cvt_pk_bf16_f32 v196, v158, v159
	s_nop 0
	v_cvt_pk_bf16_f32 v197, v160, v161
	global_store_dwordx4 v[238:239], v[194:197], off
	s_nop 1
	v_cndmask_b32_e64 v194, 0, 1, s[14:15]
	v_cmp_ne_u32_e64 s[8:9], 1, v194
	s_cbranch_vccnz .LBB0_321
	global_store_dwordx4 v[240:241], v[162:165], off
	global_store_dwordx4 v[240:241], v[158:161], off offset:16

; #define PG8_STAGE(bufoff, gbase, voff) do { _Pragma("unroll") for (int _i = 0; _i < 2; ++_i) \
;         __builtin_amdgcn_global_load_lds((const unsigned*)((const char*)(gbase) + (voff)[_i]), (LAS unsigned*)(lds + (bufoff) + ldsw + _i * 8192), 16, 0, 0); } while (0)
; #define PG8_LDA(dst, b, h) do { _Pragma("unroll") for (int m = 0; m < 4; ++m) _Pragma("unroll") for (int k = 0; k < 2; ++k) dst[m][k] = *(const LAS bf16x8*)(lds + PG8_SA(b, h) + aoff + m * 2048 + k * 1024); } while (0)
; #define PG8_LDB(dst, b, h) do { _Pragma("unroll") for (int n = 0; n < 2; ++n) _Pragma("unroll") for (int k = 0; k < 2; ++k) dst[n][k] = *(const LAS bf16x8*)(lds + PG8_SB(b, h) + boff + n * 2048 + k * 1024); } while (0)
; #define PG8_WAIT_V(n) asm volatile("s_waitcnt vmcnt(" #n ")" ::: "memory")
; #define PG8_WAIT_L(n) asm volatile("s_waitcnt lgkmcnt(" #n ")" ::: "memory")
; #define PG8_BAR __builtin_amdgcn_s_barrier()
; #define PG8_SCHED __builtin_amdgcn_sched_barrier(0)
; template <class Epi, class Sched, int KC, bool ALIGN_EPI = false, bool SP2 = false, bool ATILED = false>
; __device__ __forceinline__ void gemm_phase(LAS unsigned char* lds, const Gemm g, const Sched& S, const Epi& E, int wave_s) {
;     ...
;         const bool has_next = S.next(ui + 1, nxt);
;         const char* nA = has_next ? (const char*)g.A + (size_t)nxt.pm * tstepA : cA; const char* nB = has_next ? (const char*)g.Bt + (size_t)nxt.pn * tstep : cB;
;         for (int t = 0; t < nt; t += 2) {
;             const bool last = (t == nt - 2);
;             const char* a1 = cA + PG8_AOFF(t + 1);
;             const char* a2 = last ? nA : cA + PG8_AOFF(t + 2); const char* b2 = last ? nB : cB + (size_t)(t + 2) * kstep;
;             const char* a3 = a2 + kstep; const char* b3 = b2 + kstep;
;             if (last && has_next) S.a_ready(nxt);
;             if constexpr (SP2) {
;             PG8_LDB(B0, 0, 0); PG8_LDB(B1, 0, 1); PG8_SCHED; PG8_LDA(At, 0, 0); PG8_STAGE(PG8_SA(1, 1), a1 + hstepA, voffA);
;             PG8_WAIT_V(8); PG8_WAIT_L(0); PG8_BAR; PG8_MMA(0, 0, At, B0); PG8_MMA(0, 1, At, B1); PG8_BAR; PG8_SCHED;
;     ...
; #pragma unroll
;         for (int a = 0; a < 2; ++a)
; #pragma unroll
;             for (int b = 0; b < 2; ++b)
; #pragma unroll
;                 for (int m = 0; m < 4; ++m)
; #pragma unroll
;                     for (int n = 0; n < 2; ++n) acc[a][b][m][n] = (f32x4){0.f, 0.f, 0.f, 0.f};
.LBB0_429:
	s_ashr_i32 s19, s18, 31
	s_lshl_b64 s[20:21], s[18:19], 17
	s_add_u32 s20, s42, s20
	s_addc_u32 s21, s43, s21
	s_and_b64 s[22:23], s[6:7], exec
	s_cselect_b32 s19, s21, s27
	s_cselect_b32 s61, s20, s26
	s_ashr_i32 s17, s16, 31
	s_lshl_b64 s[22:23], s[16:17], 20
	s_add_u32 s22, s44, s22
	s_addc_u32 s23, s45, s23
	s_and_b64 s[30:31], s[6:7], exec
	s_cselect_b32 s17, s23, s29
	s_cselect_b32 s62, s22, s28
	s_add_u32 s63, s28, 0x100
	v_mov_b32_e32 v2, 0
	s_addc_u32 s64, s29, 0
	s_mov_b32 s65, -2
	s_mov_b64 s[28:29], 0
	s_mov_b32 s66, 0x400000
	v_mov_b32_e32 v3, v2
	v_mov_b32_e32 v4, v2
	v_mov_b32_e32 v5, v2
	v_mov_b32_e32 v6, v2
	v_mov_b32_e32 v7, v2
	v_mov_b32_e32 v8, v2
	v_mov_b32_e32 v9, v2
	v_mov_b32_e32 v14, v2
	v_mov_b32_e32 v15, v2
	v_mov_b32_e32 v16, v2
	v_mov_b32_e32 v17, v2
	v_mov_b32_e32 v22, v2
	v_mov_b32_e32 v23, v2
	v_mov_b32_e32 v24, v2
	v_mov_b32_e32 v25, v2
	v_mov_b32_e32 v30, v2
	v_mov_b32_e32 v31, v2
	v_mov_b32_e32 v32, v2
	v_mov_b32_e32 v33, v2
	v_mov_b32_e32 v38, v2
	v_mov_b32_e32 v39, v2
	v_mov_b32_e32 v40, v2
	v_mov_b32_e32 v41, v2
	v_mov_b32_e32 v46, v2
	v_mov_b32_e32 v47, v2
	v_mov_b32_e32 v48, v2
	v_mov_b32_e32 v49, v2
	v_mov_b32_e32 v54, v2
	v_mov_b32_e32 v55, v2
	v_mov_b32_e32 v56, v2
	v_mov_b32_e32 v57, v2
	v_mov_b32_e32 v10, v2
	v_mov_b32_e32 v11, v2
	v_mov_b32_e32 v12, v2
	v_mov_b32_e32 v13, v2
	v_mov_b32_e32 v18, v2
	v_mov_b32_e32 v19, v2
	v_mov_b32_e32 v20, v2
	v_mov_b32_e32 v21, v2
	v_mov_b32_e32 v26, v2
	v_mov_b32_e32 v27, v2
	v_mov_b32_e32 v28, v2
	v_mov_b32_e32 v29, v2
	v_mov_b32_e32 v34, v2
	v_mov_b32_e32 v35, v2
	v_mov_b32_e32 v36, v2
	v_mov_b32_e32 v37, v2
	v_mov_b32_e32 v42, v2
	v_mov_b32_e32 v43, v2
	v_mov_b32_e32 v44, v2
	v_mov_b32_e32 v45, v2
	v_mov_b32_e32 v50, v2
	v_mov_b32_e32 v51, v2
	v_mov_b32_e32 v52, v2
	v_mov_b32_e32 v53, v2
	v_mov_b32_e32 v58, v2
	v_mov_b32_e32 v59, v2
	v_mov_b32_e32 v60, v2
	v_mov_b32_e32 v61, v2
	v_mov_b32_e32 v62, v2
	v_mov_b32_e32 v63, v2
	v_mov_b32_e32 v64, v2
	v_mov_b32_e32 v65, v2
	v_mov_b32_e32 v66, v2
	v_mov_b32_e32 v67, v2
	v_mov_b32_e32 v68, v2
	v_mov_b32_e32 v69, v2
	v_mov_b32_e32 v70, v2
	v_mov_b32_e32 v71, v2
	v_mov_b32_e32 v72, v2
	v_mov_b32_e32 v73, v2
	v_mov_b32_e32 v78, v2
	v_mov_b32_e32 v79, v2
	v_mov_b32_e32 v80, v2
	v_mov_b32_e32 v81, v2
	v_mov_b32_e32 v86, v2
	v_mov_b32_e32 v87, v2
	v_mov_b32_e32 v88, v2
	v_mov_b32_e32 v89, v2
	v_mov_b32_e32 v94, v2
	v_mov_b32_e32 v95, v2
	v_mov_b32_e32 v96, v2
	v_mov_b32_e32 v97, v2
	v_mov_b32_e32 v102, v2
	v_mov_b32_e32 v103, v2
	v_mov_b32_e32 v104, v2
	v_mov_b32_e32 v105, v2
	v_mov_b32_e32 v110, v2
	v_mov_b32_e32 v111, v2
	v_mov_b32_e32 v112, v2
	v_mov_b32_e32 v113, v2
	v_mov_b32_e32 v118, v2
	v_mov_b32_e32 v119, v2
	v_mov_b32_e32 v120, v2
	v_mov_b32_e32 v121, v2
	v_mov_b32_e32 v74, v2
	v_mov_b32_e32 v75, v2
	v_mov_b32_e32 v76, v2
	v_mov_b32_e32 v77, v2
	v_mov_b32_e32 v82, v2
	v_mov_b32_e32 v83, v2
	v_mov_b32_e32 v84, v2
	v_mov_b32_e32 v85, v2
	v_mov_b32_e32 v90, v2
	v_mov_b32_e32 v91, v2
	v_mov_b32_e32 v92, v2
	v_mov_b32_e32 v93, v2
	v_mov_b32_e32 v98, v2
	v_mov_b32_e32 v99, v2
	v_mov_b32_e32 v100, v2
	v_mov_b32_e32 v101, v2
	v_mov_b32_e32 v106, v2
	v_mov_b32_e32 v107, v2
	v_mov_b32_e32 v108, v2
	v_mov_b32_e32 v109, v2
	v_mov_b32_e32 v114, v2
	v_mov_b32_e32 v115, v2
	v_mov_b32_e32 v116, v2
	v_mov_b32_e32 v117, v2
	v_mov_b32_e32 v122, v2
	v_mov_b32_e32 v123, v2
	v_mov_b32_e32 v124, v2
	v_mov_b32_e32 v125, v2
	v_mov_b32_e32 v126, v2
	v_mov_b32_e32 v127, v2
	v_mov_b32_e32 v128, v2
	v_mov_b32_e32 v129, v2
	s_add_i32 s30, s66, 0xffc00000
	s_and_b32 s30, s30, 0x3800000
	s_and_b32 s31, s28, 0x100
	s_or_b32 s67, s31, s30
	s_and_b32 s34, s66, 0x7800000
	s_add_u32 s30, s28, 0x100
	s_addc_u32 s31, s29, 0
	s_and_b32 s35, s30, 0x100
	s_or_b32 s34, s34, s35
	s_add_u32 s34, s26, s34
	s_addc_u32 s35, s27, 0
	s_add_u32 s28, s63, s28
	s_addc_u32 s29, s64, s29
	s_add_i32 s70, 0, 0x10000
	s_cmp_eq_u32 s65, 28
	s_cselect_b32 s35, s19, s35
	s_cselect_b32 s34, s61, s34
	v_add_u32_e32 v139, s70, v165
	s_cselect_b32 s29, s17, s29
	s_cselect_b32 s28, s62, s28
	s_add_i32 s71, 0, 0x14000
	ds_read_b128 v[152:155], v139
	ds_read_b128 v[160:163], v139 offset:1024
	ds_read_b128 v[174:177], v139 offset:2048
	ds_read_b128 v[178:181], v139 offset:3072
	v_add_u32_e32 v139, s71, v165
	ds_read_b128 v[182:185], v139
	ds_read_b128 v[186:189], v139 offset:1024
	ds_read_b128 v[190:193], v139 offset:2048
	ds_read_b128 v[194:197], v139 offset:3072
	s_add_u32 s67, s26, s67
	s_addc_u32 s69, s27, 0
	s_add_u32 s68, s67, 0x10080
	s_addc_u32 s69, s69, 0
	s_add_i32 m0, s25, 0xc000
	ds_read_b128 v[198:201], v173
	ds_read_b128 v[202:205], v173 offset:1024
	ds_read_b128 v[206:209], v173 offset:2048
	ds_read_b128 v[210:213], v173 offset:3072
	ds_read_b128 v[214:217], v173 offset:4096
	ds_read_b128 v[218:221], v173 offset:5120
	ds_read_b128 v[222:225], v173 offset:6144
	ds_read_b128 v[226:229], v173 offset:7168
	global_load_lds_dwordx4 v136, s[68:69]
	s_add_i32 m0, s25, 0xe000
	s_nop 0
	global_load_lds_dwordx4 v132, s[68:69]
	s_waitcnt vmcnt(24)
	s_waitcnt lgkmcnt(0)
	v_mfma_f32_16x16x32_bf16 v[126:129], v[152:155], v[198:201], v[126:129]
	v_mfma_f32_16x16x32_bf16 v[122:125], v[174:177], v[198:201], v[122:125]
	v_mfma_f32_16x16x32_bf16 v[114:117], v[152:155], v[206:209], v[114:117]
	v_mfma_f32_16x16x32_bf16 v[106:109], v[174:177], v[206:209], v[106:109]
	s_barrier
; #define PG8_STAGE(bufoff, gbase, voff) do { _Pragma("unroll") for (int _i = 0; _i < 2; ++_i) \
;         __builtin_amdgcn_global_load_lds((const unsigned*)((const char*)(gbase) + (voff)[_i]), (LAS unsigned*)(lds + (bufoff) + ldsw + _i * 8192), 16, 0, 0); } while (0)
; #define PG8_LDA(dst, b, h) do { _Pragma("unroll") for (int m = 0; m < 4; ++m) _Pragma("unroll") for (int k = 0; k < 2; ++k) dst[m][k] = *(const LAS bf16x8*)(lds + PG8_SA(b, h) + aoff + m * 2048 + k * 1024); } while (0)
; #define PG8_MMA(ai, bj, At, Bt) do { __builtin_amdgcn_s_setprio(1); _Pragma("unroll") for (int m = 0; m < 4; ++m) _Pragma("unroll") for (int n = 0; n < 2; ++n) _Pragma("unroll") for (int k = 0; k < 2; ++k) \
;         acc[ai][bj][m][n] = __builtin_amdgcn_mfma_f32_16x16x32_bf16(Bt[n][k], At[m][k], acc[ai][bj][m][n], 0, 0, 0); __builtin_amdgcn_s_setprio(0); } while (0)
; #define PG8_WAIT_V(n) asm volatile("s_waitcnt vmcnt(" #n ")" ::: "memory")
; #define PG8_WAIT_L(n) asm volatile("s_waitcnt lgkmcnt(" #n ")" ::: "memory")
; #define PG8_BAR __builtin_amdgcn_s_barrier()
; #define PG8_SCHED __builtin_amdgcn_sched_barrier(0)
; template <class Epi, class Sched, int KC, bool ALIGN_EPI = false, bool SP2 = false, bool ATILED = false>
; __device__ __forceinline__ void gemm_phase(LAS unsigned char* lds, const Gemm g, const Sched& S, const Epi& E, int wave_s) {
;     ...
;             PG8_WAIT_V(8); PG8_WAIT_L(0); PG8_BAR; PG8_MMA(0, 0, At, B0); PG8_MMA(0, 1, At, B1); PG8_BAR; PG8_SCHED;
;             PG8_LDA(At, 0, 1); PG8_STAGE(PG8_SB(0, 0), b2, voffB); PG8_STAGE(PG8_SB(0, 1), b2 + hstepB, voffB); PG8_STAGE(PG8_SA(0, 0), a2, voffA);
;             PG8_WAIT_V(8); PG8_WAIT_L(0); PG8_BAR; PG8_MMA(1, 0, At, B0); PG8_MMA(1, 1, At, B1); PG8_BAR; PG8_SCHED;
	s_waitcnt lgkmcnt(0)
	v_mfma_f32_16x16x32_bf16 v[98:101], v[152:155], v[214:217], v[98:101]
	v_mfma_f32_16x16x32_bf16 v[90:93], v[174:177], v[214:217], v[90:93]
	v_mfma_f32_16x16x32_bf16 v[82:85], v[152:155], v[222:225], v[82:85]
	v_mfma_f32_16x16x32_bf16 v[74:77], v[174:177], v[222:225], v[74:77]
	v_mfma_f32_16x16x32_bf16 v[126:129], v[160:163], v[202:205], v[126:129]
	v_mfma_f32_16x16x32_bf16 v[122:125], v[178:181], v[202:205], v[122:125]
	v_mfma_f32_16x16x32_bf16 v[114:117], v[160:163], v[210:213], v[114:117]
	v_mfma_f32_16x16x32_bf16 v[106:109], v[178:181], v[210:213], v[106:109]
	v_mfma_f32_16x16x32_bf16 v[98:101], v[160:163], v[218:221], v[98:101]
	v_mfma_f32_16x16x32_bf16 v[90:93], v[178:181], v[218:221], v[90:93]
	v_mfma_f32_16x16x32_bf16 v[82:85], v[160:163], v[226:229], v[82:85]
	v_mfma_f32_16x16x32_bf16 v[74:77], v[178:181], v[226:229], v[74:77]
	v_mfma_f32_16x16x32_bf16 v[118:121], v[182:185], v[198:201], v[118:121]
	v_mfma_f32_16x16x32_bf16 v[110:113], v[190:193], v[198:201], v[110:113]
	v_mfma_f32_16x16x32_bf16 v[102:105], v[182:185], v[206:209], v[102:105]
	v_mfma_f32_16x16x32_bf16 v[94:97], v[190:193], v[206:209], v[94:97]
	v_mfma_f32_16x16x32_bf16 v[86:89], v[182:185], v[214:217], v[86:89]
	v_mfma_f32_16x16x32_bf16 v[78:81], v[190:193], v[214:217], v[78:81]
	v_mfma_f32_16x16x32_bf16 v[70:73], v[182:185], v[222:225], v[70:73]
	v_mfma_f32_16x16x32_bf16 v[66:69], v[190:193], v[222:225], v[66:69]
	v_mfma_f32_16x16x32_bf16 v[118:121], v[186:189], v[202:205], v[118:121]
	v_mfma_f32_16x16x32_bf16 v[110:113], v[194:197], v[202:205], v[110:113]
	v_mfma_f32_16x16x32_bf16 v[102:105], v[186:189], v[210:213], v[102:105]
	v_mfma_f32_16x16x32_bf16 v[94:97], v[194:197], v[210:213], v[94:97]
	v_mfma_f32_16x16x32_bf16 v[86:89], v[186:189], v[218:221], v[86:89]
	v_mfma_f32_16x16x32_bf16 v[78:81], v[194:197], v[218:221], v[78:81]
	v_mfma_f32_16x16x32_bf16 v[70:73], v[186:189], v[226:229], v[70:73]
	v_mfma_f32_16x16x32_bf16 v[66:69], v[194:197], v[226:229], v[66:69]
	s_barrier
	s_add_u32 s100, s34, 0x80
	s_addc_u32 s101, s35, 0
	s_add_i32 s67, s70, s41
	s_mov_b32 m0, s67
	ds_read_b128 v[198:201], v173 offset:16384
	ds_read_b128 v[202:205], v173 offset:17408
	ds_read_b128 v[206:209], v173 offset:18432
	ds_read_b128 v[210:213], v173 offset:19456
	ds_read_b128 v[214:217], v173 offset:20480
	ds_read_b128 v[218:221], v173 offset:21504
	ds_read_b128 v[222:225], v173 offset:22528
	ds_read_b128 v[226:229], v173 offset:23552
	global_load_lds_dwordx4 v134, s[28:29]
	s_add_i32 m0, s67, 0x2000
	s_add_u32 s68, s28, 0x80000
	s_addc_u32 s69, s29, 0
	s_add_i32 s67, s71, s41
	global_load_lds_dwordx4 v130, s[28:29]
	s_mov_b32 m0, s67
	s_nop 0
	global_load_lds_dwordx4 v134, s[68:69]
	s_add_i32 m0, s67, 0x2000
	s_nop 0
	global_load_lds_dwordx4 v130, s[68:69]
	s_mov_b32 m0, s25
	s_nop 0
	global_load_lds_dwordx4 v136, s[34:35]
	s_mov_b32 m0, s52
	s_nop 0
	global_load_lds_dwordx4 v132, s[34:35]
	s_waitcnt vmcnt(24)
	s_waitcnt lgkmcnt(0)
	v_mfma_f32_16x16x32_bf16 v[62:65], v[152:155], v[198:201], v[62:65]
	v_mfma_f32_16x16x32_bf16 v[58:61], v[174:177], v[198:201], v[58:61]
	v_mfma_f32_16x16x32_bf16 v[50:53], v[152:155], v[206:209], v[50:53]
	v_mfma_f32_16x16x32_bf16 v[42:45], v[174:177], v[206:209], v[42:45]
	s_barrier
	s_waitcnt lgkmcnt(0)
	v_mfma_f32_16x16x32_bf16 v[34:37], v[152:155], v[214:217], v[34:37]
	v_mfma_f32_16x16x32_bf16 v[26:29], v[174:177], v[214:217], v[26:29]
	v_mfma_f32_16x16x32_bf16 v[18:21], v[152:155], v[222:225], v[18:21]
	v_mfma_f32_16x16x32_bf16 v[10:13], v[174:177], v[222:225], v[10:13]
	v_mfma_f32_16x16x32_bf16 v[62:65], v[160:163], v[202:205], v[62:65]
	v_mfma_f32_16x16x32_bf16 v[58:61], v[178:181], v[202:205], v[58:61]
	v_mfma_f32_16x16x32_bf16 v[50:53], v[160:163], v[210:213], v[50:53]
	v_mfma_f32_16x16x32_bf16 v[42:45], v[178:181], v[210:213], v[42:45]
	v_mfma_f32_16x16x32_bf16 v[34:37], v[160:163], v[218:221], v[34:37]
	v_mfma_f32_16x16x32_bf16 v[26:29], v[178:181], v[218:221], v[26:29]
	v_mfma_f32_16x16x32_bf16 v[18:21], v[160:163], v[226:229], v[18:21]
	v_mfma_f32_16x16x32_bf16 v[10:13], v[178:181], v[226:229], v[10:13]
	v_mfma_f32_16x16x32_bf16 v[54:57], v[182:185], v[198:201], v[54:57]
	v_mfma_f32_16x16x32_bf16 v[46:49], v[190:193], v[198:201], v[46:49]
	v_mfma_f32_16x16x32_bf16 v[38:41], v[182:185], v[206:209], v[38:41]
	v_mfma_f32_16x16x32_bf16 v[30:33], v[190:193], v[206:209], v[30:33]
	v_mfma_f32_16x16x32_bf16 v[22:25], v[182:185], v[214:217], v[22:25]
	v_mfma_f32_16x16x32_bf16 v[14:17], v[190:193], v[214:217], v[14:17]
	v_mfma_f32_16x16x32_bf16 v[6:9], v[182:185], v[222:225], v[6:9]
	v_mfma_f32_16x16x32_bf16 v[2:5], v[190:193], v[222:225], v[2:5]
	v_mfma_f32_16x16x32_bf16 v[54:57], v[186:189], v[202:205], v[54:57]
	v_mfma_f32_16x16x32_bf16 v[46:49], v[194:197], v[202:205], v[46:49]
	v_mfma_f32_16x16x32_bf16 v[38:41], v[186:189], v[210:213], v[38:41]
	v_mfma_f32_16x16x32_bf16 v[30:33], v[194:197], v[210:213], v[30:33]
	v_mfma_f32_16x16x32_bf16 v[22:25], v[186:189], v[218:221], v[22:25]
	v_mfma_f32_16x16x32_bf16 v[14:17], v[194:197], v[218:221], v[14:17]
	v_mfma_f32_16x16x32_bf16 v[6:9], v[186:189], v[226:229], v[6:9]
	v_mfma_f32_16x16x32_bf16 v[2:5], v[194:197], v[226:229], v[2:5]
	s_barrier
; #define PG8_STAGE(bufoff, gbase, voff) do { _Pragma("unroll") for (int _i = 0; _i < 2; ++_i) \
;         __builtin_amdgcn_global_load_lds((const unsigned*)((const char*)(gbase) + (voff)[_i]), (LAS unsigned*)(lds + (bufoff) + ldsw + _i * 8192), 16, 0, 0); } while (0)
; #define PG8_LDA(dst, b, h) do { _Pragma("unroll") for (int m = 0; m < 4; ++m) _Pragma("unroll") for (int k = 0; k < 2; ++k) dst[m][k] = *(const LAS bf16x8*)(lds + PG8_SA(b, h) + aoff + m * 2048 + k * 1024); } while (0)
; #define PG8_LDB(dst, b, h) do { _Pragma("unroll") for (int n = 0; n < 2; ++n) _Pragma("unroll") for (int k = 0; k < 2; ++k) dst[n][k] = *(const LAS bf16x8*)(lds + PG8_SB(b, h) + boff + n * 2048 + k * 1024); } while (0)
; #define PG8_MMA(ai, bj, At, Bt) do { __builtin_amdgcn_s_setprio(1); _Pragma("unroll") for (int m = 0; m < 4; ++m) _Pragma("unroll") for (int n = 0; n < 2; ++n) _Pragma("unroll") for (int k = 0; k < 2; ++k) \
;         acc[ai][bj][m][n] = __builtin_amdgcn_mfma_f32_16x16x32_bf16(Bt[n][k], At[m][k], acc[ai][bj][m][n], 0, 0, 0); __builtin_amdgcn_s_setprio(0); } while (0)
; #define PG8_WAIT_V(n) asm volatile("s_waitcnt vmcnt(" #n ")" ::: "memory")
; #define PG8_WAIT_L(n) asm volatile("s_waitcnt lgkmcnt(" #n ")" ::: "memory")
; #define PG8_BAR __builtin_amdgcn_s_barrier()
; #define PG8_SCHED __builtin_amdgcn_sched_barrier(0)
; template <class Epi, class Sched, int KC, bool ALIGN_EPI = false, bool SP2 = false, bool ATILED = false>
; __device__ __forceinline__ void gemm_phase(LAS unsigned char* lds, const Gemm g, const Sched& S, const Epi& E, int wave_s) {
;     ...
;             PG8_LDB(B0, 1, 0); PG8_LDB(B1, 1, 1); PG8_SCHED; PG8_LDA(At, 1, 0); PG8_STAGE(PG8_SA(0, 1), a2 + hstepA, voffA);
;             PG8_WAIT_V(8); PG8_WAIT_L(0); PG8_BAR; PG8_MMA(0, 0, At, B0); PG8_MMA(0, 1, At, B1); PG8_BAR; PG8_SCHED;
;             PG8_LDA(At, 1, 1); PG8_STAGE(PG8_SB(1, 0), b3, voffB); PG8_STAGE(PG8_SB(1, 1), b3 + hstepB, voffB); PG8_STAGE(PG8_SA(1, 0), a3, voffA);
;             PG8_WAIT_V(8); PG8_WAIT_L(0); PG8_BAR; PG8_MMA(1, 0, At, B0); PG8_MMA(1, 1, At, B1); PG8_BAR; PG8_SCHED;
	s_add_i32 s67, 0, 0x18000
	v_add_u32_e32 v139, s67, v165
	s_add_i32 s68, 0, 0x1c000
	ds_read_b128 v[152:155], v139
	ds_read_b128 v[160:163], v139 offset:1024
	ds_read_b128 v[174:177], v139 offset:2048
	ds_read_b128 v[178:181], v139 offset:3072
	v_add_u32_e32 v139, s68, v165
	ds_read_b128 v[182:185], v139
	ds_read_b128 v[186:189], v139 offset:1024
	ds_read_b128 v[190:193], v139 offset:2048
	ds_read_b128 v[194:197], v139 offset:3072
	s_add_u32 s34, s34, 0x10000
	s_addc_u32 s35, s35, 0
	s_mov_b32 m0, s53
	ds_read_b128 v[198:201], v173 offset:32768
	ds_read_b128 v[202:205], v173 offset:33792
	ds_read_b128 v[206:209], v173 offset:34816
	ds_read_b128 v[210:213], v173 offset:35840
	ds_read_b128 v[214:217], v173 offset:36864
	ds_read_b128 v[218:221], v173 offset:37888
	ds_read_b128 v[222:225], v173 offset:38912
	ds_read_b128 v[226:229], v173 offset:39936
	global_load_lds_dwordx4 v136, s[34:35]
	s_mov_b32 m0, s54
	s_nop 0
	global_load_lds_dwordx4 v132, s[34:35]
	s_waitcnt vmcnt(8)
	s_waitcnt lgkmcnt(0)
	v_mfma_f32_16x16x32_bf16 v[126:129], v[152:155], v[198:201], v[126:129]
	v_mfma_f32_16x16x32_bf16 v[122:125], v[174:177], v[198:201], v[122:125]
	v_mfma_f32_16x16x32_bf16 v[114:117], v[152:155], v[206:209], v[114:117]
	v_mfma_f32_16x16x32_bf16 v[106:109], v[174:177], v[206:209], v[106:109]
	s_barrier
	s_waitcnt lgkmcnt(0)
	v_mfma_f32_16x16x32_bf16 v[98:101], v[152:155], v[214:217], v[98:101]
	v_mfma_f32_16x16x32_bf16 v[90:93], v[174:177], v[214:217], v[90:93]
	v_mfma_f32_16x16x32_bf16 v[82:85], v[152:155], v[222:225], v[82:85]
	v_mfma_f32_16x16x32_bf16 v[74:77], v[174:177], v[222:225], v[74:77]
	v_mfma_f32_16x16x32_bf16 v[126:129], v[160:163], v[202:205], v[126:129]
	v_mfma_f32_16x16x32_bf16 v[122:125], v[178:181], v[202:205], v[122:125]
	v_mfma_f32_16x16x32_bf16 v[114:117], v[160:163], v[210:213], v[114:117]
	v_mfma_f32_16x16x32_bf16 v[106:109], v[178:181], v[210:213], v[106:109]
	v_mfma_f32_16x16x32_bf16 v[98:101], v[160:163], v[218:221], v[98:101]
	v_mfma_f32_16x16x32_bf16 v[90:93], v[178:181], v[218:221], v[90:93]
	v_mfma_f32_16x16x32_bf16 v[82:85], v[160:163], v[226:229], v[82:85]
	v_mfma_f32_16x16x32_bf16 v[74:77], v[178:181], v[226:229], v[74:77]
	v_mfma_f32_16x16x32_bf16 v[118:121], v[182:185], v[198:201], v[118:121]
	v_mfma_f32_16x16x32_bf16 v[110:113], v[190:193], v[198:201], v[110:113]
	v_mfma_f32_16x16x32_bf16 v[102:105], v[182:185], v[206:209], v[102:105]
	v_mfma_f32_16x16x32_bf16 v[94:97], v[190:193], v[206:209], v[94:97]
	v_mfma_f32_16x16x32_bf16 v[86:89], v[182:185], v[214:217], v[86:89]
	v_mfma_f32_16x16x32_bf16 v[78:81], v[190:193], v[214:217], v[78:81]
	v_mfma_f32_16x16x32_bf16 v[70:73], v[182:185], v[222:225], v[70:73]
	v_mfma_f32_16x16x32_bf16 v[66:69], v[190:193], v[222:225], v[66:69]
	v_mfma_f32_16x16x32_bf16 v[118:121], v[186:189], v[202:205], v[118:121]
	v_mfma_f32_16x16x32_bf16 v[110:113], v[194:197], v[202:205], v[110:113]
	v_mfma_f32_16x16x32_bf16 v[102:105], v[186:189], v[210:213], v[102:105]
	v_mfma_f32_16x16x32_bf16 v[94:97], v[194:197], v[210:213], v[94:97]
	v_mfma_f32_16x16x32_bf16 v[86:89], v[186:189], v[218:221], v[86:89]
	v_mfma_f32_16x16x32_bf16 v[78:81], v[194:197], v[218:221], v[78:81]
	v_mfma_f32_16x16x32_bf16 v[70:73], v[186:189], v[226:229], v[70:73]
	v_mfma_f32_16x16x32_bf16 v[66:69], v[194:197], v[226:229], v[66:69]
	s_barrier
	s_add_u32 s98, s28, 0x80
	s_addc_u32 s99, s29, 0
	s_add_i32 s34, s67, s41
	s_mov_b32 m0, s34
	ds_read_b128 v[198:201], v173 offset:49152
	ds_read_b128 v[202:205], v173 offset:50176
	ds_read_b128 v[206:209], v173 offset:51200
	ds_read_b128 v[210:213], v173 offset:52224
	ds_read_b128 v[214:217], v173 offset:53248
	ds_read_b128 v[218:221], v173 offset:54272
	ds_read_b128 v[222:225], v173 offset:55296
	ds_read_b128 v[226:229], v173 offset:56320
	global_load_lds_dwordx4 v134, s[98:99]
	s_add_i32 m0, s34, 0x2000
	s_add_u32 s28, s28, 0x80080
	s_addc_u32 s29, s29, 0
	s_add_i32 s34, s68, s41
	global_load_lds_dwordx4 v130, s[98:99]
	s_mov_b32 m0, s34
	s_nop 0
	global_load_lds_dwordx4 v134, s[28:29]
	s_add_i32 m0, s34, 0x2000
	s_nop 0
	global_load_lds_dwordx4 v130, s[28:29]
	s_mov_b32 m0, s55
	s_nop 0
	global_load_lds_dwordx4 v136, s[100:101]
	s_mov_b32 m0, s56
	s_nop 0
	global_load_lds_dwordx4 v132, s[100:101]
	s_waitcnt vmcnt(8)
	s_waitcnt lgkmcnt(0)
	v_mfma_f32_16x16x32_bf16 v[62:65], v[152:155], v[198:201], v[62:65]
	v_mfma_f32_16x16x32_bf16 v[58:61], v[174:177], v[198:201], v[58:61]
	v_mfma_f32_16x16x32_bf16 v[50:53], v[152:155], v[206:209], v[50:53]
	v_mfma_f32_16x16x32_bf16 v[42:45], v[174:177], v[206:209], v[42:45]
	s_barrier
	s_waitcnt lgkmcnt(0)
	v_mfma_f32_16x16x32_bf16 v[34:37], v[152:155], v[214:217], v[34:37]
	v_mfma_f32_16x16x32_bf16 v[26:29], v[174:177], v[214:217], v[26:29]
	v_mfma_f32_16x16x32_bf16 v[18:21], v[152:155], v[222:225], v[18:21]
	v_mfma_f32_16x16x32_bf16 v[10:13], v[174:177], v[222:225], v[10:13]
	v_mfma_f32_16x16x32_bf16 v[62:65], v[160:163], v[202:205], v[62:65]
	v_mfma_f32_16x16x32_bf16 v[58:61], v[178:181], v[202:205], v[58:61]
	v_mfma_f32_16x16x32_bf16 v[50:53], v[160:163], v[210:213], v[50:53]
	v_mfma_f32_16x16x32_bf16 v[42:45], v[178:181], v[210:213], v[42:45]
	v_mfma_f32_16x16x32_bf16 v[34:37], v[160:163], v[218:221], v[34:37]
	v_mfma_f32_16x16x32_bf16 v[26:29], v[178:181], v[218:221], v[26:29]
	v_mfma_f32_16x16x32_bf16 v[18:21], v[160:163], v[226:229], v[18:21]
	v_mfma_f32_16x16x32_bf16 v[10:13], v[178:181], v[226:229], v[10:13]
	v_mfma_f32_16x16x32_bf16 v[54:57], v[182:185], v[198:201], v[54:57]
	v_mfma_f32_16x16x32_bf16 v[46:49], v[190:193], v[198:201], v[46:49]
	v_mfma_f32_16x16x32_bf16 v[38:41], v[182:185], v[206:209], v[38:41]
	v_mfma_f32_16x16x32_bf16 v[30:33], v[190:193], v[206:209], v[30:33]
	v_mfma_f32_16x16x32_bf16 v[22:25], v[182:185], v[214:217], v[22:25]
	v_mfma_f32_16x16x32_bf16 v[14:17], v[190:193], v[214:217], v[14:17]
	v_mfma_f32_16x16x32_bf16 v[6:9], v[182:185], v[222:225], v[6:9]
	v_mfma_f32_16x16x32_bf16 v[2:5], v[190:193], v[222:225], v[2:5]
	v_mfma_f32_16x16x32_bf16 v[54:57], v[186:189], v[202:205], v[54:57]
	v_mfma_f32_16x16x32_bf16 v[46:49], v[194:197], v[202:205], v[46:49]
	v_mfma_f32_16x16x32_bf16 v[38:41], v[186:189], v[210:213], v[38:41]
	v_mfma_f32_16x16x32_bf16 v[30:33], v[194:197], v[210:213], v[30:33]
	v_mfma_f32_16x16x32_bf16 v[22:25], v[186:189], v[218:221], v[22:25]
	v_mfma_f32_16x16x32_bf16 v[14:17], v[194:197], v[218:221], v[14:17]
	v_mfma_f32_16x16x32_bf16 v[6:9], v[186:189], v[226:229], v[6:9]
	v_mfma_f32_16x16x32_bf16 v[2:5], v[194:197], v[226:229], v[2:5]
	s_barrier
	s_add_i32 s65, s65, 2
	s_add_i32 s66, s66, 0x400000
	s_cmp_gt_u32 s65, 29
	s_mov_b64 s[28:29], s[30:31]
; #define PG8_STAGE(bufoff, gbase, voff) do { _Pragma("unroll") for (int _i = 0; _i < 2; ++_i) \
;         __builtin_amdgcn_global_load_lds((const unsigned*)((const char*)(gbase) + (voff)[_i]), (LAS unsigned*)(lds + (bufoff) + ldsw + _i * 8192), 16, 0, 0); } while (0)
; #define PG8_LDA(dst, b, h) do { _Pragma("unroll") for (int m = 0; m < 4; ++m) _Pragma("unroll") for (int k = 0; k < 2; ++k) dst[m][k] = *(const LAS bf16x8*)(lds + PG8_SA(b, h) + aoff + m * 2048 + k * 1024); } while (0)
; #define PG8_LDB(dst, b, h) do { _Pragma("unroll") for (int n = 0; n < 2; ++n) _Pragma("unroll") for (int k = 0; k < 2; ++k) dst[n][k] = *(const LAS bf16x8*)(lds + PG8_SB(b, h) + boff + n * 2048 + k * 1024); } while (0)
; #define PG8_MMA(ai, bj, At, Bt) do { __builtin_amdgcn_s_setprio(1); _Pragma("unroll") for (int m = 0; m < 4; ++m) _Pragma("unroll") for (int n = 0; n < 2; ++n) _Pragma("unroll") for (int k = 0; k < 2; ++k) \
;         acc[ai][bj][m][n] = __builtin_amdgcn_mfma_f32_16x16x32_bf16(Bt[n][k], At[m][k], acc[ai][bj][m][n], 0, 0, 0); __builtin_amdgcn_s_setprio(0); } while (0)
; #define PG8_WAIT_V(n) asm volatile("s_waitcnt vmcnt(" #n ")" ::: "memory")
; #define PG8_WAIT_L(n) asm volatile("s_waitcnt lgkmcnt(" #n ")" ::: "memory")
; #define PG8_BAR __builtin_amdgcn_s_barrier()
; #define PG8_SCHED __builtin_amdgcn_sched_barrier(0)
; template <class Epi, class Sched, int KC, bool ALIGN_EPI = false, bool SP2 = false, bool ATILED = false>
; __device__ __forceinline__ void gemm_phase(LAS unsigned char* lds, const Gemm g, const Sched& S, const Epi& E, int wave_s) {
;     ...
;             if constexpr (SP2) {
;             PG8_LDB(B0, 0, 0); PG8_LDB(B1, 0, 1); PG8_SCHED; PG8_LDA(At, 0, 0); PG8_STAGE(PG8_SA(1, 1), a1 + hstepA, voffA);
;             PG8_WAIT_V(8); PG8_WAIT_L(0); PG8_BAR; PG8_MMA(0, 0, At, B0); PG8_MMA(0, 1, At, B1); PG8_BAR; PG8_SCHED;
;             PG8_LDA(At, 0, 1); PG8_STAGE(PG8_SB(0, 0), b2, voffB); PG8_STAGE(PG8_SB(0, 1), b2 + hstepB, voffB); PG8_STAGE(PG8_SA(0, 0), a2, voffA);
.LBB0_430:
	s_add_i32 s30, s66, 0xffc00000
	s_and_b32 s30, s30, 0x3800000
	s_and_b32 s31, s28, 0x100
	s_or_b32 s67, s31, s30
	s_and_b32 s34, s66, 0x7800000
	s_add_u32 s30, s28, 0x100
	s_addc_u32 s31, s29, 0
	s_and_b32 s35, s30, 0x100
	s_or_b32 s34, s34, s35
	s_add_u32 s34, s26, s34
	s_addc_u32 s35, s27, 0
	s_add_u32 s28, s63, s28
	s_addc_u32 s29, s64, s29
	s_add_i32 s70, 0, 0x10000
	s_cmp_eq_u32 s65, 28
	s_cselect_b32 s35, s19, s35
	s_cselect_b32 s34, s61, s34
	v_add_u32_e32 v139, s70, v165
	s_cselect_b32 s29, s17, s29
	s_cselect_b32 s28, s62, s28
	s_add_i32 s71, 0, 0x14000
	ds_read_b128 v[152:155], v139
	ds_read_b128 v[160:163], v139 offset:1024
	ds_read_b128 v[174:177], v139 offset:2048
	ds_read_b128 v[178:181], v139 offset:3072
	v_add_u32_e32 v139, s71, v165
	ds_read_b128 v[182:185], v139
	ds_read_b128 v[186:189], v139 offset:1024
	ds_read_b128 v[190:193], v139 offset:2048
	ds_read_b128 v[194:197], v139 offset:3072
	s_add_u32 s67, s26, s67
	s_addc_u32 s69, s27, 0
	s_add_u32 s68, s67, 0x10080
	s_addc_u32 s69, s69, 0
	s_add_i32 m0, s25, 0xc000
	ds_read_b128 v[198:201], v173
	ds_read_b128 v[202:205], v173 offset:1024
	ds_read_b128 v[206:209], v173 offset:2048
	ds_read_b128 v[210:213], v173 offset:3072
	ds_read_b128 v[214:217], v173 offset:4096
	ds_read_b128 v[218:221], v173 offset:5120
	ds_read_b128 v[222:225], v173 offset:6144
	ds_read_b128 v[226:229], v173 offset:7168
	global_load_lds_dwordx4 v136, s[68:69]
	s_add_i32 m0, s25, 0xe000
	s_nop 0
	global_load_lds_dwordx4 v132, s[68:69]
	s_waitcnt vmcnt(8)
	s_waitcnt lgkmcnt(0)
	v_mfma_f32_16x16x32_bf16 v[126:129], v[152:155], v[198:201], v[126:129]
	v_mfma_f32_16x16x32_bf16 v[122:125], v[174:177], v[198:201], v[122:125]
	v_mfma_f32_16x16x32_bf16 v[114:117], v[152:155], v[206:209], v[114:117]
	v_mfma_f32_16x16x32_bf16 v[106:109], v[174:177], v[206:209], v[106:109]
	s_barrier
	s_waitcnt lgkmcnt(0)
	v_mfma_f32_16x16x32_bf16 v[98:101], v[152:155], v[214:217], v[98:101]
	v_mfma_f32_16x16x32_bf16 v[90:93], v[174:177], v[214:217], v[90:93]
	v_mfma_f32_16x16x32_bf16 v[82:85], v[152:155], v[222:225], v[82:85]
	v_mfma_f32_16x16x32_bf16 v[74:77], v[174:177], v[222:225], v[74:77]
	v_mfma_f32_16x16x32_bf16 v[126:129], v[160:163], v[202:205], v[126:129]
	v_mfma_f32_16x16x32_bf16 v[122:125], v[178:181], v[202:205], v[122:125]
	v_mfma_f32_16x16x32_bf16 v[114:117], v[160:163], v[210:213], v[114:117]
	v_mfma_f32_16x16x32_bf16 v[106:109], v[178:181], v[210:213], v[106:109]
	v_mfma_f32_16x16x32_bf16 v[98:101], v[160:163], v[218:221], v[98:101]
	v_mfma_f32_16x16x32_bf16 v[90:93], v[178:181], v[218:221], v[90:93]
	v_mfma_f32_16x16x32_bf16 v[82:85], v[160:163], v[226:229], v[82:85]
	v_mfma_f32_16x16x32_bf16 v[74:77], v[178:181], v[226:229], v[74:77]
	v_mfma_f32_16x16x32_bf16 v[118:121], v[182:185], v[198:201], v[118:121]
	v_mfma_f32_16x16x32_bf16 v[110:113], v[190:193], v[198:201], v[110:113]
	v_mfma_f32_16x16x32_bf16 v[102:105], v[182:185], v[206:209], v[102:105]
	v_mfma_f32_16x16x32_bf16 v[94:97], v[190:193], v[206:209], v[94:97]
	v_mfma_f32_16x16x32_bf16 v[86:89], v[182:185], v[214:217], v[86:89]
	v_mfma_f32_16x16x32_bf16 v[78:81], v[190:193], v[214:217], v[78:81]
	v_mfma_f32_16x16x32_bf16 v[70:73], v[182:185], v[222:225], v[70:73]
	v_mfma_f32_16x16x32_bf16 v[66:69], v[190:193], v[222:225], v[66:69]
	v_mfma_f32_16x16x32_bf16 v[118:121], v[186:189], v[202:205], v[118:121]
	v_mfma_f32_16x16x32_bf16 v[110:113], v[194:197], v[202:205], v[110:113]
	v_mfma_f32_16x16x32_bf16 v[102:105], v[186:189], v[210:213], v[102:105]
	v_mfma_f32_16x16x32_bf16 v[94:97], v[194:197], v[210:213], v[94:97]
	v_mfma_f32_16x16x32_bf16 v[86:89], v[186:189], v[218:221], v[86:89]
	v_mfma_f32_16x16x32_bf16 v[78:81], v[194:197], v[218:221], v[78:81]
	v_mfma_f32_16x16x32_bf16 v[70:73], v[186:189], v[226:229], v[70:73]
	v_mfma_f32_16x16x32_bf16 v[66:69], v[194:197], v[226:229], v[66:69]
	s_barrier
	s_add_u32 s100, s34, 0x80
	s_addc_u32 s101, s35, 0
	s_add_i32 s67, s70, s41
	s_mov_b32 m0, s67
	ds_read_b128 v[198:201], v173 offset:16384
	ds_read_b128 v[202:205], v173 offset:17408
	ds_read_b128 v[206:209], v173 offset:18432
	ds_read_b128 v[210:213], v173 offset:19456
	ds_read_b128 v[214:217], v173 offset:20480
	ds_read_b128 v[218:221], v173 offset:21504
	ds_read_b128 v[222:225], v173 offset:22528
	ds_read_b128 v[226:229], v173 offset:23552
	global_load_lds_dwordx4 v134, s[28:29]
	s_add_i32 m0, s67, 0x2000
	s_add_u32 s68, s28, 0x80000
	s_addc_u32 s69, s29, 0
	s_add_i32 s67, s71, s41
	global_load_lds_dwordx4 v130, s[28:29]
	s_mov_b32 m0, s67
	s_nop 0
	global_load_lds_dwordx4 v134, s[68:69]
	s_add_i32 m0, s67, 0x2000
	s_nop 0
	global_load_lds_dwordx4 v130, s[68:69]
	s_mov_b32 m0, s25
	s_nop 0
	global_load_lds_dwordx4 v136, s[34:35]
	s_mov_b32 m0, s52
	s_nop 0
	global_load_lds_dwordx4 v132, s[34:35]
	s_waitcnt vmcnt(8)
	s_waitcnt lgkmcnt(0)
	v_mfma_f32_16x16x32_bf16 v[62:65], v[152:155], v[198:201], v[62:65]
	v_mfma_f32_16x16x32_bf16 v[58:61], v[174:177], v[198:201], v[58:61]
	v_mfma_f32_16x16x32_bf16 v[50:53], v[152:155], v[206:209], v[50:53]
	v_mfma_f32_16x16x32_bf16 v[42:45], v[174:177], v[206:209], v[42:45]
	s_barrier
; #define PG8_STAGE(bufoff, gbase, voff) do { _Pragma("unroll") for (int _i = 0; _i < 2; ++_i) \
;         __builtin_amdgcn_global_load_lds((const unsigned*)((const char*)(gbase) + (voff)[_i]), (LAS unsigned*)(lds + (bufoff) + ldsw + _i * 8192), 16, 0, 0); } while (0)
; #define PG8_LDA(dst, b, h) do { _Pragma("unroll") for (int m = 0; m < 4; ++m) _Pragma("unroll") for (int k = 0; k < 2; ++k) dst[m][k] = *(const LAS bf16x8*)(lds + PG8_SA(b, h) + aoff + m * 2048 + k * 1024); } while (0)
; #define PG8_LDB(dst, b, h) do { _Pragma("unroll") for (int n = 0; n < 2; ++n) _Pragma("unroll") for (int k = 0; k < 2; ++k) dst[n][k] = *(const LAS bf16x8*)(lds + PG8_SB(b, h) + boff + n * 2048 + k * 1024); } while (0)
; #define PG8_MMA(ai, bj, At, Bt) do { __builtin_amdgcn_s_setprio(1); _Pragma("unroll") for (int m = 0; m < 4; ++m) _Pragma("unroll") for (int n = 0; n < 2; ++n) _Pragma("unroll") for (int k = 0; k < 2; ++k) \
;         acc[ai][bj][m][n] = __builtin_amdgcn_mfma_f32_16x16x32_bf16(Bt[n][k], At[m][k], acc[ai][bj][m][n], 0, 0, 0); __builtin_amdgcn_s_setprio(0); } while (0)
; #define PG8_WAIT_V(n) asm volatile("s_waitcnt vmcnt(" #n ")" ::: "memory")
; #define PG8_WAIT_L(n) asm volatile("s_waitcnt lgkmcnt(" #n ")" ::: "memory")
; #define PG8_BAR __builtin_amdgcn_s_barrier()
; #define PG8_SCHED __builtin_amdgcn_sched_barrier(0)
; template <class Epi, class Sched, int KC, bool ALIGN_EPI = false, bool SP2 = false, bool ATILED = false>
; __device__ __forceinline__ void gemm_phase(LAS unsigned char* lds, const Gemm g, const Sched& S, const Epi& E, int wave_s) {
;     ...
;             PG8_LDA(At, 0, 1); PG8_STAGE(PG8_SB(0, 0), b2, voffB); PG8_STAGE(PG8_SB(0, 1), b2 + hstepB, voffB); PG8_STAGE(PG8_SA(0, 0), a2, voffA);
;             PG8_WAIT_V(8); PG8_WAIT_L(0); PG8_BAR; PG8_MMA(1, 0, At, B0); PG8_MMA(1, 1, At, B1); PG8_BAR; PG8_SCHED;
;             PG8_LDB(B0, 1, 0); PG8_LDB(B1, 1, 1); PG8_SCHED; PG8_LDA(At, 1, 0); PG8_STAGE(PG8_SA(0, 1), a2 + hstepA, voffA);
;             PG8_WAIT_V(8); PG8_WAIT_L(0); PG8_BAR; PG8_MMA(0, 0, At, B0); PG8_MMA(0, 1, At, B1); PG8_BAR; PG8_SCHED;
	s_waitcnt lgkmcnt(0)
	v_mfma_f32_16x16x32_bf16 v[34:37], v[152:155], v[214:217], v[34:37]
	v_mfma_f32_16x16x32_bf16 v[26:29], v[174:177], v[214:217], v[26:29]
	v_mfma_f32_16x16x32_bf16 v[18:21], v[152:155], v[222:225], v[18:21]
	v_mfma_f32_16x16x32_bf16 v[10:13], v[174:177], v[222:225], v[10:13]
	v_mfma_f32_16x16x32_bf16 v[62:65], v[160:163], v[202:205], v[62:65]
	v_mfma_f32_16x16x32_bf16 v[58:61], v[178:181], v[202:205], v[58:61]
	v_mfma_f32_16x16x32_bf16 v[50:53], v[160:163], v[210:213], v[50:53]
	v_mfma_f32_16x16x32_bf16 v[42:45], v[178:181], v[210:213], v[42:45]
	v_mfma_f32_16x16x32_bf16 v[34:37], v[160:163], v[218:221], v[34:37]
	v_mfma_f32_16x16x32_bf16 v[26:29], v[178:181], v[218:221], v[26:29]
	v_mfma_f32_16x16x32_bf16 v[18:21], v[160:163], v[226:229], v[18:21]
	v_mfma_f32_16x16x32_bf16 v[10:13], v[178:181], v[226:229], v[10:13]
	v_mfma_f32_16x16x32_bf16 v[54:57], v[182:185], v[198:201], v[54:57]
	v_mfma_f32_16x16x32_bf16 v[46:49], v[190:193], v[198:201], v[46:49]
	v_mfma_f32_16x16x32_bf16 v[38:41], v[182:185], v[206:209], v[38:41]
	v_mfma_f32_16x16x32_bf16 v[30:33], v[190:193], v[206:209], v[30:33]
	v_mfma_f32_16x16x32_bf16 v[22:25], v[182:185], v[214:217], v[22:25]
	v_mfma_f32_16x16x32_bf16 v[14:17], v[190:193], v[214:217], v[14:17]
	v_mfma_f32_16x16x32_bf16 v[6:9], v[182:185], v[222:225], v[6:9]
	v_mfma_f32_16x16x32_bf16 v[2:5], v[190:193], v[222:225], v[2:5]
	v_mfma_f32_16x16x32_bf16 v[54:57], v[186:189], v[202:205], v[54:57]
	v_mfma_f32_16x16x32_bf16 v[46:49], v[194:197], v[202:205], v[46:49]
	v_mfma_f32_16x16x32_bf16 v[38:41], v[186:189], v[210:213], v[38:41]
	v_mfma_f32_16x16x32_bf16 v[30:33], v[194:197], v[210:213], v[30:33]
	v_mfma_f32_16x16x32_bf16 v[22:25], v[186:189], v[218:221], v[22:25]
	v_mfma_f32_16x16x32_bf16 v[14:17], v[194:197], v[218:221], v[14:17]
	v_mfma_f32_16x16x32_bf16 v[6:9], v[186:189], v[226:229], v[6:9]
	v_mfma_f32_16x16x32_bf16 v[2:5], v[194:197], v[226:229], v[2:5]
	s_barrier
	s_add_i32 s67, 0, 0x18000
	v_add_u32_e32 v139, s67, v165
	s_add_i32 s68, 0, 0x1c000
	ds_read_b128 v[152:155], v139
	ds_read_b128 v[160:163], v139 offset:1024
	ds_read_b128 v[174:177], v139 offset:2048
	ds_read_b128 v[178:181], v139 offset:3072
	v_add_u32_e32 v139, s68, v165
	ds_read_b128 v[182:185], v139
	ds_read_b128 v[186:189], v139 offset:1024
	ds_read_b128 v[190:193], v139 offset:2048
	ds_read_b128 v[194:197], v139 offset:3072
	s_add_u32 s34, s34, 0x10000
	s_addc_u32 s35, s35, 0
	s_mov_b32 m0, s53
	ds_read_b128 v[198:201], v173 offset:32768
	ds_read_b128 v[202:205], v173 offset:33792
	ds_read_b128 v[206:209], v173 offset:34816
	ds_read_b128 v[210:213], v173 offset:35840
	ds_read_b128 v[214:217], v173 offset:36864
	ds_read_b128 v[218:221], v173 offset:37888
	ds_read_b128 v[222:225], v173 offset:38912
	ds_read_b128 v[226:229], v173 offset:39936
	global_load_lds_dwordx4 v136, s[34:35]
	s_mov_b32 m0, s54
	s_nop 0
	global_load_lds_dwordx4 v132, s[34:35]
	s_waitcnt vmcnt(8)
	s_waitcnt lgkmcnt(0)
	v_mfma_f32_16x16x32_bf16 v[126:129], v[152:155], v[198:201], v[126:129]
	v_mfma_f32_16x16x32_bf16 v[122:125], v[174:177], v[198:201], v[122:125]
	v_mfma_f32_16x16x32_bf16 v[114:117], v[152:155], v[206:209], v[114:117]
	v_mfma_f32_16x16x32_bf16 v[106:109], v[174:177], v[206:209], v[106:109]
	s_barrier
	s_waitcnt lgkmcnt(0)
	v_mfma_f32_16x16x32_bf16 v[98:101], v[152:155], v[214:217], v[98:101]
	v_mfma_f32_16x16x32_bf16 v[90:93], v[174:177], v[214:217], v[90:93]
	v_mfma_f32_16x16x32_bf16 v[82:85], v[152:155], v[222:225], v[82:85]
	v_mfma_f32_16x16x32_bf16 v[74:77], v[174:177], v[222:225], v[74:77]
	v_mfma_f32_16x16x32_bf16 v[126:129], v[160:163], v[202:205], v[126:129]
	v_mfma_f32_16x16x32_bf16 v[122:125], v[178:181], v[202:205], v[122:125]
	v_mfma_f32_16x16x32_bf16 v[114:117], v[160:163], v[210:213], v[114:117]
	v_mfma_f32_16x16x32_bf16 v[106:109], v[178:181], v[210:213], v[106:109]
	v_mfma_f32_16x16x32_bf16 v[98:101], v[160:163], v[218:221], v[98:101]
	v_mfma_f32_16x16x32_bf16 v[90:93], v[178:181], v[218:221], v[90:93]
	v_mfma_f32_16x16x32_bf16 v[82:85], v[160:163], v[226:229], v[82:85]
	v_mfma_f32_16x16x32_bf16 v[74:77], v[178:181], v[226:229], v[74:77]
	v_mfma_f32_16x16x32_bf16 v[118:121], v[182:185], v[198:201], v[118:121]
	v_mfma_f32_16x16x32_bf16 v[110:113], v[190:193], v[198:201], v[110:113]
	v_mfma_f32_16x16x32_bf16 v[102:105], v[182:185], v[206:209], v[102:105]
	v_mfma_f32_16x16x32_bf16 v[94:97], v[190:193], v[206:209], v[94:97]
	v_mfma_f32_16x16x32_bf16 v[86:89], v[182:185], v[214:217], v[86:89]
	v_mfma_f32_16x16x32_bf16 v[78:81], v[190:193], v[214:217], v[78:81]
	v_mfma_f32_16x16x32_bf16 v[70:73], v[182:185], v[222:225], v[70:73]
	v_mfma_f32_16x16x32_bf16 v[66:69], v[190:193], v[222:225], v[66:69]
	v_mfma_f32_16x16x32_bf16 v[118:121], v[186:189], v[202:205], v[118:121]
	v_mfma_f32_16x16x32_bf16 v[110:113], v[194:197], v[202:205], v[110:113]
	v_mfma_f32_16x16x32_bf16 v[102:105], v[186:189], v[210:213], v[102:105]
	v_mfma_f32_16x16x32_bf16 v[94:97], v[194:197], v[210:213], v[94:97]
	v_mfma_f32_16x16x32_bf16 v[86:89], v[186:189], v[218:221], v[86:89]
	v_mfma_f32_16x16x32_bf16 v[78:81], v[194:197], v[218:221], v[78:81]
	v_mfma_f32_16x16x32_bf16 v[70:73], v[186:189], v[226:229], v[70:73]
	v_mfma_f32_16x16x32_bf16 v[66:69], v[194:197], v[226:229], v[66:69]
	s_barrier
; #define PG8_STAGE(bufoff, gbase, voff) do { _Pragma("unroll") for (int _i = 0; _i < 2; ++_i) \
;         __builtin_amdgcn_global_load_lds((const unsigned*)((const char*)(gbase) + (voff)[_i]), (LAS unsigned*)(lds + (bufoff) + ldsw + _i * 8192), 16, 0, 0); } while (0)
; #define PG8_LDA(dst, b, h) do { _Pragma("unroll") for (int m = 0; m < 4; ++m) _Pragma("unroll") for (int k = 0; k < 2; ++k) dst[m][k] = *(const LAS bf16x8*)(lds + PG8_SA(b, h) + aoff + m * 2048 + k * 1024); } while (0)
; #define PG8_MMA(ai, bj, At, Bt) do { __builtin_amdgcn_s_setprio(1); _Pragma("unroll") for (int m = 0; m < 4; ++m) _Pragma("unroll") for (int n = 0; n < 2; ++n) _Pragma("unroll") for (int k = 0; k < 2; ++k) \
;         acc[ai][bj][m][n] = __builtin_amdgcn_mfma_f32_16x16x32_bf16(Bt[n][k], At[m][k], acc[ai][bj][m][n], 0, 0, 0); __builtin_amdgcn_s_setprio(0); } while (0)
; #define PG8_WAIT_V(n) asm volatile("s_waitcnt vmcnt(" #n ")" ::: "memory")
; #define PG8_WAIT_L(n) asm volatile("s_waitcnt lgkmcnt(" #n ")" ::: "memory")
; #define PG8_BAR __builtin_amdgcn_s_barrier()
; #define PG8_SCHED __builtin_amdgcn_sched_barrier(0)
; template <class Epi, class Sched, int KC, bool ALIGN_EPI = false, bool SP2 = false, bool ATILED = false>
; __device__ __forceinline__ void gemm_phase(LAS unsigned char* lds, const Gemm g, const Sched& S, const Epi& E, int wave_s) {
;     ...
;             PG8_WAIT_V(8); PG8_WAIT_L(0); PG8_BAR; PG8_MMA(0, 0, At, B0); PG8_MMA(0, 1, At, B1); PG8_BAR; PG8_SCHED;
;             PG8_LDA(At, 1, 1); PG8_STAGE(PG8_SB(1, 0), b3, voffB); PG8_STAGE(PG8_SB(1, 1), b3 + hstepB, voffB); PG8_STAGE(PG8_SA(1, 0), a3, voffA);
;             PG8_WAIT_V(8); PG8_WAIT_L(0); PG8_BAR; PG8_MMA(1, 0, At, B0); PG8_MMA(1, 1, At, B1); PG8_BAR; PG8_SCHED;
;     ...
;         if constexpr (ALIGN_EPI) { if (wr == 0) PG8_BAR; }
	s_add_u32 s98, s28, 0x80
	s_addc_u32 s99, s29, 0
	s_add_i32 s34, s67, s41
	s_mov_b32 m0, s34
	ds_read_b128 v[198:201], v173 offset:49152
	ds_read_b128 v[202:205], v173 offset:50176
	ds_read_b128 v[206:209], v173 offset:51200
	ds_read_b128 v[210:213], v173 offset:52224
	ds_read_b128 v[214:217], v173 offset:53248
	ds_read_b128 v[218:221], v173 offset:54272
	ds_read_b128 v[222:225], v173 offset:55296
	ds_read_b128 v[226:229], v173 offset:56320
	global_load_lds_dwordx4 v134, s[98:99]
	s_add_i32 m0, s34, 0x2000
	s_add_u32 s28, s28, 0x80080
	s_addc_u32 s29, s29, 0
	s_add_i32 s34, s68, s41
	global_load_lds_dwordx4 v130, s[98:99]
	s_mov_b32 m0, s34
	s_nop 0
	global_load_lds_dwordx4 v134, s[28:29]
	s_add_i32 m0, s34, 0x2000
	s_nop 0
	global_load_lds_dwordx4 v130, s[28:29]
	s_mov_b32 m0, s55
	s_nop 0
	global_load_lds_dwordx4 v136, s[100:101]
	s_mov_b32 m0, s56
	s_nop 0
	global_load_lds_dwordx4 v132, s[100:101]
	s_waitcnt vmcnt(8)
	s_waitcnt lgkmcnt(0)
	v_mfma_f32_16x16x32_bf16 v[62:65], v[152:155], v[198:201], v[62:65]
	v_mfma_f32_16x16x32_bf16 v[58:61], v[174:177], v[198:201], v[58:61]
	v_mfma_f32_16x16x32_bf16 v[50:53], v[152:155], v[206:209], v[50:53]
	v_mfma_f32_16x16x32_bf16 v[42:45], v[174:177], v[206:209], v[42:45]
	s_barrier
	s_waitcnt lgkmcnt(0)
	v_mfma_f32_16x16x32_bf16 v[34:37], v[152:155], v[214:217], v[34:37]
	v_mfma_f32_16x16x32_bf16 v[26:29], v[174:177], v[214:217], v[26:29]
	v_mfma_f32_16x16x32_bf16 v[18:21], v[152:155], v[222:225], v[18:21]
	v_mfma_f32_16x16x32_bf16 v[10:13], v[174:177], v[222:225], v[10:13]
	v_mfma_f32_16x16x32_bf16 v[62:65], v[160:163], v[202:205], v[62:65]
	v_mfma_f32_16x16x32_bf16 v[58:61], v[178:181], v[202:205], v[58:61]
	v_mfma_f32_16x16x32_bf16 v[50:53], v[160:163], v[210:213], v[50:53]
	v_mfma_f32_16x16x32_bf16 v[42:45], v[178:181], v[210:213], v[42:45]
	v_mfma_f32_16x16x32_bf16 v[34:37], v[160:163], v[218:221], v[34:37]
	v_mfma_f32_16x16x32_bf16 v[26:29], v[178:181], v[218:221], v[26:29]
	v_mfma_f32_16x16x32_bf16 v[18:21], v[160:163], v[226:229], v[18:21]
	v_mfma_f32_16x16x32_bf16 v[10:13], v[178:181], v[226:229], v[10:13]
	v_mfma_f32_16x16x32_bf16 v[54:57], v[182:185], v[198:201], v[54:57]
	v_mfma_f32_16x16x32_bf16 v[46:49], v[190:193], v[198:201], v[46:49]
	v_mfma_f32_16x16x32_bf16 v[38:41], v[182:185], v[206:209], v[38:41]
	v_mfma_f32_16x16x32_bf16 v[30:33], v[190:193], v[206:209], v[30:33]
	v_mfma_f32_16x16x32_bf16 v[22:25], v[182:185], v[214:217], v[22:25]
	v_mfma_f32_16x16x32_bf16 v[14:17], v[190:193], v[214:217], v[14:17]
	v_mfma_f32_16x16x32_bf16 v[6:9], v[182:185], v[222:225], v[6:9]
	v_mfma_f32_16x16x32_bf16 v[2:5], v[190:193], v[222:225], v[2:5]
	v_mfma_f32_16x16x32_bf16 v[54:57], v[186:189], v[202:205], v[54:57]
	v_mfma_f32_16x16x32_bf16 v[46:49], v[194:197], v[202:205], v[46:49]
	v_mfma_f32_16x16x32_bf16 v[38:41], v[186:189], v[210:213], v[38:41]
	v_mfma_f32_16x16x32_bf16 v[30:33], v[194:197], v[210:213], v[30:33]
	v_mfma_f32_16x16x32_bf16 v[22:25], v[186:189], v[218:221], v[22:25]
	v_mfma_f32_16x16x32_bf16 v[14:17], v[194:197], v[218:221], v[14:17]
	v_mfma_f32_16x16x32_bf16 v[6:9], v[186:189], v[226:229], v[6:9]
	v_mfma_f32_16x16x32_bf16 v[2:5], v[194:197], v[226:229], v[2:5]
	s_barrier
	s_add_i32 s65, s65, 2
	s_add_i32 s66, s66, 0x400000
	s_cmp_gt_u32 s65, 29
	s_mov_b64 s[28:29], s[30:31]
	s_cbranch_scc0 .LBB0_430
	s_and_b64 vcc, exec, s[14:15]
	s_cbranch_vccz .LBB0_433
	s_barrier

; #define PG8_STAGE(bufoff, gbase, voff) do { _Pragma("unroll") for (int _i = 0; _i < 2; ++_i) \
;         __builtin_amdgcn_global_load_lds((const unsigned*)((const char*)(gbase) + (voff)[_i]), (LAS unsigned*)(lds + (bufoff) + ldsw + _i * 8192), 16, 0, 0); } while (0)
; #define PG8_LDA(dst, b, h) do { _Pragma("unroll") for (int m = 0; m < 4; ++m) _Pragma("unroll") for (int k = 0; k < 2; ++k) dst[m][k] = *(const LAS bf16x8*)(lds + PG8_SA(b, h) + aoff + m * 2048 + k * 1024); } while (0)
; #define PG8_LDB(dst, b, h) do { _Pragma("unroll") for (int n = 0; n < 2; ++n) _Pragma("unroll") for (int k = 0; k < 2; ++k) dst[n][k] = *(const LAS bf16x8*)(lds + PG8_SB(b, h) + boff + n * 2048 + k * 1024); } while (0)
; #define PG8_WAIT_V(n) asm volatile("s_waitcnt vmcnt(" #n ")" ::: "memory")
; #define PG8_WAIT_L(n) asm volatile("s_waitcnt lgkmcnt(" #n ")" ::: "memory")
; #define PG8_BAR __builtin_amdgcn_s_barrier()
; #define PG8_SCHED __builtin_amdgcn_sched_barrier(0)
; template <class Epi, class Sched, int KC, bool ALIGN_EPI = false, bool SP2 = false, bool ATILED = false>
; __device__ __forceinline__ void gemm_phase(LAS unsigned char* lds, const Gemm g, const Sched& S, const Epi& E, int wave_s) {
;     ...
;         const bool has_next = S.next(ui + 1, nxt);
;         const char* nA = has_next ? (const char*)g.A + (size_t)nxt.pm * tstepA : cA; const char* nB = has_next ? (const char*)g.Bt + (size_t)nxt.pn * tstep : cB;
;         for (int t = 0; t < nt; t += 2) {
;             const bool last = (t == nt - 2);
;             const char* a1 = cA + PG8_AOFF(t + 1);
;             const char* a2 = last ? nA : cA + PG8_AOFF(t + 2); const char* b2 = last ? nB : cB + (size_t)(t + 2) * kstep;
;             const char* a3 = a2 + kstep; const char* b3 = b2 + kstep;
;             if (last && has_next) S.a_ready(nxt);
;             if constexpr (SP2) {
;             PG8_LDB(B0, 0, 0); PG8_LDB(B1, 0, 1); PG8_SCHED; PG8_LDA(At, 0, 0); PG8_STAGE(PG8_SA(1, 1), a1 + hstepA, voffA);
;             PG8_WAIT_V(8); PG8_WAIT_L(0); PG8_BAR; PG8_MMA(0, 0, At, B0); PG8_MMA(0, 1, At, B1); PG8_BAR; PG8_SCHED;
;     ...
; #pragma unroll
;         for (int a = 0; a < 2; ++a)
; #pragma unroll
;             for (int b = 0; b < 2; ++b)
; #pragma unroll
;                 for (int m = 0; m < 4; ++m)
; #pragma unroll
;                     for (int n = 0; n < 2; ++n) acc[a][b][m][n] = (f32x4){0.f, 0.f, 0.f, 0.f};
.LBB0_1020:
	v_mov_b64_e32 v[2:3], 0x200
	s_ashr_i32 s9, s8, 31
	v_cmp_lt_i64_e32 vcc, s[10:11], v[2:3]
	s_lshl_b64 s[10:11], s[8:9], 20
	s_add_u32 s10, s27, s10
	s_addc_u32 s11, s28, s11
	s_and_b64 s[12:13], vcc, exec
	s_cselect_b32 s9, s11, s21
	s_cselect_b32 s15, s10, s20
	s_ashr_i32 s3, s2, 31
	s_lshl_b64 s[12:13], s[2:3], 20
	s_add_u32 s12, s29, s12
	s_addc_u32 s13, s30, s13
	s_and_b64 s[22:23], vcc, exec
	s_cselect_b32 s3, s13, s19
	s_cselect_b32 s17, s12, s18
	s_add_u32 s46, s18, 0x100
	s_addc_u32 s47, s19, 0
	s_add_u32 s18, s20, 0x80080
	v_mov_b32_e32 v2, 0
	s_addc_u32 s19, s21, 0
	s_mov_b32 s48, -2
	v_mov_b32_e32 v3, v2
	v_mov_b32_e32 v4, v2
	v_mov_b32_e32 v5, v2
	v_mov_b32_e32 v6, v2
	v_mov_b32_e32 v7, v2
	v_mov_b32_e32 v8, v2
	v_mov_b32_e32 v9, v2
	v_mov_b32_e32 v18, v2
	v_mov_b32_e32 v19, v2
	v_mov_b32_e32 v20, v2
	v_mov_b32_e32 v21, v2
	v_mov_b32_e32 v22, v2
	v_mov_b32_e32 v23, v2
	v_mov_b32_e32 v24, v2
	v_mov_b32_e32 v25, v2
	v_mov_b32_e32 v34, v2
	v_mov_b32_e32 v35, v2
	v_mov_b32_e32 v36, v2
	v_mov_b32_e32 v37, v2
	v_mov_b32_e32 v38, v2
	v_mov_b32_e32 v39, v2
	v_mov_b32_e32 v40, v2
	v_mov_b32_e32 v41, v2
	v_mov_b32_e32 v50, v2
	v_mov_b32_e32 v51, v2
	v_mov_b32_e32 v52, v2
	v_mov_b32_e32 v53, v2
	v_mov_b32_e32 v54, v2
	v_mov_b32_e32 v55, v2
	v_mov_b32_e32 v56, v2
	v_mov_b32_e32 v57, v2
	v_mov_b32_e32 v10, v2
	v_mov_b32_e32 v11, v2
	v_mov_b32_e32 v12, v2
	v_mov_b32_e32 v13, v2
	v_mov_b32_e32 v14, v2
	v_mov_b32_e32 v15, v2
	v_mov_b32_e32 v16, v2
	v_mov_b32_e32 v17, v2
	v_mov_b32_e32 v26, v2
	v_mov_b32_e32 v27, v2
	v_mov_b32_e32 v28, v2
	v_mov_b32_e32 v29, v2
	v_mov_b32_e32 v30, v2
	v_mov_b32_e32 v31, v2
	v_mov_b32_e32 v32, v2
	v_mov_b32_e32 v33, v2
	v_mov_b32_e32 v42, v2
	v_mov_b32_e32 v43, v2
	v_mov_b32_e32 v44, v2
	v_mov_b32_e32 v45, v2
	v_mov_b32_e32 v46, v2
	v_mov_b32_e32 v47, v2
	v_mov_b32_e32 v48, v2
	v_mov_b32_e32 v49, v2
	v_mov_b32_e32 v58, v2
	v_mov_b32_e32 v59, v2
	v_mov_b32_e32 v60, v2
	v_mov_b32_e32 v61, v2
	v_mov_b32_e32 v62, v2
	v_mov_b32_e32 v63, v2
	v_mov_b32_e32 v64, v2
	v_mov_b32_e32 v65, v2
	v_mov_b32_e32 v66, v2
	v_mov_b32_e32 v67, v2
	v_mov_b32_e32 v68, v2
	v_mov_b32_e32 v69, v2
	v_mov_b32_e32 v70, v2
	v_mov_b32_e32 v71, v2
	v_mov_b32_e32 v72, v2
	v_mov_b32_e32 v73, v2
	s_waitcnt vmcnt(0)
	v_mov_b32_e32 v82, v2
	v_mov_b32_e32 v83, v2
	v_mov_b32_e32 v84, v2
	v_mov_b32_e32 v85, v2
	v_mov_b32_e32 v86, v2
	v_mov_b32_e32 v87, v2
	v_mov_b32_e32 v88, v2
	v_mov_b32_e32 v89, v2
	v_mov_b32_e32 v98, v2
	v_mov_b32_e32 v99, v2
	v_mov_b32_e32 v100, v2
	v_mov_b32_e32 v101, v2
	v_mov_b32_e32 v102, v2
	v_mov_b32_e32 v103, v2
	v_mov_b32_e32 v104, v2
	v_mov_b32_e32 v105, v2
	v_mov_b32_e32 v114, v2
	v_mov_b32_e32 v115, v2
	v_mov_b32_e32 v116, v2
	v_mov_b32_e32 v117, v2
	v_mov_b32_e32 v118, v2
	v_mov_b32_e32 v119, v2
	v_mov_b32_e32 v120, v2
	v_mov_b32_e32 v121, v2
	v_mov_b32_e32 v74, v2
	v_mov_b32_e32 v75, v2
	v_mov_b32_e32 v76, v2
	v_mov_b32_e32 v77, v2
	v_mov_b32_e32 v78, v2
	v_mov_b32_e32 v79, v2
	v_mov_b32_e32 v80, v2
	v_mov_b32_e32 v81, v2
	v_mov_b32_e32 v90, v2
	v_mov_b32_e32 v91, v2
	v_mov_b32_e32 v92, v2
	v_mov_b32_e32 v93, v2
	v_mov_b32_e32 v94, v2
	v_mov_b32_e32 v95, v2
	v_mov_b32_e32 v96, v2
	v_mov_b32_e32 v97, v2
	v_mov_b32_e32 v106, v2
	v_mov_b32_e32 v107, v2
	v_mov_b32_e32 v108, v2
	v_mov_b32_e32 v109, v2
	v_mov_b32_e32 v110, v2
	v_mov_b32_e32 v111, v2
	v_mov_b32_e32 v112, v2
	v_mov_b32_e32 v113, v2
	v_mov_b32_e32 v122, v2
	v_mov_b32_e32 v123, v2
	v_mov_b32_e32 v124, v2
	v_mov_b32_e32 v125, v2
	v_mov_b32_e32 v126, v2
	v_mov_b32_e32 v127, v2
	v_mov_b32_e32 v128, v2
	v_mov_b32_e32 v129, v2
	s_add_u32 s20, s18, 0xfff80080
	s_addc_u32 s21, s19, -1
	s_add_i32 s49, 0, 0x10000
	s_cmp_eq_u32 s48, 28
	s_cselect_b32 s23, s9, s21
	s_cselect_b32 s22, s15, s20
	s_cselect_b32 s21, s3, s47
	s_cselect_b32 s20, s17, s46
	s_add_i32 s52, 0, 0x14000
	v_add_u32_e32 v142, s49, v229
	v_add_u32_e32 v158, s52, v229
	ds_read_b128 v[130:133], v142
	ds_read_b128 v[134:137], v142 offset:1024
	ds_read_b128 v[138:141], v142 offset:2048
	ds_read_b128 v[142:145], v142 offset:3072
	ds_read_b128 v[146:149], v158
	ds_read_b128 v[150:153], v158 offset:1024
	ds_read_b128 v[154:157], v158 offset:2048
	ds_read_b128 v[158:161], v158 offset:3072
	s_add_i32 m0, s34, 0xc000
	ds_read_b128 v[162:165], v230
	ds_read_b128 v[166:169], v230 offset:1024
	ds_read_b128 v[170:173], v230 offset:2048
	ds_read_b128 v[174:177], v230 offset:3072
	ds_read_b128 v[178:181], v230 offset:4096
	ds_read_b128 v[182:185], v230 offset:5120
	ds_read_b128 v[186:189], v230 offset:6144
	ds_read_b128 v[190:193], v230 offset:7168
	global_load_lds_dwordx4 v208, s[18:19]
	s_add_i32 m0, s34, 0xe000
	s_nop 0
	global_load_lds_dwordx4 v206, s[18:19]
	s_waitcnt vmcnt(32)
	s_waitcnt lgkmcnt(0)
	v_mfma_f32_16x16x32_bf16 v[126:129], v[130:133], v[162:165], v[126:129]
	v_mfma_f32_16x16x32_bf16 v[122:125], v[138:141], v[162:165], v[122:125]
	v_mfma_f32_16x16x32_bf16 v[110:113], v[130:133], v[170:173], v[110:113]
	v_mfma_f32_16x16x32_bf16 v[106:109], v[138:141], v[170:173], v[106:109]
	s_barrier
; #define PG8_STAGE(bufoff, gbase, voff) do { _Pragma("unroll") for (int _i = 0; _i < 2; ++_i) \
;         __builtin_amdgcn_global_load_lds((const unsigned*)((const char*)(gbase) + (voff)[_i]), (LAS unsigned*)(lds + (bufoff) + ldsw + _i * 8192), 16, 0, 0); } while (0)
; #define PG8_LDA(dst, b, h) do { _Pragma("unroll") for (int m = 0; m < 4; ++m) _Pragma("unroll") for (int k = 0; k < 2; ++k) dst[m][k] = *(const LAS bf16x8*)(lds + PG8_SA(b, h) + aoff + m * 2048 + k * 1024); } while (0)
; #define PG8_MMA(ai, bj, At, Bt) do { __builtin_amdgcn_s_setprio(1); _Pragma("unroll") for (int m = 0; m < 4; ++m) _Pragma("unroll") for (int n = 0; n < 2; ++n) _Pragma("unroll") for (int k = 0; k < 2; ++k) \
;         acc[ai][bj][m][n] = __builtin_amdgcn_mfma_f32_16x16x32_bf16(Bt[n][k], At[m][k], acc[ai][bj][m][n], 0, 0, 0); __builtin_amdgcn_s_setprio(0); } while (0)
; #define PG8_WAIT_V(n) asm volatile("s_waitcnt vmcnt(" #n ")" ::: "memory")
; #define PG8_WAIT_L(n) asm volatile("s_waitcnt lgkmcnt(" #n ")" ::: "memory")
; #define PG8_BAR __builtin_amdgcn_s_barrier()
; #define PG8_SCHED __builtin_amdgcn_sched_barrier(0)
; template <class Epi, class Sched, int KC, bool ALIGN_EPI = false, bool SP2 = false, bool ATILED = false>
; __device__ __forceinline__ void gemm_phase(LAS unsigned char* lds, const Gemm g, const Sched& S, const Epi& E, int wave_s) {
;     ...
;             PG8_WAIT_V(8); PG8_WAIT_L(0); PG8_BAR; PG8_MMA(0, 0, At, B0); PG8_MMA(0, 1, At, B1); PG8_BAR; PG8_SCHED;
;             PG8_LDA(At, 0, 1); PG8_STAGE(PG8_SB(0, 0), b2, voffB); PG8_STAGE(PG8_SB(0, 1), b2 + hstepB, voffB); PG8_STAGE(PG8_SA(0, 0), a2, voffA);
;             PG8_WAIT_V(8); PG8_WAIT_L(0); PG8_BAR; PG8_MMA(1, 0, At, B0); PG8_MMA(1, 1, At, B1); PG8_BAR; PG8_SCHED;
	s_waitcnt lgkmcnt(0)
	v_mfma_f32_16x16x32_bf16 v[94:97], v[130:133], v[178:181], v[94:97]
	v_mfma_f32_16x16x32_bf16 v[90:93], v[138:141], v[178:181], v[90:93]
	v_mfma_f32_16x16x32_bf16 v[78:81], v[130:133], v[186:189], v[78:81]
	v_mfma_f32_16x16x32_bf16 v[74:77], v[138:141], v[186:189], v[74:77]
	v_mfma_f32_16x16x32_bf16 v[126:129], v[134:137], v[166:169], v[126:129]
	v_mfma_f32_16x16x32_bf16 v[122:125], v[142:145], v[166:169], v[122:125]
	v_mfma_f32_16x16x32_bf16 v[110:113], v[134:137], v[174:177], v[110:113]
	v_mfma_f32_16x16x32_bf16 v[106:109], v[142:145], v[174:177], v[106:109]
	v_mfma_f32_16x16x32_bf16 v[94:97], v[134:137], v[182:185], v[94:97]
	v_mfma_f32_16x16x32_bf16 v[90:93], v[142:145], v[182:185], v[90:93]
	v_mfma_f32_16x16x32_bf16 v[78:81], v[134:137], v[190:193], v[78:81]
	v_mfma_f32_16x16x32_bf16 v[74:77], v[142:145], v[190:193], v[74:77]
	v_mfma_f32_16x16x32_bf16 v[118:121], v[146:149], v[162:165], v[118:121]
	v_mfma_f32_16x16x32_bf16 v[114:117], v[154:157], v[162:165], v[114:117]
	v_mfma_f32_16x16x32_bf16 v[102:105], v[146:149], v[170:173], v[102:105]
	v_mfma_f32_16x16x32_bf16 v[98:101], v[154:157], v[170:173], v[98:101]
	v_mfma_f32_16x16x32_bf16 v[86:89], v[146:149], v[178:181], v[86:89]
	v_mfma_f32_16x16x32_bf16 v[82:85], v[154:157], v[178:181], v[82:85]
	v_mfma_f32_16x16x32_bf16 v[70:73], v[146:149], v[186:189], v[70:73]
	v_mfma_f32_16x16x32_bf16 v[66:69], v[154:157], v[186:189], v[66:69]
	v_mfma_f32_16x16x32_bf16 v[118:121], v[150:153], v[166:169], v[118:121]
	v_mfma_f32_16x16x32_bf16 v[114:117], v[158:161], v[166:169], v[114:117]
	v_mfma_f32_16x16x32_bf16 v[102:105], v[150:153], v[174:177], v[102:105]
	v_mfma_f32_16x16x32_bf16 v[98:101], v[158:161], v[174:177], v[98:101]
	v_mfma_f32_16x16x32_bf16 v[86:89], v[150:153], v[182:185], v[86:89]
	v_mfma_f32_16x16x32_bf16 v[82:85], v[158:161], v[182:185], v[82:85]
	v_mfma_f32_16x16x32_bf16 v[70:73], v[150:153], v[190:193], v[70:73]
	v_mfma_f32_16x16x32_bf16 v[66:69], v[158:161], v[190:193], v[66:69]
	s_barrier
	s_add_u32 s100, s22, 0x80
	s_addc_u32 s101, s23, 0
	s_add_i32 s49, s49, s31
	s_mov_b32 m0, s49
	ds_read_b128 v[162:165], v230 offset:16384
	ds_read_b128 v[166:169], v230 offset:17408
	ds_read_b128 v[170:173], v230 offset:18432
	ds_read_b128 v[174:177], v230 offset:19456
	ds_read_b128 v[178:181], v230 offset:20480
	ds_read_b128 v[182:185], v230 offset:21504
	ds_read_b128 v[186:189], v230 offset:22528
	ds_read_b128 v[190:193], v230 offset:23552
	global_load_lds_dwordx4 v0, s[20:21]
	s_add_i32 m0, s49, 0x2000
	s_add_u32 s50, s20, 0x20000
	s_addc_u32 s51, s21, 0
	s_add_i32 s49, s52, s31
	global_load_lds_dwordx4 v202, s[20:21]
	s_mov_b32 m0, s49
	s_nop 0
	global_load_lds_dwordx4 v0, s[50:51]
	s_add_i32 m0, s49, 0x2000
	s_nop 0
	global_load_lds_dwordx4 v202, s[50:51]
	s_mov_b32 m0, s34
	s_nop 0
	global_load_lds_dwordx4 v198, s[22:23]
	s_mov_b32 m0, s35
	s_nop 0
	global_load_lds_dwordx4 v200, s[22:23]
	s_waitcnt vmcnt(32)
	s_waitcnt lgkmcnt(0)
	v_mfma_f32_16x16x32_bf16 v[62:65], v[130:133], v[162:165], v[62:65]
	v_mfma_f32_16x16x32_bf16 v[58:61], v[138:141], v[162:165], v[58:61]
	v_mfma_f32_16x16x32_bf16 v[46:49], v[130:133], v[170:173], v[46:49]
	v_mfma_f32_16x16x32_bf16 v[42:45], v[138:141], v[170:173], v[42:45]
	s_barrier
	s_waitcnt lgkmcnt(0)
	v_mfma_f32_16x16x32_bf16 v[30:33], v[130:133], v[178:181], v[30:33]
	v_mfma_f32_16x16x32_bf16 v[26:29], v[138:141], v[178:181], v[26:29]
	v_mfma_f32_16x16x32_bf16 v[14:17], v[130:133], v[186:189], v[14:17]
	v_mfma_f32_16x16x32_bf16 v[10:13], v[138:141], v[186:189], v[10:13]
	v_mfma_f32_16x16x32_bf16 v[62:65], v[134:137], v[166:169], v[62:65]
	v_mfma_f32_16x16x32_bf16 v[58:61], v[142:145], v[166:169], v[58:61]
	v_mfma_f32_16x16x32_bf16 v[46:49], v[134:137], v[174:177], v[46:49]
	v_mfma_f32_16x16x32_bf16 v[42:45], v[142:145], v[174:177], v[42:45]
	v_mfma_f32_16x16x32_bf16 v[30:33], v[134:137], v[182:185], v[30:33]
	v_mfma_f32_16x16x32_bf16 v[26:29], v[142:145], v[182:185], v[26:29]
	v_mfma_f32_16x16x32_bf16 v[14:17], v[134:137], v[190:193], v[14:17]
	v_mfma_f32_16x16x32_bf16 v[10:13], v[142:145], v[190:193], v[10:13]
	v_mfma_f32_16x16x32_bf16 v[54:57], v[146:149], v[162:165], v[54:57]
	v_mfma_f32_16x16x32_bf16 v[50:53], v[154:157], v[162:165], v[50:53]
	v_mfma_f32_16x16x32_bf16 v[38:41], v[146:149], v[170:173], v[38:41]
	v_mfma_f32_16x16x32_bf16 v[34:37], v[154:157], v[170:173], v[34:37]
	v_mfma_f32_16x16x32_bf16 v[22:25], v[146:149], v[178:181], v[22:25]
	v_mfma_f32_16x16x32_bf16 v[18:21], v[154:157], v[178:181], v[18:21]
	v_mfma_f32_16x16x32_bf16 v[6:9], v[146:149], v[186:189], v[6:9]
	v_mfma_f32_16x16x32_bf16 v[2:5], v[154:157], v[186:189], v[2:5]
	v_mfma_f32_16x16x32_bf16 v[54:57], v[150:153], v[166:169], v[54:57]
	v_mfma_f32_16x16x32_bf16 v[50:53], v[158:161], v[166:169], v[50:53]
	v_mfma_f32_16x16x32_bf16 v[38:41], v[150:153], v[174:177], v[38:41]
	v_mfma_f32_16x16x32_bf16 v[34:37], v[158:161], v[174:177], v[34:37]
	v_mfma_f32_16x16x32_bf16 v[22:25], v[150:153], v[182:185], v[22:25]
	v_mfma_f32_16x16x32_bf16 v[18:21], v[158:161], v[182:185], v[18:21]
	v_mfma_f32_16x16x32_bf16 v[6:9], v[150:153], v[190:193], v[6:9]
	v_mfma_f32_16x16x32_bf16 v[2:5], v[158:161], v[190:193], v[2:5]
	s_barrier
; #define PG8_STAGE(bufoff, gbase, voff) do { _Pragma("unroll") for (int _i = 0; _i < 2; ++_i) \
;         __builtin_amdgcn_global_load_lds((const unsigned*)((const char*)(gbase) + (voff)[_i]), (LAS unsigned*)(lds + (bufoff) + ldsw + _i * 8192), 16, 0, 0); } while (0)
; #define PG8_LDA(dst, b, h) do { _Pragma("unroll") for (int m = 0; m < 4; ++m) _Pragma("unroll") for (int k = 0; k < 2; ++k) dst[m][k] = *(const LAS bf16x8*)(lds + PG8_SA(b, h) + aoff + m * 2048 + k * 1024); } while (0)
; #define PG8_LDB(dst, b, h) do { _Pragma("unroll") for (int n = 0; n < 2; ++n) _Pragma("unroll") for (int k = 0; k < 2; ++k) dst[n][k] = *(const LAS bf16x8*)(lds + PG8_SB(b, h) + boff + n * 2048 + k * 1024); } while (0)
; #define PG8_MMA(ai, bj, At, Bt) do { __builtin_amdgcn_s_setprio(1); _Pragma("unroll") for (int m = 0; m < 4; ++m) _Pragma("unroll") for (int n = 0; n < 2; ++n) _Pragma("unroll") for (int k = 0; k < 2; ++k) \
;         acc[ai][bj][m][n] = __builtin_amdgcn_mfma_f32_16x16x32_bf16(Bt[n][k], At[m][k], acc[ai][bj][m][n], 0, 0, 0); __builtin_amdgcn_s_setprio(0); } while (0)
; #define PG8_WAIT_V(n) asm volatile("s_waitcnt vmcnt(" #n ")" ::: "memory")
; #define PG8_WAIT_L(n) asm volatile("s_waitcnt lgkmcnt(" #n ")" ::: "memory")
; #define PG8_BAR __builtin_amdgcn_s_barrier()
; #define PG8_SCHED __builtin_amdgcn_sched_barrier(0)
; template <class Epi, class Sched, int KC, bool ALIGN_EPI = false, bool SP2 = false, bool ATILED = false>
; __device__ __forceinline__ void gemm_phase(LAS unsigned char* lds, const Gemm g, const Sched& S, const Epi& E, int wave_s) {
;     ...
;             PG8_LDB(B0, 1, 0); PG8_LDB(B1, 1, 1); PG8_SCHED; PG8_LDA(At, 1, 0); PG8_STAGE(PG8_SA(0, 1), a2 + hstepA, voffA);
;             PG8_WAIT_V(8); PG8_WAIT_L(0); PG8_BAR; PG8_MMA(0, 0, At, B0); PG8_MMA(0, 1, At, B1); PG8_BAR; PG8_SCHED;
;             PG8_LDA(At, 1, 1); PG8_STAGE(PG8_SB(1, 0), b3, voffB); PG8_STAGE(PG8_SB(1, 1), b3 + hstepB, voffB); PG8_STAGE(PG8_SA(1, 0), a3, voffA);
;             PG8_WAIT_V(8); PG8_WAIT_L(0); PG8_BAR; PG8_MMA(1, 0, At, B0); PG8_MMA(1, 1, At, B1); PG8_BAR; PG8_SCHED;
	s_add_i32 s49, 0, 0x18000
	s_add_i32 s50, 0, 0x1c000
	v_add_u32_e32 v142, s49, v229
	v_add_u32_e32 v158, s50, v229
	ds_read_b128 v[130:133], v142
	ds_read_b128 v[134:137], v142 offset:1024
	ds_read_b128 v[138:141], v142 offset:2048
	ds_read_b128 v[142:145], v142 offset:3072
	ds_read_b128 v[146:149], v158
	ds_read_b128 v[150:153], v158 offset:1024
	ds_read_b128 v[154:157], v158 offset:2048
	ds_read_b128 v[158:161], v158 offset:3072
	s_add_u32 s22, s22, 0x80000
	s_addc_u32 s23, s23, 0
	s_mov_b32 m0, s36
	ds_read_b128 v[162:165], v230 offset:32768
	ds_read_b128 v[166:169], v230 offset:33792
	ds_read_b128 v[170:173], v230 offset:34816
	ds_read_b128 v[174:177], v230 offset:35840
	ds_read_b128 v[178:181], v230 offset:36864
	ds_read_b128 v[182:185], v230 offset:37888
	ds_read_b128 v[186:189], v230 offset:38912
	ds_read_b128 v[190:193], v230 offset:39936
	global_load_lds_dwordx4 v198, s[22:23]
	s_mov_b32 m0, s37
	s_nop 0
	global_load_lds_dwordx4 v200, s[22:23]
	s_waitcnt vmcnt(8)
	s_waitcnt lgkmcnt(0)
	v_mfma_f32_16x16x32_bf16 v[126:129], v[130:133], v[162:165], v[126:129]
	v_mfma_f32_16x16x32_bf16 v[122:125], v[138:141], v[162:165], v[122:125]
	v_mfma_f32_16x16x32_bf16 v[110:113], v[130:133], v[170:173], v[110:113]
	v_mfma_f32_16x16x32_bf16 v[106:109], v[138:141], v[170:173], v[106:109]
	s_barrier
	s_waitcnt lgkmcnt(0)
	v_mfma_f32_16x16x32_bf16 v[94:97], v[130:133], v[178:181], v[94:97]
	v_mfma_f32_16x16x32_bf16 v[90:93], v[138:141], v[178:181], v[90:93]
	v_mfma_f32_16x16x32_bf16 v[78:81], v[130:133], v[186:189], v[78:81]
	v_mfma_f32_16x16x32_bf16 v[74:77], v[138:141], v[186:189], v[74:77]
	v_mfma_f32_16x16x32_bf16 v[126:129], v[134:137], v[166:169], v[126:129]
	v_mfma_f32_16x16x32_bf16 v[122:125], v[142:145], v[166:169], v[122:125]
	v_mfma_f32_16x16x32_bf16 v[110:113], v[134:137], v[174:177], v[110:113]
	v_mfma_f32_16x16x32_bf16 v[106:109], v[142:145], v[174:177], v[106:109]
	v_mfma_f32_16x16x32_bf16 v[94:97], v[134:137], v[182:185], v[94:97]
	v_mfma_f32_16x16x32_bf16 v[90:93], v[142:145], v[182:185], v[90:93]
	v_mfma_f32_16x16x32_bf16 v[78:81], v[134:137], v[190:193], v[78:81]
	v_mfma_f32_16x16x32_bf16 v[74:77], v[142:145], v[190:193], v[74:77]
	v_mfma_f32_16x16x32_bf16 v[118:121], v[146:149], v[162:165], v[118:121]
	v_mfma_f32_16x16x32_bf16 v[114:117], v[154:157], v[162:165], v[114:117]
	v_mfma_f32_16x16x32_bf16 v[102:105], v[146:149], v[170:173], v[102:105]
	v_mfma_f32_16x16x32_bf16 v[98:101], v[154:157], v[170:173], v[98:101]
	v_mfma_f32_16x16x32_bf16 v[86:89], v[146:149], v[178:181], v[86:89]
	v_mfma_f32_16x16x32_bf16 v[82:85], v[154:157], v[178:181], v[82:85]
	v_mfma_f32_16x16x32_bf16 v[70:73], v[146:149], v[186:189], v[70:73]
	v_mfma_f32_16x16x32_bf16 v[66:69], v[154:157], v[186:189], v[66:69]
	v_mfma_f32_16x16x32_bf16 v[118:121], v[150:153], v[166:169], v[118:121]
	v_mfma_f32_16x16x32_bf16 v[114:117], v[158:161], v[166:169], v[114:117]
	v_mfma_f32_16x16x32_bf16 v[102:105], v[150:153], v[174:177], v[102:105]
	v_mfma_f32_16x16x32_bf16 v[98:101], v[158:161], v[174:177], v[98:101]
	v_mfma_f32_16x16x32_bf16 v[86:89], v[150:153], v[182:185], v[86:89]
	v_mfma_f32_16x16x32_bf16 v[82:85], v[158:161], v[182:185], v[82:85]
	v_mfma_f32_16x16x32_bf16 v[70:73], v[150:153], v[190:193], v[70:73]
	v_mfma_f32_16x16x32_bf16 v[66:69], v[158:161], v[190:193], v[66:69]
	s_barrier
	s_add_u32 s98, s20, 0x80
	s_addc_u32 s99, s21, 0
	s_add_i32 s22, s49, s31
	s_mov_b32 m0, s22
	ds_read_b128 v[162:165], v230 offset:49152
	ds_read_b128 v[166:169], v230 offset:50176
	ds_read_b128 v[170:173], v230 offset:51200
	ds_read_b128 v[174:177], v230 offset:52224
	ds_read_b128 v[178:181], v230 offset:53248
	ds_read_b128 v[182:185], v230 offset:54272
	ds_read_b128 v[186:189], v230 offset:55296
	ds_read_b128 v[190:193], v230 offset:56320
	global_load_lds_dwordx4 v0, s[98:99]
	s_add_i32 m0, s22, 0x2000
	s_add_u32 s20, s20, 0x20080
	s_addc_u32 s21, s21, 0
	s_add_i32 s22, s50, s31
	global_load_lds_dwordx4 v202, s[98:99]
	s_mov_b32 m0, s22
	s_nop 0
	global_load_lds_dwordx4 v0, s[20:21]
	s_add_i32 m0, s22, 0x2000
	s_nop 0
	global_load_lds_dwordx4 v202, s[20:21]
	s_mov_b32 m0, s41
	s_nop 0
	global_load_lds_dwordx4 v198, s[100:101]
	s_mov_b32 m0, s42
	s_nop 0
	global_load_lds_dwordx4 v200, s[100:101]
	s_waitcnt vmcnt(8)
	s_waitcnt lgkmcnt(0)
	v_mfma_f32_16x16x32_bf16 v[62:65], v[130:133], v[162:165], v[62:65]
	v_mfma_f32_16x16x32_bf16 v[58:61], v[138:141], v[162:165], v[58:61]
	v_mfma_f32_16x16x32_bf16 v[46:49], v[130:133], v[170:173], v[46:49]
	v_mfma_f32_16x16x32_bf16 v[42:45], v[138:141], v[170:173], v[42:45]
	s_barrier
	s_waitcnt lgkmcnt(0)
	v_mfma_f32_16x16x32_bf16 v[30:33], v[130:133], v[178:181], v[30:33]
	v_mfma_f32_16x16x32_bf16 v[26:29], v[138:141], v[178:181], v[26:29]
	v_mfma_f32_16x16x32_bf16 v[14:17], v[130:133], v[186:189], v[14:17]
	v_mfma_f32_16x16x32_bf16 v[10:13], v[138:141], v[186:189], v[10:13]
	v_mfma_f32_16x16x32_bf16 v[62:65], v[134:137], v[166:169], v[62:65]
	v_mfma_f32_16x16x32_bf16 v[58:61], v[142:145], v[166:169], v[58:61]
	v_mfma_f32_16x16x32_bf16 v[46:49], v[134:137], v[174:177], v[46:49]
	v_mfma_f32_16x16x32_bf16 v[42:45], v[142:145], v[174:177], v[42:45]
	v_mfma_f32_16x16x32_bf16 v[30:33], v[134:137], v[182:185], v[30:33]
	v_mfma_f32_16x16x32_bf16 v[26:29], v[142:145], v[182:185], v[26:29]
	v_mfma_f32_16x16x32_bf16 v[14:17], v[134:137], v[190:193], v[14:17]
	v_mfma_f32_16x16x32_bf16 v[10:13], v[142:145], v[190:193], v[10:13]
	v_mfma_f32_16x16x32_bf16 v[54:57], v[146:149], v[162:165], v[54:57]
	v_mfma_f32_16x16x32_bf16 v[50:53], v[154:157], v[162:165], v[50:53]
	v_mfma_f32_16x16x32_bf16 v[38:41], v[146:149], v[170:173], v[38:41]
	v_mfma_f32_16x16x32_bf16 v[34:37], v[154:157], v[170:173], v[34:37]
	v_mfma_f32_16x16x32_bf16 v[22:25], v[146:149], v[178:181], v[22:25]
	v_mfma_f32_16x16x32_bf16 v[18:21], v[154:157], v[178:181], v[18:21]
	v_mfma_f32_16x16x32_bf16 v[6:9], v[146:149], v[186:189], v[6:9]
	v_mfma_f32_16x16x32_bf16 v[2:5], v[154:157], v[186:189], v[2:5]
	v_mfma_f32_16x16x32_bf16 v[54:57], v[150:153], v[166:169], v[54:57]
	v_mfma_f32_16x16x32_bf16 v[50:53], v[158:161], v[166:169], v[50:53]
	v_mfma_f32_16x16x32_bf16 v[38:41], v[150:153], v[174:177], v[38:41]
	v_mfma_f32_16x16x32_bf16 v[34:37], v[158:161], v[174:177], v[34:37]
	v_mfma_f32_16x16x32_bf16 v[22:25], v[150:153], v[182:185], v[22:25]
	v_mfma_f32_16x16x32_bf16 v[18:21], v[158:161], v[182:185], v[18:21]
	v_mfma_f32_16x16x32_bf16 v[6:9], v[150:153], v[190:193], v[6:9]
	v_mfma_f32_16x16x32_bf16 v[2:5], v[158:161], v[190:193], v[2:5]
	s_barrier
	s_add_i32 s48, s48, 2
	s_add_u32 s46, s46, 0x100
	s_addc_u32 s47, s47, 0
	s_add_u32 s18, s18, 0x100
	s_addc_u32 s19, s19, 0
	s_cmp_gt_u32 s48, 29
; #define PG8_STAGE(bufoff, gbase, voff) do { _Pragma("unroll") for (int _i = 0; _i < 2; ++_i) \
;         __builtin_amdgcn_global_load_lds((const unsigned*)((const char*)(gbase) + (voff)[_i]), (LAS unsigned*)(lds + (bufoff) + ldsw + _i * 8192), 16, 0, 0); } while (0)
; #define PG8_LDA(dst, b, h) do { _Pragma("unroll") for (int m = 0; m < 4; ++m) _Pragma("unroll") for (int k = 0; k < 2; ++k) dst[m][k] = *(const LAS bf16x8*)(lds + PG8_SA(b, h) + aoff + m * 2048 + k * 1024); } while (0)
; #define PG8_LDB(dst, b, h) do { _Pragma("unroll") for (int n = 0; n < 2; ++n) _Pragma("unroll") for (int k = 0; k < 2; ++k) dst[n][k] = *(const LAS bf16x8*)(lds + PG8_SB(b, h) + boff + n * 2048 + k * 1024); } while (0)
; #define PG8_MMA(ai, bj, At, Bt) do { __builtin_amdgcn_s_setprio(1); _Pragma("unroll") for (int m = 0; m < 4; ++m) _Pragma("unroll") for (int n = 0; n < 2; ++n) _Pragma("unroll") for (int k = 0; k < 2; ++k) \
;         acc[ai][bj][m][n] = __builtin_amdgcn_mfma_f32_16x16x32_bf16(Bt[n][k], At[m][k], acc[ai][bj][m][n], 0, 0, 0); __builtin_amdgcn_s_setprio(0); } while (0)
; #define PG8_WAIT_V(n) asm volatile("s_waitcnt vmcnt(" #n ")" ::: "memory")
; #define PG8_WAIT_L(n) asm volatile("s_waitcnt lgkmcnt(" #n ")" ::: "memory")
; #define PG8_BAR __builtin_amdgcn_s_barrier()
; #define PG8_SCHED __builtin_amdgcn_sched_barrier(0)
; template <class Epi, class Sched, int KC, bool ALIGN_EPI = false, bool SP2 = false, bool ATILED = false>
; __device__ __forceinline__ void gemm_phase(LAS unsigned char* lds, const Gemm g, const Sched& S, const Epi& E, int wave_s) {
;     ...
;             if constexpr (SP2) {
;             PG8_LDB(B0, 0, 0); PG8_LDB(B1, 0, 1); PG8_SCHED; PG8_LDA(At, 0, 0); PG8_STAGE(PG8_SA(1, 1), a1 + hstepA, voffA);
;             PG8_WAIT_V(8); PG8_WAIT_L(0); PG8_BAR; PG8_MMA(0, 0, At, B0); PG8_MMA(0, 1, At, B1); PG8_BAR; PG8_SCHED;
;             PG8_LDA(At, 0, 1); PG8_STAGE(PG8_SB(0, 0), b2, voffB); PG8_STAGE(PG8_SB(0, 1), b2 + hstepB, voffB); PG8_STAGE(PG8_SA(0, 0), a2, voffA);
.LBB0_1021:
	s_add_u32 s20, s18, 0xfff80080
	s_addc_u32 s21, s19, -1
	s_add_i32 s49, 0, 0x10000
	s_cmp_eq_u32 s48, 28
	s_cselect_b32 s23, s9, s21
	s_cselect_b32 s22, s15, s20
	s_cselect_b32 s21, s3, s47
	s_cselect_b32 s20, s17, s46
	s_add_i32 s52, 0, 0x14000
	v_add_u32_e32 v142, s49, v229
	v_add_u32_e32 v158, s52, v229
	ds_read_b128 v[130:133], v142
	ds_read_b128 v[134:137], v142 offset:1024
	ds_read_b128 v[138:141], v142 offset:2048
	ds_read_b128 v[142:145], v142 offset:3072
	ds_read_b128 v[146:149], v158
	ds_read_b128 v[150:153], v158 offset:1024
	ds_read_b128 v[154:157], v158 offset:2048
	ds_read_b128 v[158:161], v158 offset:3072
	s_add_i32 m0, s34, 0xc000
	ds_read_b128 v[162:165], v230
	ds_read_b128 v[166:169], v230 offset:1024
	ds_read_b128 v[170:173], v230 offset:2048
	ds_read_b128 v[174:177], v230 offset:3072
	ds_read_b128 v[178:181], v230 offset:4096
	ds_read_b128 v[182:185], v230 offset:5120
	ds_read_b128 v[186:189], v230 offset:6144
	ds_read_b128 v[190:193], v230 offset:7168
	global_load_lds_dwordx4 v208, s[18:19]
	s_add_i32 m0, s34, 0xe000
	s_nop 0
	global_load_lds_dwordx4 v206, s[18:19]
	s_waitcnt vmcnt(8)
	s_waitcnt lgkmcnt(0)
	v_mfma_f32_16x16x32_bf16 v[126:129], v[130:133], v[162:165], v[126:129]
	v_mfma_f32_16x16x32_bf16 v[122:125], v[138:141], v[162:165], v[122:125]
	v_mfma_f32_16x16x32_bf16 v[110:113], v[130:133], v[170:173], v[110:113]
	v_mfma_f32_16x16x32_bf16 v[106:109], v[138:141], v[170:173], v[106:109]
	s_barrier
	s_waitcnt lgkmcnt(0)
	v_mfma_f32_16x16x32_bf16 v[94:97], v[130:133], v[178:181], v[94:97]
	v_mfma_f32_16x16x32_bf16 v[90:93], v[138:141], v[178:181], v[90:93]
	v_mfma_f32_16x16x32_bf16 v[78:81], v[130:133], v[186:189], v[78:81]
	v_mfma_f32_16x16x32_bf16 v[74:77], v[138:141], v[186:189], v[74:77]
	v_mfma_f32_16x16x32_bf16 v[126:129], v[134:137], v[166:169], v[126:129]
	v_mfma_f32_16x16x32_bf16 v[122:125], v[142:145], v[166:169], v[122:125]
	v_mfma_f32_16x16x32_bf16 v[110:113], v[134:137], v[174:177], v[110:113]
	v_mfma_f32_16x16x32_bf16 v[106:109], v[142:145], v[174:177], v[106:109]
	v_mfma_f32_16x16x32_bf16 v[94:97], v[134:137], v[182:185], v[94:97]
	v_mfma_f32_16x16x32_bf16 v[90:93], v[142:145], v[182:185], v[90:93]
	v_mfma_f32_16x16x32_bf16 v[78:81], v[134:137], v[190:193], v[78:81]
	v_mfma_f32_16x16x32_bf16 v[74:77], v[142:145], v[190:193], v[74:77]
	v_mfma_f32_16x16x32_bf16 v[118:121], v[146:149], v[162:165], v[118:121]
	v_mfma_f32_16x16x32_bf16 v[114:117], v[154:157], v[162:165], v[114:117]
	v_mfma_f32_16x16x32_bf16 v[102:105], v[146:149], v[170:173], v[102:105]
	v_mfma_f32_16x16x32_bf16 v[98:101], v[154:157], v[170:173], v[98:101]
	v_mfma_f32_16x16x32_bf16 v[86:89], v[146:149], v[178:181], v[86:89]
	v_mfma_f32_16x16x32_bf16 v[82:85], v[154:157], v[178:181], v[82:85]
	v_mfma_f32_16x16x32_bf16 v[70:73], v[146:149], v[186:189], v[70:73]
	v_mfma_f32_16x16x32_bf16 v[66:69], v[154:157], v[186:189], v[66:69]
	v_mfma_f32_16x16x32_bf16 v[118:121], v[150:153], v[166:169], v[118:121]
	v_mfma_f32_16x16x32_bf16 v[114:117], v[158:161], v[166:169], v[114:117]
	v_mfma_f32_16x16x32_bf16 v[102:105], v[150:153], v[174:177], v[102:105]
	v_mfma_f32_16x16x32_bf16 v[98:101], v[158:161], v[174:177], v[98:101]
	v_mfma_f32_16x16x32_bf16 v[86:89], v[150:153], v[182:185], v[86:89]
	v_mfma_f32_16x16x32_bf16 v[82:85], v[158:161], v[182:185], v[82:85]
	v_mfma_f32_16x16x32_bf16 v[70:73], v[150:153], v[190:193], v[70:73]
	v_mfma_f32_16x16x32_bf16 v[66:69], v[158:161], v[190:193], v[66:69]
	s_barrier
	s_add_u32 s100, s22, 0x80
	s_addc_u32 s101, s23, 0
	s_add_i32 s49, s49, s31
	s_mov_b32 m0, s49
	ds_read_b128 v[162:165], v230 offset:16384
	ds_read_b128 v[166:169], v230 offset:17408
	ds_read_b128 v[170:173], v230 offset:18432
	ds_read_b128 v[174:177], v230 offset:19456
	ds_read_b128 v[178:181], v230 offset:20480
	ds_read_b128 v[182:185], v230 offset:21504
	ds_read_b128 v[186:189], v230 offset:22528
	ds_read_b128 v[190:193], v230 offset:23552
	global_load_lds_dwordx4 v0, s[20:21]
	s_add_i32 m0, s49, 0x2000
	s_add_u32 s50, s20, 0x20000
	s_addc_u32 s51, s21, 0
	s_add_i32 s49, s52, s31
	global_load_lds_dwordx4 v202, s[20:21]
	s_mov_b32 m0, s49
	s_nop 0
	global_load_lds_dwordx4 v0, s[50:51]
	s_add_i32 m0, s49, 0x2000
	s_nop 0
	global_load_lds_dwordx4 v202, s[50:51]
	s_mov_b32 m0, s34
	s_nop 0
	global_load_lds_dwordx4 v198, s[22:23]
	s_mov_b32 m0, s35
	s_nop 0
	global_load_lds_dwordx4 v200, s[22:23]
	s_waitcnt vmcnt(8)
	s_waitcnt lgkmcnt(0)
	v_mfma_f32_16x16x32_bf16 v[62:65], v[130:133], v[162:165], v[62:65]
	v_mfma_f32_16x16x32_bf16 v[58:61], v[138:141], v[162:165], v[58:61]
	v_mfma_f32_16x16x32_bf16 v[46:49], v[130:133], v[170:173], v[46:49]
	v_mfma_f32_16x16x32_bf16 v[42:45], v[138:141], v[170:173], v[42:45]
	s_barrier
; #define PG8_STAGE(bufoff, gbase, voff) do { _Pragma("unroll") for (int _i = 0; _i < 2; ++_i) \
;         __builtin_amdgcn_global_load_lds((const unsigned*)((const char*)(gbase) + (voff)[_i]), (LAS unsigned*)(lds + (bufoff) + ldsw + _i * 8192), 16, 0, 0); } while (0)
; #define PG8_LDA(dst, b, h) do { _Pragma("unroll") for (int m = 0; m < 4; ++m) _Pragma("unroll") for (int k = 0; k < 2; ++k) dst[m][k] = *(const LAS bf16x8*)(lds + PG8_SA(b, h) + aoff + m * 2048 + k * 1024); } while (0)
; #define PG8_LDB(dst, b, h) do { _Pragma("unroll") for (int n = 0; n < 2; ++n) _Pragma("unroll") for (int k = 0; k < 2; ++k) dst[n][k] = *(const LAS bf16x8*)(lds + PG8_SB(b, h) + boff + n * 2048 + k * 1024); } while (0)
; #define PG8_MMA(ai, bj, At, Bt) do { __builtin_amdgcn_s_setprio(1); _Pragma("unroll") for (int m = 0; m < 4; ++m) _Pragma("unroll") for (int n = 0; n < 2; ++n) _Pragma("unroll") for (int k = 0; k < 2; ++k) \
;         acc[ai][bj][m][n] = __builtin_amdgcn_mfma_f32_16x16x32_bf16(Bt[n][k], At[m][k], acc[ai][bj][m][n], 0, 0, 0); __builtin_amdgcn_s_setprio(0); } while (0)
; #define PG8_WAIT_V(n) asm volatile("s_waitcnt vmcnt(" #n ")" ::: "memory")
; #define PG8_WAIT_L(n) asm volatile("s_waitcnt lgkmcnt(" #n ")" ::: "memory")
; #define PG8_BAR __builtin_amdgcn_s_barrier()
; #define PG8_SCHED __builtin_amdgcn_sched_barrier(0)
; template <class Epi, class Sched, int KC, bool ALIGN_EPI = false, bool SP2 = false, bool ATILED = false>
; __device__ __forceinline__ void gemm_phase(LAS unsigned char* lds, const Gemm g, const Sched& S, const Epi& E, int wave_s) {
;     ...
;             PG8_LDA(At, 0, 1); PG8_STAGE(PG8_SB(0, 0), b2, voffB); PG8_STAGE(PG8_SB(0, 1), b2 + hstepB, voffB); PG8_STAGE(PG8_SA(0, 0), a2, voffA);
;             PG8_WAIT_V(8); PG8_WAIT_L(0); PG8_BAR; PG8_MMA(1, 0, At, B0); PG8_MMA(1, 1, At, B1); PG8_BAR; PG8_SCHED;
;             PG8_LDB(B0, 1, 0); PG8_LDB(B1, 1, 1); PG8_SCHED; PG8_LDA(At, 1, 0); PG8_STAGE(PG8_SA(0, 1), a2 + hstepA, voffA);
;             PG8_WAIT_V(8); PG8_WAIT_L(0); PG8_BAR; PG8_MMA(0, 0, At, B0); PG8_MMA(0, 1, At, B1); PG8_BAR; PG8_SCHED;
	s_waitcnt lgkmcnt(0)
	v_mfma_f32_16x16x32_bf16 v[30:33], v[130:133], v[178:181], v[30:33]
	v_mfma_f32_16x16x32_bf16 v[26:29], v[138:141], v[178:181], v[26:29]
	v_mfma_f32_16x16x32_bf16 v[14:17], v[130:133], v[186:189], v[14:17]
	v_mfma_f32_16x16x32_bf16 v[10:13], v[138:141], v[186:189], v[10:13]
	v_mfma_f32_16x16x32_bf16 v[62:65], v[134:137], v[166:169], v[62:65]
	v_mfma_f32_16x16x32_bf16 v[58:61], v[142:145], v[166:169], v[58:61]
	v_mfma_f32_16x16x32_bf16 v[46:49], v[134:137], v[174:177], v[46:49]
	v_mfma_f32_16x16x32_bf16 v[42:45], v[142:145], v[174:177], v[42:45]
	v_mfma_f32_16x16x32_bf16 v[30:33], v[134:137], v[182:185], v[30:33]
	v_mfma_f32_16x16x32_bf16 v[26:29], v[142:145], v[182:185], v[26:29]
	v_mfma_f32_16x16x32_bf16 v[14:17], v[134:137], v[190:193], v[14:17]
	v_mfma_f32_16x16x32_bf16 v[10:13], v[142:145], v[190:193], v[10:13]
	v_mfma_f32_16x16x32_bf16 v[54:57], v[146:149], v[162:165], v[54:57]
	v_mfma_f32_16x16x32_bf16 v[50:53], v[154:157], v[162:165], v[50:53]
	v_mfma_f32_16x16x32_bf16 v[38:41], v[146:149], v[170:173], v[38:41]
	v_mfma_f32_16x16x32_bf16 v[34:37], v[154:157], v[170:173], v[34:37]
	v_mfma_f32_16x16x32_bf16 v[22:25], v[146:149], v[178:181], v[22:25]
	v_mfma_f32_16x16x32_bf16 v[18:21], v[154:157], v[178:181], v[18:21]
	v_mfma_f32_16x16x32_bf16 v[6:9], v[146:149], v[186:189], v[6:9]
	v_mfma_f32_16x16x32_bf16 v[2:5], v[154:157], v[186:189], v[2:5]
	v_mfma_f32_16x16x32_bf16 v[54:57], v[150:153], v[166:169], v[54:57]
	v_mfma_f32_16x16x32_bf16 v[50:53], v[158:161], v[166:169], v[50:53]
	v_mfma_f32_16x16x32_bf16 v[38:41], v[150:153], v[174:177], v[38:41]
	v_mfma_f32_16x16x32_bf16 v[34:37], v[158:161], v[174:177], v[34:37]
	v_mfma_f32_16x16x32_bf16 v[22:25], v[150:153], v[182:185], v[22:25]
	v_mfma_f32_16x16x32_bf16 v[18:21], v[158:161], v[182:185], v[18:21]
	v_mfma_f32_16x16x32_bf16 v[6:9], v[150:153], v[190:193], v[6:9]
	v_mfma_f32_16x16x32_bf16 v[2:5], v[158:161], v[190:193], v[2:5]
	s_barrier
	s_add_i32 s49, 0, 0x18000
	s_add_i32 s50, 0, 0x1c000
	v_add_u32_e32 v142, s49, v229
	v_add_u32_e32 v158, s50, v229
	ds_read_b128 v[130:133], v142
	ds_read_b128 v[134:137], v142 offset:1024
	ds_read_b128 v[138:141], v142 offset:2048
	ds_read_b128 v[142:145], v142 offset:3072
	ds_read_b128 v[146:149], v158
	ds_read_b128 v[150:153], v158 offset:1024
	ds_read_b128 v[154:157], v158 offset:2048
	ds_read_b128 v[158:161], v158 offset:3072
	s_add_u32 s22, s22, 0x80000
	s_addc_u32 s23, s23, 0
	s_mov_b32 m0, s36
	ds_read_b128 v[162:165], v230 offset:32768
	ds_read_b128 v[166:169], v230 offset:33792
	ds_read_b128 v[170:173], v230 offset:34816
	ds_read_b128 v[174:177], v230 offset:35840
	ds_read_b128 v[178:181], v230 offset:36864
	ds_read_b128 v[182:185], v230 offset:37888
	ds_read_b128 v[186:189], v230 offset:38912
	ds_read_b128 v[190:193], v230 offset:39936
	global_load_lds_dwordx4 v198, s[22:23]
	s_mov_b32 m0, s37
	s_nop 0
	global_load_lds_dwordx4 v200, s[22:23]
	s_waitcnt vmcnt(8)
	s_waitcnt lgkmcnt(0)
	v_mfma_f32_16x16x32_bf16 v[126:129], v[130:133], v[162:165], v[126:129]
	v_mfma_f32_16x16x32_bf16 v[122:125], v[138:141], v[162:165], v[122:125]
	v_mfma_f32_16x16x32_bf16 v[110:113], v[130:133], v[170:173], v[110:113]
	v_mfma_f32_16x16x32_bf16 v[106:109], v[138:141], v[170:173], v[106:109]
	s_barrier
	s_waitcnt lgkmcnt(0)
	v_mfma_f32_16x16x32_bf16 v[94:97], v[130:133], v[178:181], v[94:97]
	v_mfma_f32_16x16x32_bf16 v[90:93], v[138:141], v[178:181], v[90:93]
	v_mfma_f32_16x16x32_bf16 v[78:81], v[130:133], v[186:189], v[78:81]
	v_mfma_f32_16x16x32_bf16 v[74:77], v[138:141], v[186:189], v[74:77]
	v_mfma_f32_16x16x32_bf16 v[126:129], v[134:137], v[166:169], v[126:129]
	v_mfma_f32_16x16x32_bf16 v[122:125], v[142:145], v[166:169], v[122:125]
	v_mfma_f32_16x16x32_bf16 v[110:113], v[134:137], v[174:177], v[110:113]
	v_mfma_f32_16x16x32_bf16 v[106:109], v[142:145], v[174:177], v[106:109]
	v_mfma_f32_16x16x32_bf16 v[94:97], v[134:137], v[182:185], v[94:97]
	v_mfma_f32_16x16x32_bf16 v[90:93], v[142:145], v[182:185], v[90:93]
	v_mfma_f32_16x16x32_bf16 v[78:81], v[134:137], v[190:193], v[78:81]
	v_mfma_f32_16x16x32_bf16 v[74:77], v[142:145], v[190:193], v[74:77]
	v_mfma_f32_16x16x32_bf16 v[118:121], v[146:149], v[162:165], v[118:121]
	v_mfma_f32_16x16x32_bf16 v[114:117], v[154:157], v[162:165], v[114:117]
	v_mfma_f32_16x16x32_bf16 v[102:105], v[146:149], v[170:173], v[102:105]
	v_mfma_f32_16x16x32_bf16 v[98:101], v[154:157], v[170:173], v[98:101]
	v_mfma_f32_16x16x32_bf16 v[86:89], v[146:149], v[178:181], v[86:89]
	v_mfma_f32_16x16x32_bf16 v[82:85], v[154:157], v[178:181], v[82:85]
	v_mfma_f32_16x16x32_bf16 v[70:73], v[146:149], v[186:189], v[70:73]
	v_mfma_f32_16x16x32_bf16 v[66:69], v[154:157], v[186:189], v[66:69]
	v_mfma_f32_16x16x32_bf16 v[118:121], v[150:153], v[166:169], v[118:121]
	v_mfma_f32_16x16x32_bf16 v[114:117], v[158:161], v[166:169], v[114:117]
	v_mfma_f32_16x16x32_bf16 v[102:105], v[150:153], v[174:177], v[102:105]
	v_mfma_f32_16x16x32_bf16 v[98:101], v[158:161], v[174:177], v[98:101]
	v_mfma_f32_16x16x32_bf16 v[86:89], v[150:153], v[182:185], v[86:89]
	v_mfma_f32_16x16x32_bf16 v[82:85], v[158:161], v[182:185], v[82:85]
	v_mfma_f32_16x16x32_bf16 v[70:73], v[150:153], v[190:193], v[70:73]
	v_mfma_f32_16x16x32_bf16 v[66:69], v[158:161], v[190:193], v[66:69]
	s_barrier
; #define PG8_STAGE(bufoff, gbase, voff) do { _Pragma("unroll") for (int _i = 0; _i < 2; ++_i) \
;         __builtin_amdgcn_global_load_lds((const unsigned*)((const char*)(gbase) + (voff)[_i]), (LAS unsigned*)(lds + (bufoff) + ldsw + _i * 8192), 16, 0, 0); } while (0)
; #define PG8_LDA(dst, b, h) do { _Pragma("unroll") for (int m = 0; m < 4; ++m) _Pragma("unroll") for (int k = 0; k < 2; ++k) dst[m][k] = *(const LAS bf16x8*)(lds + PG8_SA(b, h) + aoff + m * 2048 + k * 1024); } while (0)
; #define PG8_MMA(ai, bj, At, Bt) do { __builtin_amdgcn_s_setprio(1); _Pragma("unroll") for (int m = 0; m < 4; ++m) _Pragma("unroll") for (int n = 0; n < 2; ++n) _Pragma("unroll") for (int k = 0; k < 2; ++k) \
;         acc[ai][bj][m][n] = __builtin_amdgcn_mfma_f32_16x16x32_bf16(Bt[n][k], At[m][k], acc[ai][bj][m][n], 0, 0, 0); __builtin_amdgcn_s_setprio(0); } while (0)
; #define PG8_WAIT_V(n) asm volatile("s_waitcnt vmcnt(" #n ")" ::: "memory")
; #define PG8_WAIT_L(n) asm volatile("s_waitcnt lgkmcnt(" #n ")" ::: "memory")
; #define PG8_BAR __builtin_amdgcn_s_barrier()
; #define PG8_SCHED __builtin_amdgcn_sched_barrier(0)
; template <class Epi, class Sched, int KC, bool ALIGN_EPI = false, bool SP2 = false, bool ATILED = false>
; __device__ __forceinline__ void gemm_phase(LAS unsigned char* lds, const Gemm g, const Sched& S, const Epi& E, int wave_s) {
;     ...
;             PG8_WAIT_V(8); PG8_WAIT_L(0); PG8_BAR; PG8_MMA(0, 0, At, B0); PG8_MMA(0, 1, At, B1); PG8_BAR; PG8_SCHED;
;             PG8_LDA(At, 1, 1); PG8_STAGE(PG8_SB(1, 0), b3, voffB); PG8_STAGE(PG8_SB(1, 1), b3 + hstepB, voffB); PG8_STAGE(PG8_SA(1, 0), a3, voffA);
;             PG8_WAIT_V(8); PG8_WAIT_L(0); PG8_BAR; PG8_MMA(1, 0, At, B0); PG8_MMA(1, 1, At, B1); PG8_BAR; PG8_SCHED;
	s_add_u32 s98, s20, 0x80
	s_addc_u32 s99, s21, 0
	s_add_i32 s22, s49, s31
	s_mov_b32 m0, s22
	ds_read_b128 v[162:165], v230 offset:49152
	ds_read_b128 v[166:169], v230 offset:50176
	ds_read_b128 v[170:173], v230 offset:51200
	ds_read_b128 v[174:177], v230 offset:52224
	ds_read_b128 v[178:181], v230 offset:53248
	ds_read_b128 v[182:185], v230 offset:54272
	ds_read_b128 v[186:189], v230 offset:55296
	ds_read_b128 v[190:193], v230 offset:56320
	global_load_lds_dwordx4 v0, s[98:99]
	s_add_i32 m0, s22, 0x2000
	s_add_u32 s20, s20, 0x20080
	s_addc_u32 s21, s21, 0
	s_add_i32 s22, s50, s31
	global_load_lds_dwordx4 v202, s[98:99]
	s_mov_b32 m0, s22
	s_nop 0
	global_load_lds_dwordx4 v0, s[20:21]
	s_add_i32 m0, s22, 0x2000
	s_nop 0
	global_load_lds_dwordx4 v202, s[20:21]
	s_mov_b32 m0, s41
	s_nop 0
	global_load_lds_dwordx4 v198, s[100:101]
	s_mov_b32 m0, s42
	s_nop 0
	global_load_lds_dwordx4 v200, s[100:101]
	s_waitcnt vmcnt(8)
	s_waitcnt lgkmcnt(0)
	v_mfma_f32_16x16x32_bf16 v[62:65], v[130:133], v[162:165], v[62:65]
	v_mfma_f32_16x16x32_bf16 v[58:61], v[138:141], v[162:165], v[58:61]
	v_mfma_f32_16x16x32_bf16 v[46:49], v[130:133], v[170:173], v[46:49]
	v_mfma_f32_16x16x32_bf16 v[42:45], v[138:141], v[170:173], v[42:45]
	s_barrier
	s_waitcnt lgkmcnt(0)
	v_mfma_f32_16x16x32_bf16 v[30:33], v[130:133], v[178:181], v[30:33]
	v_mfma_f32_16x16x32_bf16 v[26:29], v[138:141], v[178:181], v[26:29]
	v_mfma_f32_16x16x32_bf16 v[14:17], v[130:133], v[186:189], v[14:17]
	v_mfma_f32_16x16x32_bf16 v[10:13], v[138:141], v[186:189], v[10:13]
	v_mfma_f32_16x16x32_bf16 v[62:65], v[134:137], v[166:169], v[62:65]
	v_mfma_f32_16x16x32_bf16 v[58:61], v[142:145], v[166:169], v[58:61]
	v_mfma_f32_16x16x32_bf16 v[46:49], v[134:137], v[174:177], v[46:49]
	v_mfma_f32_16x16x32_bf16 v[42:45], v[142:145], v[174:177], v[42:45]
	v_mfma_f32_16x16x32_bf16 v[30:33], v[134:137], v[182:185], v[30:33]
	v_mfma_f32_16x16x32_bf16 v[26:29], v[142:145], v[182:185], v[26:29]
	v_mfma_f32_16x16x32_bf16 v[14:17], v[134:137], v[190:193], v[14:17]
	v_mfma_f32_16x16x32_bf16 v[10:13], v[142:145], v[190:193], v[10:13]
	v_mfma_f32_16x16x32_bf16 v[54:57], v[146:149], v[162:165], v[54:57]
	v_mfma_f32_16x16x32_bf16 v[50:53], v[154:157], v[162:165], v[50:53]
	v_mfma_f32_16x16x32_bf16 v[38:41], v[146:149], v[170:173], v[38:41]
	v_mfma_f32_16x16x32_bf16 v[34:37], v[154:157], v[170:173], v[34:37]
	v_mfma_f32_16x16x32_bf16 v[22:25], v[146:149], v[178:181], v[22:25]
	v_mfma_f32_16x16x32_bf16 v[18:21], v[154:157], v[178:181], v[18:21]
	v_mfma_f32_16x16x32_bf16 v[6:9], v[146:149], v[186:189], v[6:9]
	v_mfma_f32_16x16x32_bf16 v[2:5], v[154:157], v[186:189], v[2:5]
	v_mfma_f32_16x16x32_bf16 v[54:57], v[150:153], v[166:169], v[54:57]
	v_mfma_f32_16x16x32_bf16 v[50:53], v[158:161], v[166:169], v[50:53]
	v_mfma_f32_16x16x32_bf16 v[38:41], v[150:153], v[174:177], v[38:41]
	v_mfma_f32_16x16x32_bf16 v[34:37], v[158:161], v[174:177], v[34:37]
	v_mfma_f32_16x16x32_bf16 v[22:25], v[150:153], v[182:185], v[22:25]
	v_mfma_f32_16x16x32_bf16 v[18:21], v[158:161], v[182:185], v[18:21]
	v_mfma_f32_16x16x32_bf16 v[6:9], v[150:153], v[190:193], v[6:9]
	v_mfma_f32_16x16x32_bf16 v[2:5], v[158:161], v[190:193], v[2:5]
	s_barrier
	s_add_i32 s48, s48, 2
	s_add_u32 s46, s46, 0x100
	s_addc_u32 s47, s47, 0
	s_add_u32 s18, s18, 0x100
	s_addc_u32 s19, s19, 0
	s_cmp_gt_u32 s48, 29
	s_cbranch_scc0 .LBB0_1021
; #define GAS __attribute__((address_space(1)))
; DI unsigned cvtpk(float lo, float hi) { unsigned r; asm volatile("v_cvt_pk_bf16_f32 %0, %1, %2" : "=v"(r) : "v"(lo), "v"(hi)); return r; }
;     DI void operator()(const f32x4 (&acc)[2][2][4][2], const Unit& u, int wr, int wc, int fr, int fq) const {
;         const int row0 = u.pm * BM + wr * 64 + fr, col0 = u.pn * BM + wc * 64 + 8 * fq;
;         const size_t hbase = (size_t)u.pn * ((size_t)M * 256) + wc * 64 + 8 * fq;
;         u32x4 H[2][4][2];
; #pragma unroll
;         for (int ai = 0; ai < 2; ++ai)
; #pragma unroll
;             for (int m = 0; m < 4; ++m)
; #pragma unroll
;                 for (int bj = 0; bj < 2; ++bj) H[ai][m][bj] = *(const GAS u32x4*)(hi + hbase + (size_t)(row0 + ai * HALF + m * 16) * 256 + bj * 32);
;         asm volatile("" ::: "memory");
; #pragma unroll
;         for (int ai = 0; ai < 2; ++ai) {
; #pragma unroll
;             for (int m = 0; m < 4; ++m) {
;                 const int r = row0 + ai * HALF + m * 16; const size_t off = (size_t)r * DM + col0; float ss = 0.f;
; #pragma unroll
;                 for (int bj = 0; bj < 2; ++bj) {
;                     const u32x4 h = H[ai][m][bj];
;                     const f32x4 a0 = acc[ai][bj][m][0], a1 = acc[ai][bj][m][1];
;                     float v[8];
;                     v[0] = bflo(h.x) + a0[0] * scale; v[1] = bfhi(h.x) + a0[1] * scale;
;                     v[2] = bflo(h.y) + a0[2] * scale; v[3] = bfhi(h.y) + a0[3] * scale;
;                     v[4] = bflo(h.z) + a1[0] * scale; v[5] = bfhi(h.z) + a1[1] * scale;
;                     v[6] = bflo(h.w) + a1[2] * scale; v[7] = bfhi(h.w) + a1[3] * scale;
; #pragma unroll
;                     for (int e = 0; e < 8; ++e) ss += v[e] * v[e];
;                     u32x4 nh;
;                     nh.x = cvtpk(v[0], v[1]); nh.y = cvtpk(v[2], v[3]); nh.z = cvtpk(v[4], v[5]); nh.w = cvtpk(v[6], v[7]);
;                     *(GAS u32x4*)(hi + hbase + (size_t)r * 256 + bj * 32) = nh;
;                     if (out) { *(GAS f32x4*)(out + off + bj * 32) = (f32x4){v[0], v[1], v[2], v[3]}; *(GAS f32x4*)(out + off + bj * 32 + 4) = (f32x4){v[4], v[5], v[6], v[7]}; }
;                 }
;                 ss = sum_xor32(sum_xor16(ss));
;                 if (fq == 0) ((GAS float*)rowss)[(size_t)(u.pn * 4 + wc) * M + r] = ss;
	v_lshl_add_u32 v210, s16, 8, v228
	s_ashr_i32 s15, s14, 31
	s_lshl_b64 s[16:17], s[14:15], 23
	v_ashrrev_i32_e32 v211, 31, v210
	v_lshl_add_u64 v[130:131], v[204:205], 0, s[16:17]
	v_lshlrev_b64 v[132:133], 9, v[210:211]
	v_lshl_add_u64 v[226:227], v[130:131], 0, v[132:133]
	global_load_dwordx4 v[190:193], v[226:227], off
	global_load_dwordx4 v[186:189], v[226:227], off offset:64
	v_or_b32_e32 v132, 16, v210
	v_ashrrev_i32_e32 v133, 31, v132
	v_lshlrev_b64 v[132:133], 9, v[132:133]
	v_lshl_add_u64 v[224:225], v[130:131], 0, v[132:133]
	v_or_b32_e32 v132, 32, v210
	v_ashrrev_i32_e32 v133, 31, v132
	v_lshlrev_b64 v[132:133], 9, v[132:133]
	v_lshl_add_u64 v[222:223], v[130:131], 0, v[132:133]
	v_or_b32_e32 v132, 48, v210
	v_ashrrev_i32_e32 v133, 31, v132
	v_lshlrev_b64 v[132:133], 9, v[132:133]
	s_mov_b32 s3, 0x10000
	v_lshl_add_u64 v[220:221], v[130:131], 0, v[132:133]
	v_add_co_u32_e32 v130, vcc, s3, v226
	s_mov_b64 s[16:17], 0x10000
	s_nop 0
	v_addc_co_u32_e32 v131, vcc, 0, v227, vcc
	s_mov_b32 s3, 0x12000
	global_load_dwordx4 v[182:185], v[224:225], off
	global_load_dwordx4 v[178:181], v[224:225], off offset:64
	global_load_dwordx4 v[174:177], v[222:223], off
	global_load_dwordx4 v[170:173], v[222:223], off offset:64
	global_load_dwordx4 v[166:169], v[220:221], off
	global_load_dwordx4 v[162:165], v[220:221], off offset:64
	v_lshl_add_u64 v[218:219], v[226:227], 0, s[16:17]
	global_load_dwordx4 v[158:161], v[130:131], off
	global_load_dwordx4 v[150:153], v[218:219], off offset:64
	v_add_co_u32_e32 v130, vcc, s3, v226
	s_mov_b64 s[16:17], 0x12000
	s_nop 0
	v_addc_co_u32_e32 v131, vcc, 0, v227, vcc
	s_mov_b32 s3, 0x14000
	v_lshl_add_u64 v[216:217], v[226:227], 0, s[16:17]
	global_load_dwordx4 v[154:157], v[130:131], off
	global_load_dwordx4 v[146:149], v[216:217], off offset:64
	v_add_co_u32_e32 v130, vcc, s3, v226
	s_mov_b64 s[16:17], 0x14000
	s_nop 0
	v_addc_co_u32_e32 v131, vcc, 0, v227, vcc
	s_mov_b32 s3, 0x16000
	v_lshl_add_u64 v[214:215], v[226:227], 0, s[16:17]
	global_load_dwordx4 v[142:145], v[130:131], off
	global_load_dwordx4 v[134:137], v[214:215], off offset:64
	v_add_co_u32_e32 v130, vcc, s3, v226
	s_mov_b64 s[16:17], 0x16000
	s_nop 0
	v_addc_co_u32_e32 v131, vcc, 0, v227, vcc
	v_lshl_add_u64 v[212:213], v[226:227], 0, s[16:17]
	global_load_dwordx4 v[138:141], v[130:131], off
	s_nop 0
	global_load_dwordx4 v[130:133], v[212:213], off offset:64
	s_lshl_b32 s3, s14, 2
	s_or_b32 s14, s3, s40
	s_ashr_i32 s15, s14, 31
	s_lshl_b64 s[14:15], s[14:15], 16
	s_waitcnt vmcnt(0)
	v_lshlrev_b32_e32 v194, 16, v190
	v_and_b32_e32 v190, 0xffff0000, v190
	v_add_f32_e32 v127, v127, v190
	v_lshlrev_b32_e32 v190, 16, v191
	v_add_f32_e32 v128, v128, v190
	v_and_b32_e32 v190, 0xffff0000, v191
	v_add_f32_e32 v129, v129, v190
	v_lshlrev_b32_e32 v190, 16, v192
	v_add_f32_e32 v190, v122, v190
	v_and_b32_e32 v122, 0xffff0000, v192
	v_add_f32_e32 v191, v123, v122
	v_lshlrev_b32_e32 v122, 16, v193
	v_add_f32_e32 v126, v126, v194
	v_add_f32_e32 v192, v124, v122
	v_and_b32_e32 v122, 0xffff0000, v193
	v_mul_f32_e32 v193, v127, v127
	v_fmac_f32_e32 v193, v126, v126
	v_fmac_f32_e32 v193, v128, v128
	v_fmac_f32_e32 v193, v129, v129
	v_fmac_f32_e32 v193, v190, v190
	v_fmac_f32_e32 v193, v191, v191
	v_add_f32_e32 v125, v125, v122
	v_fmac_f32_e32 v193, v192, v192
	v_cvt_pk_bf16_f32 v122, v126, v127
	v_fmac_f32_e32 v193, v125, v125
	v_cvt_pk_bf16_f32 v123, v128, v129
	v_cvt_pk_bf16_f32 v124, v190, v191
	v_cvt_pk_bf16_f32 v125, v192, v125
	global_store_dwordx4 v[226:227], v[122:125], off
	s_nop 1
	v_lshlrev_b32_e32 v122, 16, v186
	v_add_f32_e32 v118, v118, v122
	v_and_b32_e32 v122, 0xffff0000, v186
	v_add_f32_e32 v119, v119, v122
	v_lshlrev_b32_e32 v122, 16, v187
	v_fmac_f32_e32 v193, v118, v118
	v_add_f32_e32 v120, v120, v122
	v_and_b32_e32 v122, 0xffff0000, v187
	v_fmac_f32_e32 v193, v119, v119
	v_add_f32_e32 v121, v121, v122
	v_lshlrev_b32_e32 v122, 16, v188
	v_fmac_f32_e32 v193, v120, v120
	v_add_f32_e32 v122, v114, v122
	v_and_b32_e32 v114, 0xffff0000, v188
	v_fmac_f32_e32 v193, v121, v121
	v_add_f32_e32 v123, v115, v114
	v_lshlrev_b32_e32 v114, 16, v189
	v_fmac_f32_e32 v193, v122, v122
	v_add_f32_e32 v124, v116, v114
	v_and_b32_e32 v114, 0xffff0000, v189
	v_fmac_f32_e32 v193, v123, v123
	v_add_f32_e32 v117, v117, v114
	v_fmac_f32_e32 v193, v124, v124
	v_fmac_f32_e32 v193, v117, v117
	v_cvt_pk_bf16_f32 v114, v118, v119
	v_cvt_pk_bf16_f32 v115, v120, v121
	v_cvt_pk_bf16_f32 v116, v122, v123
	v_cvt_pk_bf16_f32 v117, v124, v117
	global_store_dwordx4 v[226:227], v[114:117], off offset:64
	s_nop 1
	v_mov_b32_e32 v114, v193
	s_nop 1
	v_permlane16_swap_b32_e32 v193, v114
	v_add_f32_e32 v114, v193, v114
	v_mov_b32_e32 v115, v114
	s_nop 1
	v_permlane32_swap_b32_e32 v114, v115
	s_and_saveexec_b64 s[16:17], s[4:5]
	s_cbranch_execz .LBB0_1024
	s_add_u32 s18, s38, s14
	s_addc_u32 s19, s39, s15
	v_lshl_add_u64 v[116:117], v[210:211], 2, s[18:19]
	v_add_f32_e32 v114, v114, v115
	global_store_dword v[116:117], v114, off
